# GEMM k-step: the six LDS-DMA issues spread over the step (one per five MFMAs) instead of back to back at its head; s_setprio 1 over the whole MFMA block
# speedup vs baseline: 1.0153x; 1.0153x over previous
.Lgy_nn_a:
	s_waitcnt vmcnt(6) lgkmcnt(0)
	s_barrier
	v_add_u32_e32 v240, s61, v238
	v_add_u32_e32 v241, s61, v239
	s_setprio 1
	s_add_i32 m0, s60, s62
	v_mfma_f32_16x16x32_bf16 v[2:5], v[162:165], v[130:133], 0
	global_load_lds_dwordx4 v226, s[54:55]
	v_mfma_f32_16x16x32_bf16 v[6:9], v[166:169], v[130:133], 0
	v_mfma_f32_16x16x32_bf16 v[10:13], v[170:173], v[130:133], 0
	v_mfma_f32_16x16x32_bf16 v[14:17], v[174:177], v[130:133], 0
	v_mfma_f32_16x16x32_bf16 v[18:21], v[162:165], v[134:137], 0
	v_mfma_f32_16x16x32_bf16 v[22:25], v[166:169], v[134:137], 0
	global_load_lds_dwordx4 v226, s[54:55] offset:1024
	v_mfma_f32_16x16x32_bf16 v[26:29], v[170:173], v[134:137], 0
	v_mfma_f32_16x16x32_bf16 v[30:33], v[174:177], v[134:137], 0
	v_mfma_f32_16x16x32_bf16 v[34:37], v[162:165], v[138:141], 0
	ds_read_b128 v[210:213], v241 offset:0
	v_mfma_f32_16x16x32_bf16 v[38:41], v[166:169], v[138:141], 0
	ds_read_b128 v[214:217], v241 offset:256
	v_mfma_f32_16x16x32_bf16 v[42:45], v[170:173], v[138:141], 0
	ds_read_b128 v[218:221], v241 offset:512
	global_load_lds_dwordx4 v226, s[54:55] offset:2048
	v_mfma_f32_16x16x32_bf16 v[46:49], v[174:177], v[138:141], 0
	ds_read_b128 v[222:225], v241 offset:768
	v_mfma_f32_16x16x32_bf16 v[50:53], v[162:165], v[142:145], 0
	ds_read_b128 v[178:181], v240 offset:0
	v_mfma_f32_16x16x32_bf16 v[54:57], v[166:169], v[142:145], 0
	ds_read_b128 v[182:185], v240 offset:1024
	v_mfma_f32_16x16x32_bf16 v[58:61], v[170:173], v[142:145], 0
	ds_read_b128 v[186:189], v240 offset:2048
	v_mfma_f32_16x16x32_bf16 v[62:65], v[174:177], v[142:145], 0
	ds_read_b128 v[190:193], v240 offset:3072
	global_load_lds_dwordx4 v226, s[54:55] offset:3072
	v_mfma_f32_16x16x32_bf16 v[66:69], v[162:165], v[146:149], 0
	ds_read_b128 v[194:197], v240 offset:4096
	v_mfma_f32_16x16x32_bf16 v[70:73], v[166:169], v[146:149], 0
	ds_read_b128 v[198:201], v240 offset:5120
	v_mfma_f32_16x16x32_bf16 v[74:77], v[170:173], v[146:149], 0
	ds_read_b128 v[202:205], v240 offset:6144
	v_mfma_f32_16x16x32_bf16 v[78:81], v[174:177], v[146:149], 0
	ds_read_b128 v[206:209], v240 offset:7168
	s_add_i32 m0, s60, s63
	v_mfma_f32_16x16x32_bf16 v[82:85], v[162:165], v[150:153], 0
	global_load_lds_dwordx4 v230, s[56:57]
	v_mfma_f32_16x16x32_bf16 v[86:89], v[166:169], v[150:153], 0
	v_mfma_f32_16x16x32_bf16 v[90:93], v[170:173], v[150:153], 0
	v_mfma_f32_16x16x32_bf16 v[94:97], v[174:177], v[150:153], 0
	v_mfma_f32_16x16x32_bf16 v[98:101], v[162:165], v[154:157], 0
	v_mfma_f32_16x16x32_bf16 v[102:105], v[166:169], v[154:157], 0
	global_load_lds_dwordx4 v231, s[56:57] offset:1024
	v_mfma_f32_16x16x32_bf16 v[106:109], v[170:173], v[154:157], 0
	v_mfma_f32_16x16x32_bf16 v[110:113], v[174:177], v[154:157], 0
	v_mfma_f32_16x16x32_bf16 v[114:117], v[162:165], v[158:161], 0
	v_mfma_f32_16x16x32_bf16 v[118:121], v[166:169], v[158:161], 0
	v_mfma_f32_16x16x32_bf16 v[122:125], v[170:173], v[158:161], 0
	v_mfma_f32_16x16x32_bf16 v[126:129], v[174:177], v[158:161], 0
	s_setprio 0
	s_add_i32 s60, s60, 0x6000
	s_cmp_eq_u32 s60, 0x12000
	s_cselect_b32 s60, 0, s60
	s_add_u32 s54, s54, s72
	s_addc_u32 s55, s55, 0
	s_add_u32 s56, s56, s73
	s_addc_u32 s57, s57, 0
	s_add_i32 s61, s61, 0x6000
	s_cmp_eq_u32 s61, 0x12000
	s_cselect_b32 s61, 0, s61
	s_waitcnt vmcnt(6) lgkmcnt(0)
	s_barrier
	v_add_u32_e32 v240, s61, v238
	v_add_u32_e32 v241, s61, v239
	s_setprio 1
	s_add_i32 m0, s60, s62
	v_mfma_f32_16x16x32_bf16 v[2:5], v[210:213], v[178:181], v[2:5]
	global_load_lds_dwordx4 v226, s[54:55]
	v_mfma_f32_16x16x32_bf16 v[6:9], v[214:217], v[178:181], v[6:9]
	v_mfma_f32_16x16x32_bf16 v[10:13], v[218:221], v[178:181], v[10:13]
	v_mfma_f32_16x16x32_bf16 v[14:17], v[222:225], v[178:181], v[14:17]
	v_mfma_f32_16x16x32_bf16 v[18:21], v[210:213], v[182:185], v[18:21]
	v_mfma_f32_16x16x32_bf16 v[22:25], v[214:217], v[182:185], v[22:25]
	global_load_lds_dwordx4 v226, s[54:55] offset:1024
	v_mfma_f32_16x16x32_bf16 v[26:29], v[218:221], v[182:185], v[26:29]
	v_mfma_f32_16x16x32_bf16 v[30:33], v[222:225], v[182:185], v[30:33]
	v_mfma_f32_16x16x32_bf16 v[34:37], v[210:213], v[186:189], v[34:37]
	ds_read_b128 v[162:165], v241 offset:0
	v_mfma_f32_16x16x32_bf16 v[38:41], v[214:217], v[186:189], v[38:41]
	ds_read_b128 v[166:169], v241 offset:256
	v_mfma_f32_16x16x32_bf16 v[42:45], v[218:221], v[186:189], v[42:45]
	ds_read_b128 v[170:173], v241 offset:512
	global_load_lds_dwordx4 v226, s[54:55] offset:2048
	v_mfma_f32_16x16x32_bf16 v[46:49], v[222:225], v[186:189], v[46:49]
	ds_read_b128 v[174:177], v241 offset:768
	v_mfma_f32_16x16x32_bf16 v[50:53], v[210:213], v[190:193], v[50:53]
	ds_read_b128 v[130:133], v240 offset:0
	v_mfma_f32_16x16x32_bf16 v[54:57], v[214:217], v[190:193], v[54:57]
	ds_read_b128 v[134:137], v240 offset:1024
	v_mfma_f32_16x16x32_bf16 v[58:61], v[218:221], v[190:193], v[58:61]
	ds_read_b128 v[138:141], v240 offset:2048
	v_mfma_f32_16x16x32_bf16 v[62:65], v[222:225], v[190:193], v[62:65]
	ds_read_b128 v[142:145], v240 offset:3072
	global_load_lds_dwordx4 v226, s[54:55] offset:3072
	v_mfma_f32_16x16x32_bf16 v[66:69], v[210:213], v[194:197], v[66:69]
	ds_read_b128 v[146:149], v240 offset:4096
	v_mfma_f32_16x16x32_bf16 v[70:73], v[214:217], v[194:197], v[70:73]
	ds_read_b128 v[150:153], v240 offset:5120
	v_mfma_f32_16x16x32_bf16 v[74:77], v[218:221], v[194:197], v[74:77]
	ds_read_b128 v[154:157], v240 offset:6144
	v_mfma_f32_16x16x32_bf16 v[78:81], v[222:225], v[194:197], v[78:81]
	ds_read_b128 v[158:161], v240 offset:7168
	s_add_i32 m0, s60, s63
	v_mfma_f32_16x16x32_bf16 v[82:85], v[210:213], v[198:201], v[82:85]
	global_load_lds_dwordx4 v230, s[56:57]
	v_mfma_f32_16x16x32_bf16 v[86:89], v[214:217], v[198:201], v[86:89]
	v_mfma_f32_16x16x32_bf16 v[90:93], v[218:221], v[198:201], v[90:93]
	v_mfma_f32_16x16x32_bf16 v[94:97], v[222:225], v[198:201], v[94:97]
	v_mfma_f32_16x16x32_bf16 v[98:101], v[210:213], v[202:205], v[98:101]
	v_mfma_f32_16x16x32_bf16 v[102:105], v[214:217], v[202:205], v[102:105]
	global_load_lds_dwordx4 v231, s[56:57] offset:1024
	v_mfma_f32_16x16x32_bf16 v[106:109], v[218:221], v[202:205], v[106:109]
	v_mfma_f32_16x16x32_bf16 v[110:113], v[222:225], v[202:205], v[110:113]
	v_mfma_f32_16x16x32_bf16 v[114:117], v[210:213], v[206:209], v[114:117]
	v_mfma_f32_16x16x32_bf16 v[118:121], v[214:217], v[206:209], v[118:121]
	v_mfma_f32_16x16x32_bf16 v[122:125], v[218:221], v[206:209], v[122:125]
	v_mfma_f32_16x16x32_bf16 v[126:129], v[222:225], v[206:209], v[126:129]
	s_setprio 0
	s_add_i32 s60, s60, 0x6000
	s_cmp_eq_u32 s60, 0x12000
	s_cselect_b32 s60, 0, s60
	s_add_u32 s54, s54, s72
	s_addc_u32 s55, s55, 0
	s_add_u32 s56, s56, s73
	s_addc_u32 s57, s57, 0
	s_add_i32 s61, s61, 0x6000
	s_cmp_eq_u32 s61, 0x12000
	s_cselect_b32 s61, 0, s61
	s_branch .Lgy_main

.Lgy_nn_b:
	s_waitcnt vmcnt(22) lgkmcnt(0)
	s_barrier
	v_add_u32_e32 v240, s61, v238
	v_add_u32_e32 v241, s61, v239
	s_setprio 1
	s_add_i32 m0, s60, s62
	v_mfma_f32_16x16x32_bf16 v[2:5], v[162:165], v[130:133], 0
	global_load_lds_dwordx4 v226, s[54:55]
	v_mfma_f32_16x16x32_bf16 v[6:9], v[166:169], v[130:133], 0
	v_mfma_f32_16x16x32_bf16 v[10:13], v[170:173], v[130:133], 0
	v_mfma_f32_16x16x32_bf16 v[14:17], v[174:177], v[130:133], 0
	v_mfma_f32_16x16x32_bf16 v[18:21], v[162:165], v[134:137], 0
	v_mfma_f32_16x16x32_bf16 v[22:25], v[166:169], v[134:137], 0
	global_load_lds_dwordx4 v226, s[54:55] offset:1024
	v_mfma_f32_16x16x32_bf16 v[26:29], v[170:173], v[134:137], 0
	v_mfma_f32_16x16x32_bf16 v[30:33], v[174:177], v[134:137], 0
	v_mfma_f32_16x16x32_bf16 v[34:37], v[162:165], v[138:141], 0
	ds_read_b128 v[210:213], v241 offset:0
	v_mfma_f32_16x16x32_bf16 v[38:41], v[166:169], v[138:141], 0
	ds_read_b128 v[214:217], v241 offset:256
	v_mfma_f32_16x16x32_bf16 v[42:45], v[170:173], v[138:141], 0
	ds_read_b128 v[218:221], v241 offset:512
	global_load_lds_dwordx4 v226, s[54:55] offset:2048
	v_mfma_f32_16x16x32_bf16 v[46:49], v[174:177], v[138:141], 0
	ds_read_b128 v[222:225], v241 offset:768
	v_mfma_f32_16x16x32_bf16 v[50:53], v[162:165], v[142:145], 0
	ds_read_b128 v[178:181], v240 offset:0
	v_mfma_f32_16x16x32_bf16 v[54:57], v[166:169], v[142:145], 0
	ds_read_b128 v[182:185], v240 offset:1024
	v_mfma_f32_16x16x32_bf16 v[58:61], v[170:173], v[142:145], 0
	ds_read_b128 v[186:189], v240 offset:2048
	v_mfma_f32_16x16x32_bf16 v[62:65], v[174:177], v[142:145], 0
	ds_read_b128 v[190:193], v240 offset:3072
	global_load_lds_dwordx4 v226, s[54:55] offset:3072
	v_mfma_f32_16x16x32_bf16 v[66:69], v[162:165], v[146:149], 0
	ds_read_b128 v[194:197], v240 offset:4096
	v_mfma_f32_16x16x32_bf16 v[70:73], v[166:169], v[146:149], 0
	ds_read_b128 v[198:201], v240 offset:5120
	v_mfma_f32_16x16x32_bf16 v[74:77], v[170:173], v[146:149], 0
	ds_read_b128 v[202:205], v240 offset:6144
	v_mfma_f32_16x16x32_bf16 v[78:81], v[174:177], v[146:149], 0
	ds_read_b128 v[206:209], v240 offset:7168
	s_add_i32 m0, s60, s63
	v_mfma_f32_16x16x32_bf16 v[82:85], v[162:165], v[150:153], 0
	global_load_lds_dwordx4 v230, s[56:57]
	v_mfma_f32_16x16x32_bf16 v[86:89], v[166:169], v[150:153], 0
	v_mfma_f32_16x16x32_bf16 v[90:93], v[170:173], v[150:153], 0
	v_mfma_f32_16x16x32_bf16 v[94:97], v[174:177], v[150:153], 0
	v_mfma_f32_16x16x32_bf16 v[98:101], v[162:165], v[154:157], 0
	v_mfma_f32_16x16x32_bf16 v[102:105], v[166:169], v[154:157], 0
	global_load_lds_dwordx4 v231, s[56:57] offset:1024
	v_mfma_f32_16x16x32_bf16 v[106:109], v[170:173], v[154:157], 0
	v_mfma_f32_16x16x32_bf16 v[110:113], v[174:177], v[154:157], 0
	v_mfma_f32_16x16x32_bf16 v[114:117], v[162:165], v[158:161], 0
	v_mfma_f32_16x16x32_bf16 v[118:121], v[166:169], v[158:161], 0
	v_mfma_f32_16x16x32_bf16 v[122:125], v[170:173], v[158:161], 0
	v_mfma_f32_16x16x32_bf16 v[126:129], v[174:177], v[158:161], 0
	s_setprio 0
	s_add_i32 s60, s60, 0x6000
	s_cmp_eq_u32 s60, 0x12000
	s_cselect_b32 s60, 0, s60
	s_add_u32 s54, s54, s72
	s_addc_u32 s55, s55, 0
	s_add_u32 s56, s56, s73
	s_addc_u32 s57, s57, 0
	s_add_i32 s61, s61, 0x6000
	s_cmp_eq_u32 s61, 0x12000
	s_cselect_b32 s61, 0, s61
	s_waitcnt vmcnt(22) lgkmcnt(0)
	s_barrier
	v_add_u32_e32 v240, s61, v238
	v_add_u32_e32 v241, s61, v239
	s_setprio 1
	s_add_i32 m0, s60, s62
	v_mfma_f32_16x16x32_bf16 v[2:5], v[210:213], v[178:181], v[2:5]
	global_load_lds_dwordx4 v226, s[54:55]
	v_mfma_f32_16x16x32_bf16 v[6:9], v[214:217], v[178:181], v[6:9]
	v_mfma_f32_16x16x32_bf16 v[10:13], v[218:221], v[178:181], v[10:13]
	v_mfma_f32_16x16x32_bf16 v[14:17], v[222:225], v[178:181], v[14:17]
	v_mfma_f32_16x16x32_bf16 v[18:21], v[210:213], v[182:185], v[18:21]
	v_mfma_f32_16x16x32_bf16 v[22:25], v[214:217], v[182:185], v[22:25]
	global_load_lds_dwordx4 v226, s[54:55] offset:1024
	v_mfma_f32_16x16x32_bf16 v[26:29], v[218:221], v[182:185], v[26:29]
	v_mfma_f32_16x16x32_bf16 v[30:33], v[222:225], v[182:185], v[30:33]
	v_mfma_f32_16x16x32_bf16 v[34:37], v[210:213], v[186:189], v[34:37]
	ds_read_b128 v[162:165], v241 offset:0
	v_mfma_f32_16x16x32_bf16 v[38:41], v[214:217], v[186:189], v[38:41]
	ds_read_b128 v[166:169], v241 offset:256
	v_mfma_f32_16x16x32_bf16 v[42:45], v[218:221], v[186:189], v[42:45]
	ds_read_b128 v[170:173], v241 offset:512
	global_load_lds_dwordx4 v226, s[54:55] offset:2048
	v_mfma_f32_16x16x32_bf16 v[46:49], v[222:225], v[186:189], v[46:49]
	ds_read_b128 v[174:177], v241 offset:768
	v_mfma_f32_16x16x32_bf16 v[50:53], v[210:213], v[190:193], v[50:53]
	ds_read_b128 v[130:133], v240 offset:0
	v_mfma_f32_16x16x32_bf16 v[54:57], v[214:217], v[190:193], v[54:57]
	ds_read_b128 v[134:137], v240 offset:1024
	v_mfma_f32_16x16x32_bf16 v[58:61], v[218:221], v[190:193], v[58:61]
	ds_read_b128 v[138:141], v240 offset:2048
	v_mfma_f32_16x16x32_bf16 v[62:65], v[222:225], v[190:193], v[62:65]
	ds_read_b128 v[142:145], v240 offset:3072
	global_load_lds_dwordx4 v226, s[54:55] offset:3072
	v_mfma_f32_16x16x32_bf16 v[66:69], v[210:213], v[194:197], v[66:69]
	ds_read_b128 v[146:149], v240 offset:4096
	v_mfma_f32_16x16x32_bf16 v[70:73], v[214:217], v[194:197], v[70:73]
	ds_read_b128 v[150:153], v240 offset:5120
	v_mfma_f32_16x16x32_bf16 v[74:77], v[218:221], v[194:197], v[74:77]
	ds_read_b128 v[154:157], v240 offset:6144
	v_mfma_f32_16x16x32_bf16 v[78:81], v[222:225], v[194:197], v[78:81]
	ds_read_b128 v[158:161], v240 offset:7168
	s_add_i32 m0, s60, s63
	v_mfma_f32_16x16x32_bf16 v[82:85], v[210:213], v[198:201], v[82:85]
	global_load_lds_dwordx4 v230, s[56:57]
	v_mfma_f32_16x16x32_bf16 v[86:89], v[214:217], v[198:201], v[86:89]
	v_mfma_f32_16x16x32_bf16 v[90:93], v[218:221], v[198:201], v[90:93]
	v_mfma_f32_16x16x32_bf16 v[94:97], v[222:225], v[198:201], v[94:97]
	v_mfma_f32_16x16x32_bf16 v[98:101], v[210:213], v[202:205], v[98:101]
	v_mfma_f32_16x16x32_bf16 v[102:105], v[214:217], v[202:205], v[102:105]
	global_load_lds_dwordx4 v231, s[56:57] offset:1024
	v_mfma_f32_16x16x32_bf16 v[106:109], v[218:221], v[202:205], v[106:109]
	v_mfma_f32_16x16x32_bf16 v[110:113], v[222:225], v[202:205], v[110:113]
	v_mfma_f32_16x16x32_bf16 v[114:117], v[210:213], v[206:209], v[114:117]
	v_mfma_f32_16x16x32_bf16 v[118:121], v[214:217], v[206:209], v[118:121]
	v_mfma_f32_16x16x32_bf16 v[122:125], v[218:221], v[206:209], v[122:125]
	v_mfma_f32_16x16x32_bf16 v[126:129], v[222:225], v[206:209], v[126:129]
	s_setprio 0
	s_add_i32 s60, s60, 0x6000
	s_cmp_eq_u32 s60, 0x12000
	s_cselect_b32 s60, 0, s60
	s_add_u32 s54, s54, s72
	s_addc_u32 s55, s55, 0
	s_add_u32 s56, s56, s73
	s_addc_u32 s57, s57, 0
	s_add_i32 s61, s61, 0x6000
	s_cmp_eq_u32 s61, 0x12000
	s_cselect_b32 s61, 0, s61

.Lgy_kloop:
	s_waitcnt vmcnt(6) lgkmcnt(0)
	s_barrier
	v_add_u32_e32 v240, s61, v238
	v_add_u32_e32 v241, s61, v239
	s_setprio 1
	s_add_i32 m0, s60, s62
	v_mfma_f32_16x16x32_bf16 v[2:5], v[162:165], v[130:133], v[2:5]
	global_load_lds_dwordx4 v226, s[54:55]
	v_mfma_f32_16x16x32_bf16 v[6:9], v[166:169], v[130:133], v[6:9]
	v_mfma_f32_16x16x32_bf16 v[10:13], v[170:173], v[130:133], v[10:13]
	v_mfma_f32_16x16x32_bf16 v[14:17], v[174:177], v[130:133], v[14:17]
	v_mfma_f32_16x16x32_bf16 v[18:21], v[162:165], v[134:137], v[18:21]
	v_mfma_f32_16x16x32_bf16 v[22:25], v[166:169], v[134:137], v[22:25]
	global_load_lds_dwordx4 v226, s[54:55] offset:1024
	v_mfma_f32_16x16x32_bf16 v[26:29], v[170:173], v[134:137], v[26:29]
	v_mfma_f32_16x16x32_bf16 v[30:33], v[174:177], v[134:137], v[30:33]
	v_mfma_f32_16x16x32_bf16 v[34:37], v[162:165], v[138:141], v[34:37]
	ds_read_b128 v[210:213], v241 offset:0
	v_mfma_f32_16x16x32_bf16 v[38:41], v[166:169], v[138:141], v[38:41]
	ds_read_b128 v[214:217], v241 offset:256
	v_mfma_f32_16x16x32_bf16 v[42:45], v[170:173], v[138:141], v[42:45]
	ds_read_b128 v[218:221], v241 offset:512
	global_load_lds_dwordx4 v226, s[54:55] offset:2048
	v_mfma_f32_16x16x32_bf16 v[46:49], v[174:177], v[138:141], v[46:49]
	ds_read_b128 v[222:225], v241 offset:768
	v_mfma_f32_16x16x32_bf16 v[50:53], v[162:165], v[142:145], v[50:53]
	ds_read_b128 v[178:181], v240 offset:0
	v_mfma_f32_16x16x32_bf16 v[54:57], v[166:169], v[142:145], v[54:57]
	ds_read_b128 v[182:185], v240 offset:1024
	v_mfma_f32_16x16x32_bf16 v[58:61], v[170:173], v[142:145], v[58:61]
	ds_read_b128 v[186:189], v240 offset:2048
	v_mfma_f32_16x16x32_bf16 v[62:65], v[174:177], v[142:145], v[62:65]
	ds_read_b128 v[190:193], v240 offset:3072
	global_load_lds_dwordx4 v226, s[54:55] offset:3072
	v_mfma_f32_16x16x32_bf16 v[66:69], v[162:165], v[146:149], v[66:69]
	ds_read_b128 v[194:197], v240 offset:4096
	v_mfma_f32_16x16x32_bf16 v[70:73], v[166:169], v[146:149], v[70:73]
	ds_read_b128 v[198:201], v240 offset:5120
	v_mfma_f32_16x16x32_bf16 v[74:77], v[170:173], v[146:149], v[74:77]
	ds_read_b128 v[202:205], v240 offset:6144
	v_mfma_f32_16x16x32_bf16 v[78:81], v[174:177], v[146:149], v[78:81]
	ds_read_b128 v[206:209], v240 offset:7168
	s_add_i32 m0, s60, s63
	v_mfma_f32_16x16x32_bf16 v[82:85], v[162:165], v[150:153], v[82:85]
	global_load_lds_dwordx4 v230, s[56:57]
	v_mfma_f32_16x16x32_bf16 v[86:89], v[166:169], v[150:153], v[86:89]
	v_mfma_f32_16x16x32_bf16 v[90:93], v[170:173], v[150:153], v[90:93]
	v_mfma_f32_16x16x32_bf16 v[94:97], v[174:177], v[150:153], v[94:97]
	v_mfma_f32_16x16x32_bf16 v[98:101], v[162:165], v[154:157], v[98:101]
	v_mfma_f32_16x16x32_bf16 v[102:105], v[166:169], v[154:157], v[102:105]
	global_load_lds_dwordx4 v231, s[56:57] offset:1024
	v_mfma_f32_16x16x32_bf16 v[106:109], v[170:173], v[154:157], v[106:109]
	v_mfma_f32_16x16x32_bf16 v[110:113], v[174:177], v[154:157], v[110:113]
	v_mfma_f32_16x16x32_bf16 v[114:117], v[162:165], v[158:161], v[114:117]
	v_mfma_f32_16x16x32_bf16 v[118:121], v[166:169], v[158:161], v[118:121]
	v_mfma_f32_16x16x32_bf16 v[122:125], v[170:173], v[158:161], v[122:125]
	v_mfma_f32_16x16x32_bf16 v[126:129], v[174:177], v[158:161], v[126:129]
	s_setprio 0
	s_add_i32 s60, s60, 0x6000
	s_cmp_eq_u32 s60, 0x12000
	s_cselect_b32 s60, 0, s60
	s_add_u32 s54, s54, s72
	s_addc_u32 s55, s55, 0
	s_add_u32 s56, s56, s73
	s_addc_u32 s57, s57, 0
	s_add_i32 s61, s61, 0x6000
	s_cmp_eq_u32 s61, 0x12000
	s_cselect_b32 s61, 0, s61
	s_waitcnt vmcnt(6) lgkmcnt(0)
	s_barrier
	v_add_u32_e32 v240, s61, v238
	v_add_u32_e32 v241, s61, v239
	s_setprio 1
	s_add_i32 m0, s60, s62
	v_mfma_f32_16x16x32_bf16 v[2:5], v[210:213], v[178:181], v[2:5]
	global_load_lds_dwordx4 v226, s[54:55]
	v_mfma_f32_16x16x32_bf16 v[6:9], v[214:217], v[178:181], v[6:9]
	v_mfma_f32_16x16x32_bf16 v[10:13], v[218:221], v[178:181], v[10:13]
	v_mfma_f32_16x16x32_bf16 v[14:17], v[222:225], v[178:181], v[14:17]
	v_mfma_f32_16x16x32_bf16 v[18:21], v[210:213], v[182:185], v[18:21]
	v_mfma_f32_16x16x32_bf16 v[22:25], v[214:217], v[182:185], v[22:25]
	global_load_lds_dwordx4 v226, s[54:55] offset:1024
	v_mfma_f32_16x16x32_bf16 v[26:29], v[218:221], v[182:185], v[26:29]
	v_mfma_f32_16x16x32_bf16 v[30:33], v[222:225], v[182:185], v[30:33]
	v_mfma_f32_16x16x32_bf16 v[34:37], v[210:213], v[186:189], v[34:37]
	ds_read_b128 v[162:165], v241 offset:0
	v_mfma_f32_16x16x32_bf16 v[38:41], v[214:217], v[186:189], v[38:41]
	ds_read_b128 v[166:169], v241 offset:256
	v_mfma_f32_16x16x32_bf16 v[42:45], v[218:221], v[186:189], v[42:45]
	ds_read_b128 v[170:173], v241 offset:512
	global_load_lds_dwordx4 v226, s[54:55] offset:2048
	v_mfma_f32_16x16x32_bf16 v[46:49], v[222:225], v[186:189], v[46:49]
	ds_read_b128 v[174:177], v241 offset:768
	v_mfma_f32_16x16x32_bf16 v[50:53], v[210:213], v[190:193], v[50:53]
	ds_read_b128 v[130:133], v240 offset:0
	v_mfma_f32_16x16x32_bf16 v[54:57], v[214:217], v[190:193], v[54:57]
	ds_read_b128 v[134:137], v240 offset:1024
	v_mfma_f32_16x16x32_bf16 v[58:61], v[218:221], v[190:193], v[58:61]
	ds_read_b128 v[138:141], v240 offset:2048
	v_mfma_f32_16x16x32_bf16 v[62:65], v[222:225], v[190:193], v[62:65]
	ds_read_b128 v[142:145], v240 offset:3072
	global_load_lds_dwordx4 v226, s[54:55] offset:3072
	v_mfma_f32_16x16x32_bf16 v[66:69], v[210:213], v[194:197], v[66:69]
	ds_read_b128 v[146:149], v240 offset:4096
	v_mfma_f32_16x16x32_bf16 v[70:73], v[214:217], v[194:197], v[70:73]
	ds_read_b128 v[150:153], v240 offset:5120
	v_mfma_f32_16x16x32_bf16 v[74:77], v[218:221], v[194:197], v[74:77]
	ds_read_b128 v[154:157], v240 offset:6144
	v_mfma_f32_16x16x32_bf16 v[78:81], v[222:225], v[194:197], v[78:81]
	ds_read_b128 v[158:161], v240 offset:7168
	s_add_i32 m0, s60, s63
	v_mfma_f32_16x16x32_bf16 v[82:85], v[210:213], v[198:201], v[82:85]
	global_load_lds_dwordx4 v230, s[56:57]
	v_mfma_f32_16x16x32_bf16 v[86:89], v[214:217], v[198:201], v[86:89]
	v_mfma_f32_16x16x32_bf16 v[90:93], v[218:221], v[198:201], v[90:93]
	v_mfma_f32_16x16x32_bf16 v[94:97], v[222:225], v[198:201], v[94:97]
	v_mfma_f32_16x16x32_bf16 v[98:101], v[210:213], v[202:205], v[98:101]
	v_mfma_f32_16x16x32_bf16 v[102:105], v[214:217], v[202:205], v[102:105]
	global_load_lds_dwordx4 v231, s[56:57] offset:1024
	v_mfma_f32_16x16x32_bf16 v[106:109], v[218:221], v[202:205], v[106:109]
	v_mfma_f32_16x16x32_bf16 v[110:113], v[222:225], v[202:205], v[110:113]
	v_mfma_f32_16x16x32_bf16 v[114:117], v[210:213], v[206:209], v[114:117]
	v_mfma_f32_16x16x32_bf16 v[118:121], v[214:217], v[206:209], v[118:121]
	v_mfma_f32_16x16x32_bf16 v[122:125], v[218:221], v[206:209], v[122:125]
	v_mfma_f32_16x16x32_bf16 v[126:129], v[222:225], v[206:209], v[126:129]
	s_setprio 0
	s_add_i32 s60, s60, 0x6000
	s_cmp_eq_u32 s60, 0x12000
	s_cselect_b32 s60, 0, s60
	s_add_u32 s54, s54, s72
	s_addc_u32 s55, s55, 0
	s_add_u32 s56, s56, s73
	s_addc_u32 s57, s57, 0
	s_add_i32 s61, s61, 0x6000
	s_cmp_eq_u32 s61, 0x12000
	s_cselect_b32 s61, 0, s61
	s_add_i32 s40, s40, -1
	s_cmp_lg_u32 s40, 0
	s_cbranch_scc1 .Lgy_kloop
.Lgy_kdone:
	s_cmp_eq_u32 s37, 0
	s_cbranch_scc1 .Lgy_tail_last
	s_waitcnt vmcnt(6) lgkmcnt(0)
	s_barrier
	v_add_u32_e32 v240, s61, v238
	v_add_u32_e32 v241, s61, v239
	s_setprio 1
	s_add_i32 m0, s60, s62
	v_mfma_f32_16x16x32_bf16 v[2:5], v[162:165], v[130:133], v[2:5]
	global_load_lds_dwordx4 v226, s[54:55]
	v_mfma_f32_16x16x32_bf16 v[6:9], v[166:169], v[130:133], v[6:9]
	v_mfma_f32_16x16x32_bf16 v[10:13], v[170:173], v[130:133], v[10:13]
	v_mfma_f32_16x16x32_bf16 v[14:17], v[174:177], v[130:133], v[14:17]
	v_mfma_f32_16x16x32_bf16 v[18:21], v[162:165], v[134:137], v[18:21]
	v_mfma_f32_16x16x32_bf16 v[22:25], v[166:169], v[134:137], v[22:25]
	global_load_lds_dwordx4 v226, s[54:55] offset:1024
	v_mfma_f32_16x16x32_bf16 v[26:29], v[170:173], v[134:137], v[26:29]
	v_mfma_f32_16x16x32_bf16 v[30:33], v[174:177], v[134:137], v[30:33]
	v_mfma_f32_16x16x32_bf16 v[34:37], v[162:165], v[138:141], v[34:37]
	ds_read_b128 v[210:213], v241 offset:0
	v_mfma_f32_16x16x32_bf16 v[38:41], v[166:169], v[138:141], v[38:41]
	ds_read_b128 v[214:217], v241 offset:256
	v_mfma_f32_16x16x32_bf16 v[42:45], v[170:173], v[138:141], v[42:45]
	ds_read_b128 v[218:221], v241 offset:512
	global_load_lds_dwordx4 v226, s[54:55] offset:2048
	v_mfma_f32_16x16x32_bf16 v[46:49], v[174:177], v[138:141], v[46:49]
	ds_read_b128 v[222:225], v241 offset:768
	v_mfma_f32_16x16x32_bf16 v[50:53], v[162:165], v[142:145], v[50:53]
	ds_read_b128 v[178:181], v240 offset:0
	v_mfma_f32_16x16x32_bf16 v[54:57], v[166:169], v[142:145], v[54:57]
	ds_read_b128 v[182:185], v240 offset:1024
	v_mfma_f32_16x16x32_bf16 v[58:61], v[170:173], v[142:145], v[58:61]
	ds_read_b128 v[186:189], v240 offset:2048
	v_mfma_f32_16x16x32_bf16 v[62:65], v[174:177], v[142:145], v[62:65]
	ds_read_b128 v[190:193], v240 offset:3072
	global_load_lds_dwordx4 v226, s[54:55] offset:3072
	v_mfma_f32_16x16x32_bf16 v[66:69], v[162:165], v[146:149], v[66:69]
	ds_read_b128 v[194:197], v240 offset:4096
	v_mfma_f32_16x16x32_bf16 v[70:73], v[166:169], v[146:149], v[70:73]
	ds_read_b128 v[198:201], v240 offset:5120
	v_mfma_f32_16x16x32_bf16 v[74:77], v[170:173], v[146:149], v[74:77]
	ds_read_b128 v[202:205], v240 offset:6144
	v_mfma_f32_16x16x32_bf16 v[78:81], v[174:177], v[146:149], v[78:81]
	ds_read_b128 v[206:209], v240 offset:7168
	s_add_i32 m0, s60, s63
	v_mfma_f32_16x16x32_bf16 v[82:85], v[162:165], v[150:153], v[82:85]
	global_load_lds_dwordx4 v230, s[56:57]
	v_mfma_f32_16x16x32_bf16 v[86:89], v[166:169], v[150:153], v[86:89]
	v_mfma_f32_16x16x32_bf16 v[90:93], v[170:173], v[150:153], v[90:93]
	v_mfma_f32_16x16x32_bf16 v[94:97], v[174:177], v[150:153], v[94:97]
	v_mfma_f32_16x16x32_bf16 v[98:101], v[162:165], v[154:157], v[98:101]
	v_mfma_f32_16x16x32_bf16 v[102:105], v[166:169], v[154:157], v[102:105]
	global_load_lds_dwordx4 v231, s[56:57] offset:1024
	v_mfma_f32_16x16x32_bf16 v[106:109], v[170:173], v[154:157], v[106:109]
	v_mfma_f32_16x16x32_bf16 v[110:113], v[174:177], v[154:157], v[110:113]
	v_mfma_f32_16x16x32_bf16 v[114:117], v[162:165], v[158:161], v[114:117]
	v_mfma_f32_16x16x32_bf16 v[118:121], v[166:169], v[158:161], v[118:121]
	v_mfma_f32_16x16x32_bf16 v[122:125], v[170:173], v[158:161], v[122:125]
	v_mfma_f32_16x16x32_bf16 v[126:129], v[174:177], v[158:161], v[126:129]
	s_setprio 0
	s_add_i32 s60, s60, 0x6000
	s_cmp_eq_u32 s60, 0x12000
	s_cselect_b32 s60, 0, s60
	s_add_u32 s54, s54, s72
	s_addc_u32 s55, s55, 0
	s_add_u32 s56, s56, s73
	s_addc_u32 s57, s57, 0
	s_add_i32 s61, s61, 0x6000
	s_cmp_eq_u32 s61, 0x12000
	s_cselect_b32 s61, 0, s61
	v_mov_b32_e32 v226, v232
	v_mov_b32_e32 v230, v236
	v_mov_b32_e32 v231, v237
	s_mov_b64 s[54:55], s[48:49]
	s_mov_b64 s[56:57], s[50:51]
	s_waitcnt vmcnt(6) lgkmcnt(0)
	s_barrier
	v_add_u32_e32 v240, s61, v238
	v_add_u32_e32 v241, s61, v239
	s_setprio 1
	s_add_i32 m0, s60, s62
	v_mfma_f32_16x16x32_bf16 v[2:5], v[210:213], v[178:181], v[2:5]
	global_load_lds_dwordx4 v226, s[54:55]
	v_mfma_f32_16x16x32_bf16 v[6:9], v[214:217], v[178:181], v[6:9]
	v_mfma_f32_16x16x32_bf16 v[10:13], v[218:221], v[178:181], v[10:13]
	v_mfma_f32_16x16x32_bf16 v[14:17], v[222:225], v[178:181], v[14:17]
	v_mfma_f32_16x16x32_bf16 v[18:21], v[210:213], v[182:185], v[18:21]
	v_mfma_f32_16x16x32_bf16 v[22:25], v[214:217], v[182:185], v[22:25]
	global_load_lds_dwordx4 v226, s[54:55] offset:1024
	v_mfma_f32_16x16x32_bf16 v[26:29], v[218:221], v[182:185], v[26:29]
	v_mfma_f32_16x16x32_bf16 v[30:33], v[222:225], v[182:185], v[30:33]
	v_mfma_f32_16x16x32_bf16 v[34:37], v[210:213], v[186:189], v[34:37]
	ds_read_b128 v[162:165], v241 offset:0
	v_mfma_f32_16x16x32_bf16 v[38:41], v[214:217], v[186:189], v[38:41]
	ds_read_b128 v[166:169], v241 offset:256
	v_mfma_f32_16x16x32_bf16 v[42:45], v[218:221], v[186:189], v[42:45]
	ds_read_b128 v[170:173], v241 offset:512
	global_load_lds_dwordx4 v226, s[54:55] offset:2048
	v_mfma_f32_16x16x32_bf16 v[46:49], v[222:225], v[186:189], v[46:49]
	ds_read_b128 v[174:177], v241 offset:768
	v_mfma_f32_16x16x32_bf16 v[50:53], v[210:213], v[190:193], v[50:53]
	ds_read_b128 v[130:133], v240 offset:0
	v_mfma_f32_16x16x32_bf16 v[54:57], v[214:217], v[190:193], v[54:57]
	ds_read_b128 v[134:137], v240 offset:1024
	v_mfma_f32_16x16x32_bf16 v[58:61], v[218:221], v[190:193], v[58:61]
	ds_read_b128 v[138:141], v240 offset:2048
	v_mfma_f32_16x16x32_bf16 v[62:65], v[222:225], v[190:193], v[62:65]
	ds_read_b128 v[142:145], v240 offset:3072
	global_load_lds_dwordx4 v226, s[54:55] offset:3072
	v_mfma_f32_16x16x32_bf16 v[66:69], v[210:213], v[194:197], v[66:69]
	ds_read_b128 v[146:149], v240 offset:4096
	v_mfma_f32_16x16x32_bf16 v[70:73], v[214:217], v[194:197], v[70:73]
	ds_read_b128 v[150:153], v240 offset:5120
	v_mfma_f32_16x16x32_bf16 v[74:77], v[218:221], v[194:197], v[74:77]
	ds_read_b128 v[154:157], v240 offset:6144
	v_mfma_f32_16x16x32_bf16 v[78:81], v[222:225], v[194:197], v[78:81]
	ds_read_b128 v[158:161], v240 offset:7168
	s_add_i32 m0, s60, s63
	v_mfma_f32_16x16x32_bf16 v[82:85], v[210:213], v[198:201], v[82:85]
	global_load_lds_dwordx4 v230, s[56:57]
	v_mfma_f32_16x16x32_bf16 v[86:89], v[214:217], v[198:201], v[86:89]
	v_mfma_f32_16x16x32_bf16 v[90:93], v[218:221], v[198:201], v[90:93]
	v_mfma_f32_16x16x32_bf16 v[94:97], v[222:225], v[198:201], v[94:97]
	v_mfma_f32_16x16x32_bf16 v[98:101], v[210:213], v[202:205], v[98:101]
	v_mfma_f32_16x16x32_bf16 v[102:105], v[214:217], v[202:205], v[102:105]
	global_load_lds_dwordx4 v231, s[56:57] offset:1024
	v_mfma_f32_16x16x32_bf16 v[106:109], v[218:221], v[202:205], v[106:109]
	v_mfma_f32_16x16x32_bf16 v[110:113], v[222:225], v[202:205], v[110:113]
	v_mfma_f32_16x16x32_bf16 v[114:117], v[210:213], v[206:209], v[114:117]
	v_mfma_f32_16x16x32_bf16 v[118:121], v[214:217], v[206:209], v[118:121]
	v_mfma_f32_16x16x32_bf16 v[122:125], v[218:221], v[206:209], v[122:125]
	v_mfma_f32_16x16x32_bf16 v[126:129], v[222:225], v[206:209], v[126:129]
	s_setprio 0
	s_add_i32 s60, s60, 0x6000
	s_cmp_eq_u32 s60, 0x12000
	s_cselect_b32 s60, 0, s60
	s_add_u32 s54, s54, s72
	s_addc_u32 s55, s55, 0
	s_add_u32 s56, s56, s73
	s_addc_u32 s57, s57, 0
	s_add_i32 s61, s61, 0x6000
	s_cmp_eq_u32 s61, 0x12000
	s_cselect_b32 s61, 0, s61
	s_waitcnt vmcnt(6) lgkmcnt(0)
	s_barrier
	v_add_u32_e32 v240, s61, v238
	v_add_u32_e32 v241, s61, v239
	s_setprio 1
	s_add_i32 m0, s60, s62
	v_mfma_f32_16x16x32_bf16 v[2:5], v[162:165], v[130:133], v[2:5]
	global_load_lds_dwordx4 v226, s[54:55]
	v_mfma_f32_16x16x32_bf16 v[6:9], v[166:169], v[130:133], v[6:9]
	v_mfma_f32_16x16x32_bf16 v[10:13], v[170:173], v[130:133], v[10:13]
	v_mfma_f32_16x16x32_bf16 v[14:17], v[174:177], v[130:133], v[14:17]
	v_mfma_f32_16x16x32_bf16 v[18:21], v[162:165], v[134:137], v[18:21]
	v_mfma_f32_16x16x32_bf16 v[22:25], v[166:169], v[134:137], v[22:25]
	global_load_lds_dwordx4 v226, s[54:55] offset:1024
	v_mfma_f32_16x16x32_bf16 v[26:29], v[170:173], v[134:137], v[26:29]
	v_mfma_f32_16x16x32_bf16 v[30:33], v[174:177], v[134:137], v[30:33]
	v_mfma_f32_16x16x32_bf16 v[34:37], v[162:165], v[138:141], v[34:37]
	ds_read_b128 v[210:213], v241 offset:0
	v_mfma_f32_16x16x32_bf16 v[38:41], v[166:169], v[138:141], v[38:41]
	ds_read_b128 v[214:217], v241 offset:256
	v_mfma_f32_16x16x32_bf16 v[42:45], v[170:173], v[138:141], v[42:45]
	ds_read_b128 v[218:221], v241 offset:512
	global_load_lds_dwordx4 v226, s[54:55] offset:2048
	v_mfma_f32_16x16x32_bf16 v[46:49], v[174:177], v[138:141], v[46:49]
	ds_read_b128 v[222:225], v241 offset:768
	v_mfma_f32_16x16x32_bf16 v[50:53], v[162:165], v[142:145], v[50:53]
	ds_read_b128 v[178:181], v240 offset:0
	v_mfma_f32_16x16x32_bf16 v[54:57], v[166:169], v[142:145], v[54:57]
	ds_read_b128 v[182:185], v240 offset:1024
	v_mfma_f32_16x16x32_bf16 v[58:61], v[170:173], v[142:145], v[58:61]
	ds_read_b128 v[186:189], v240 offset:2048
	v_mfma_f32_16x16x32_bf16 v[62:65], v[174:177], v[142:145], v[62:65]
	ds_read_b128 v[190:193], v240 offset:3072
	global_load_lds_dwordx4 v226, s[54:55] offset:3072
	v_mfma_f32_16x16x32_bf16 v[66:69], v[162:165], v[146:149], v[66:69]
	ds_read_b128 v[194:197], v240 offset:4096
	v_mfma_f32_16x16x32_bf16 v[70:73], v[166:169], v[146:149], v[70:73]
	ds_read_b128 v[198:201], v240 offset:5120
	v_mfma_f32_16x16x32_bf16 v[74:77], v[170:173], v[146:149], v[74:77]
	ds_read_b128 v[202:205], v240 offset:6144
	v_mfma_f32_16x16x32_bf16 v[78:81], v[174:177], v[146:149], v[78:81]
	ds_read_b128 v[206:209], v240 offset:7168
	s_add_i32 m0, s60, s63
	v_mfma_f32_16x16x32_bf16 v[82:85], v[162:165], v[150:153], v[82:85]
	global_load_lds_dwordx4 v230, s[56:57]
	v_mfma_f32_16x16x32_bf16 v[86:89], v[166:169], v[150:153], v[86:89]
	v_mfma_f32_16x16x32_bf16 v[90:93], v[170:173], v[150:153], v[90:93]
	v_mfma_f32_16x16x32_bf16 v[94:97], v[174:177], v[150:153], v[94:97]
	v_mfma_f32_16x16x32_bf16 v[98:101], v[162:165], v[154:157], v[98:101]
	v_mfma_f32_16x16x32_bf16 v[102:105], v[166:169], v[154:157], v[102:105]
	global_load_lds_dwordx4 v231, s[56:57] offset:1024
	v_mfma_f32_16x16x32_bf16 v[106:109], v[170:173], v[154:157], v[106:109]
	v_mfma_f32_16x16x32_bf16 v[110:113], v[174:177], v[154:157], v[110:113]
	v_mfma_f32_16x16x32_bf16 v[114:117], v[162:165], v[158:161], v[114:117]
	v_mfma_f32_16x16x32_bf16 v[118:121], v[166:169], v[158:161], v[118:121]
	v_mfma_f32_16x16x32_bf16 v[122:125], v[170:173], v[158:161], v[122:125]
	v_mfma_f32_16x16x32_bf16 v[126:129], v[174:177], v[158:161], v[126:129]
	s_setprio 0
	s_add_i32 s60, s60, 0x6000
	s_cmp_eq_u32 s60, 0x12000
	s_cselect_b32 s60, 0, s60
	s_add_u32 s54, s54, s72
	s_addc_u32 s55, s55, 0
	s_add_u32 s56, s56, s73
	s_addc_u32 s57, s57, 0
	s_add_i32 s61, s61, 0x6000
	s_cmp_eq_u32 s61, 0x12000
	s_cselect_b32 s61, 0, s61
	s_waitcnt vmcnt(6) lgkmcnt(0)
	s_barrier
	v_add_u32_e32 v240, s61, v238
	v_add_u32_e32 v241, s61, v239
	s_setprio 1
	s_add_i32 m0, s60, s62
	v_mfma_f32_16x16x32_bf16 v[2:5], v[210:213], v[178:181], v[2:5]
	global_load_lds_dwordx4 v226, s[54:55]
	v_mfma_f32_16x16x32_bf16 v[6:9], v[214:217], v[178:181], v[6:9]
	v_mfma_f32_16x16x32_bf16 v[10:13], v[218:221], v[178:181], v[10:13]
	v_mfma_f32_16x16x32_bf16 v[14:17], v[222:225], v[178:181], v[14:17]
	v_mfma_f32_16x16x32_bf16 v[18:21], v[210:213], v[182:185], v[18:21]
	v_mfma_f32_16x16x32_bf16 v[22:25], v[214:217], v[182:185], v[22:25]
	global_load_lds_dwordx4 v226, s[54:55] offset:1024
	v_mfma_f32_16x16x32_bf16 v[26:29], v[218:221], v[182:185], v[26:29]
	v_mfma_f32_16x16x32_bf16 v[30:33], v[222:225], v[182:185], v[30:33]
	v_mfma_f32_16x16x32_bf16 v[34:37], v[210:213], v[186:189], v[34:37]
	ds_read_b128 v[162:165], v241 offset:0
	v_mfma_f32_16x16x32_bf16 v[38:41], v[214:217], v[186:189], v[38:41]
	ds_read_b128 v[166:169], v241 offset:256
	v_mfma_f32_16x16x32_bf16 v[42:45], v[218:221], v[186:189], v[42:45]
	ds_read_b128 v[170:173], v241 offset:512
	global_load_lds_dwordx4 v226, s[54:55] offset:2048
	v_mfma_f32_16x16x32_bf16 v[46:49], v[222:225], v[186:189], v[46:49]
	ds_read_b128 v[174:177], v241 offset:768
	v_mfma_f32_16x16x32_bf16 v[50:53], v[210:213], v[190:193], v[50:53]
	ds_read_b128 v[130:133], v240 offset:0
	v_mfma_f32_16x16x32_bf16 v[54:57], v[214:217], v[190:193], v[54:57]
	ds_read_b128 v[134:137], v240 offset:1024
	v_mfma_f32_16x16x32_bf16 v[58:61], v[218:221], v[190:193], v[58:61]
	ds_read_b128 v[138:141], v240 offset:2048
	v_mfma_f32_16x16x32_bf16 v[62:65], v[222:225], v[190:193], v[62:65]
	ds_read_b128 v[142:145], v240 offset:3072
	global_load_lds_dwordx4 v226, s[54:55] offset:3072
	v_mfma_f32_16x16x32_bf16 v[66:69], v[210:213], v[194:197], v[66:69]
	ds_read_b128 v[146:149], v240 offset:4096
	v_mfma_f32_16x16x32_bf16 v[70:73], v[214:217], v[194:197], v[70:73]
	ds_read_b128 v[150:153], v240 offset:5120
	v_mfma_f32_16x16x32_bf16 v[74:77], v[218:221], v[194:197], v[74:77]
	ds_read_b128 v[154:157], v240 offset:6144
	v_mfma_f32_16x16x32_bf16 v[78:81], v[222:225], v[194:197], v[78:81]
	ds_read_b128 v[158:161], v240 offset:7168
	s_add_i32 m0, s60, s63
	v_mfma_f32_16x16x32_bf16 v[82:85], v[210:213], v[198:201], v[82:85]
	global_load_lds_dwordx4 v230, s[56:57]
	v_mfma_f32_16x16x32_bf16 v[86:89], v[214:217], v[198:201], v[86:89]
	v_mfma_f32_16x16x32_bf16 v[90:93], v[218:221], v[198:201], v[90:93]
	v_mfma_f32_16x16x32_bf16 v[94:97], v[222:225], v[198:201], v[94:97]
	v_mfma_f32_16x16x32_bf16 v[98:101], v[210:213], v[202:205], v[98:101]
	v_mfma_f32_16x16x32_bf16 v[102:105], v[214:217], v[202:205], v[102:105]
	global_load_lds_dwordx4 v231, s[56:57] offset:1024
	v_mfma_f32_16x16x32_bf16 v[106:109], v[218:221], v[202:205], v[106:109]
	v_mfma_f32_16x16x32_bf16 v[110:113], v[222:225], v[202:205], v[110:113]
	v_mfma_f32_16x16x32_bf16 v[114:117], v[210:213], v[206:209], v[114:117]
	v_mfma_f32_16x16x32_bf16 v[118:121], v[214:217], v[206:209], v[118:121]
	v_mfma_f32_16x16x32_bf16 v[122:125], v[218:221], v[206:209], v[122:125]
	v_mfma_f32_16x16x32_bf16 v[126:129], v[222:225], v[206:209], v[126:129]
	s_setprio 0
	s_add_i32 s60, s60, 0x6000
	s_cmp_eq_u32 s60, 0x12000
	s_cselect_b32 s60, 0, s60
	s_add_u32 s54, s54, s72
	s_addc_u32 s55, s55, 0
	s_add_u32 s56, s56, s73
	s_addc_u32 s57, s57, 0
	s_add_i32 s61, s61, 0x6000
	s_cmp_eq_u32 s61, 0x12000
	s_cselect_b32 s61, 0, s61
	s_nop 7
	s_nop 1
	s_lshl_b32 s26, s35, 11
	s_lshl_b32 s27, s36, 1
	s_add_i32 s26, s26, s27
	s_add_u32 s18, s52, s26
	s_addc_u32 s19, s53, 0
	v_cvt_pk_bf16_f32 v2, v2, v3
	v_cvt_pk_bf16_f32 v3, v4, v5
	v_cvt_pk_bf16_f32 v4, v6, v7
	v_cvt_pk_bf16_f32 v5, v8, v9
	v_cvt_pk_bf16_f32 v6, v10, v11
	v_cvt_pk_bf16_f32 v7, v12, v13
	v_cvt_pk_bf16_f32 v8, v14, v15
	v_cvt_pk_bf16_f32 v9, v16, v17
	global_store_dwordx4 v242, v[2:5], s[18:19]
	global_store_dwordx4 v242, v[6:9], s[18:19] offset:16
	s_add_u32 s18, s18, 0x8000
	s_addc_u32 s19, s19, 0
	v_cvt_pk_bf16_f32 v18, v18, v19
	v_cvt_pk_bf16_f32 v19, v20, v21
	v_cvt_pk_bf16_f32 v20, v22, v23
	v_cvt_pk_bf16_f32 v21, v24, v25
	v_cvt_pk_bf16_f32 v22, v26, v27
	v_cvt_pk_bf16_f32 v23, v28, v29
	v_cvt_pk_bf16_f32 v24, v30, v31
	v_cvt_pk_bf16_f32 v25, v32, v33
	global_store_dwordx4 v242, v[18:21], s[18:19]
	global_store_dwordx4 v242, v[22:25], s[18:19] offset:16
	s_add_u32 s18, s18, 0x8000
	s_addc_u32 s19, s19, 0
	v_cvt_pk_bf16_f32 v34, v34, v35
	v_cvt_pk_bf16_f32 v35, v36, v37
	v_cvt_pk_bf16_f32 v36, v38, v39
	v_cvt_pk_bf16_f32 v37, v40, v41
	v_cvt_pk_bf16_f32 v38, v42, v43
	v_cvt_pk_bf16_f32 v39, v44, v45
	v_cvt_pk_bf16_f32 v40, v46, v47
	v_cvt_pk_bf16_f32 v41, v48, v49
	global_store_dwordx4 v242, v[34:37], s[18:19]
	global_store_dwordx4 v242, v[38:41], s[18:19] offset:16
	s_add_u32 s18, s18, 0x8000
	s_addc_u32 s19, s19, 0
	v_cvt_pk_bf16_f32 v50, v50, v51
	v_cvt_pk_bf16_f32 v51, v52, v53
	v_cvt_pk_bf16_f32 v52, v54, v55
	v_cvt_pk_bf16_f32 v53, v56, v57
	v_cvt_pk_bf16_f32 v54, v58, v59
	v_cvt_pk_bf16_f32 v55, v60, v61
	v_cvt_pk_bf16_f32 v56, v62, v63
	v_cvt_pk_bf16_f32 v57, v64, v65
	global_store_dwordx4 v242, v[50:53], s[18:19]
	global_store_dwordx4 v242, v[54:57], s[18:19] offset:16
	s_add_u32 s18, s18, 0x8000
	s_addc_u32 s19, s19, 0
	v_cvt_pk_bf16_f32 v66, v66, v67
	v_cvt_pk_bf16_f32 v67, v68, v69
	v_cvt_pk_bf16_f32 v68, v70, v71
	v_cvt_pk_bf16_f32 v69, v72, v73
	v_cvt_pk_bf16_f32 v70, v74, v75
	v_cvt_pk_bf16_f32 v71, v76, v77
	v_cvt_pk_bf16_f32 v72, v78, v79
	v_cvt_pk_bf16_f32 v73, v80, v81
	global_store_dwordx4 v242, v[66:69], s[18:19]
	global_store_dwordx4 v242, v[70:73], s[18:19] offset:16
	s_add_u32 s18, s18, 0x8000
	s_addc_u32 s19, s19, 0
	v_cvt_pk_bf16_f32 v82, v82, v83
	v_cvt_pk_bf16_f32 v83, v84, v85
	v_cvt_pk_bf16_f32 v84, v86, v87
	v_cvt_pk_bf16_f32 v85, v88, v89
	v_cvt_pk_bf16_f32 v86, v90, v91
	v_cvt_pk_bf16_f32 v87, v92, v93
	v_cvt_pk_bf16_f32 v88, v94, v95
	v_cvt_pk_bf16_f32 v89, v96, v97
	global_store_dwordx4 v242, v[82:85], s[18:19]
	global_store_dwordx4 v242, v[86:89], s[18:19] offset:16
	s_add_u32 s18, s18, 0x8000
	s_addc_u32 s19, s19, 0
	v_cvt_pk_bf16_f32 v98, v98, v99
	v_cvt_pk_bf16_f32 v99, v100, v101
	v_cvt_pk_bf16_f32 v100, v102, v103
	v_cvt_pk_bf16_f32 v101, v104, v105
	v_cvt_pk_bf16_f32 v102, v106, v107
	v_cvt_pk_bf16_f32 v103, v108, v109
	v_cvt_pk_bf16_f32 v104, v110, v111
	v_cvt_pk_bf16_f32 v105, v112, v113
	global_store_dwordx4 v242, v[98:101], s[18:19]
	global_store_dwordx4 v242, v[102:105], s[18:19] offset:16
	s_add_u32 s18, s18, 0x8000
	s_addc_u32 s19, s19, 0
	v_cvt_pk_bf16_f32 v114, v114, v115
	v_cvt_pk_bf16_f32 v115, v116, v117
	v_cvt_pk_bf16_f32 v116, v118, v119
	v_cvt_pk_bf16_f32 v117, v120, v121
	v_cvt_pk_bf16_f32 v118, v122, v123
	v_cvt_pk_bf16_f32 v119, v124, v125
	v_cvt_pk_bf16_f32 v120, v126, v127
	v_cvt_pk_bf16_f32 v121, v128, v129
	global_store_dwordx4 v242, v[114:117], s[18:19]
	global_store_dwordx4 v242, v[118:121], s[18:19] offset:16
	s_mov_b32 s34, s38
	s_mov_b32 s35, s30
	s_mov_b32 s36, s31
	s_branch .Lgy_tile
.Lgy_tail_last:
	s_waitcnt vmcnt(6) lgkmcnt(0)
	s_barrier
	v_add_u32_e32 v240, s61, v238
	v_add_u32_e32 v241, s61, v239
	s_setprio 1
	s_add_i32 m0, s60, s62
	v_mfma_f32_16x16x32_bf16 v[2:5], v[162:165], v[130:133], v[2:5]
	global_load_lds_dwordx4 v226, s[54:55]
	v_mfma_f32_16x16x32_bf16 v[6:9], v[166:169], v[130:133], v[6:9]
	v_mfma_f32_16x16x32_bf16 v[10:13], v[170:173], v[130:133], v[10:13]
	v_mfma_f32_16x16x32_bf16 v[14:17], v[174:177], v[130:133], v[14:17]
	v_mfma_f32_16x16x32_bf16 v[18:21], v[162:165], v[134:137], v[18:21]
	v_mfma_f32_16x16x32_bf16 v[22:25], v[166:169], v[134:137], v[22:25]
	global_load_lds_dwordx4 v226, s[54:55] offset:1024
	v_mfma_f32_16x16x32_bf16 v[26:29], v[170:173], v[134:137], v[26:29]
	v_mfma_f32_16x16x32_bf16 v[30:33], v[174:177], v[134:137], v[30:33]
	v_mfma_f32_16x16x32_bf16 v[34:37], v[162:165], v[138:141], v[34:37]
	ds_read_b128 v[210:213], v241 offset:0
	v_mfma_f32_16x16x32_bf16 v[38:41], v[166:169], v[138:141], v[38:41]
	ds_read_b128 v[214:217], v241 offset:256
	v_mfma_f32_16x16x32_bf16 v[42:45], v[170:173], v[138:141], v[42:45]
	ds_read_b128 v[218:221], v241 offset:512
	global_load_lds_dwordx4 v226, s[54:55] offset:2048
	v_mfma_f32_16x16x32_bf16 v[46:49], v[174:177], v[138:141], v[46:49]
	ds_read_b128 v[222:225], v241 offset:768
	v_mfma_f32_16x16x32_bf16 v[50:53], v[162:165], v[142:145], v[50:53]
	ds_read_b128 v[178:181], v240 offset:0
	v_mfma_f32_16x16x32_bf16 v[54:57], v[166:169], v[142:145], v[54:57]
	ds_read_b128 v[182:185], v240 offset:1024
	v_mfma_f32_16x16x32_bf16 v[58:61], v[170:173], v[142:145], v[58:61]
	ds_read_b128 v[186:189], v240 offset:2048
	v_mfma_f32_16x16x32_bf16 v[62:65], v[174:177], v[142:145], v[62:65]
	ds_read_b128 v[190:193], v240 offset:3072
	global_load_lds_dwordx4 v226, s[54:55] offset:3072
	v_mfma_f32_16x16x32_bf16 v[66:69], v[162:165], v[146:149], v[66:69]
	ds_read_b128 v[194:197], v240 offset:4096
	v_mfma_f32_16x16x32_bf16 v[70:73], v[166:169], v[146:149], v[70:73]
	ds_read_b128 v[198:201], v240 offset:5120
	v_mfma_f32_16x16x32_bf16 v[74:77], v[170:173], v[146:149], v[74:77]
	ds_read_b128 v[202:205], v240 offset:6144
	v_mfma_f32_16x16x32_bf16 v[78:81], v[174:177], v[146:149], v[78:81]
	ds_read_b128 v[206:209], v240 offset:7168
	s_add_i32 m0, s60, s63
	v_mfma_f32_16x16x32_bf16 v[82:85], v[162:165], v[150:153], v[82:85]
	global_load_lds_dwordx4 v230, s[56:57]
	v_mfma_f32_16x16x32_bf16 v[86:89], v[166:169], v[150:153], v[86:89]
	v_mfma_f32_16x16x32_bf16 v[90:93], v[170:173], v[150:153], v[90:93]
	v_mfma_f32_16x16x32_bf16 v[94:97], v[174:177], v[150:153], v[94:97]
	v_mfma_f32_16x16x32_bf16 v[98:101], v[162:165], v[154:157], v[98:101]
	v_mfma_f32_16x16x32_bf16 v[102:105], v[166:169], v[154:157], v[102:105]
	global_load_lds_dwordx4 v231, s[56:57] offset:1024
	v_mfma_f32_16x16x32_bf16 v[106:109], v[170:173], v[154:157], v[106:109]
	v_mfma_f32_16x16x32_bf16 v[110:113], v[174:177], v[154:157], v[110:113]
	v_mfma_f32_16x16x32_bf16 v[114:117], v[162:165], v[158:161], v[114:117]
	v_mfma_f32_16x16x32_bf16 v[118:121], v[166:169], v[158:161], v[118:121]
	v_mfma_f32_16x16x32_bf16 v[122:125], v[170:173], v[158:161], v[122:125]
	v_mfma_f32_16x16x32_bf16 v[126:129], v[174:177], v[158:161], v[126:129]
	s_setprio 0
	s_add_i32 s60, s60, 0x6000
	s_cmp_eq_u32 s60, 0x12000
	s_cselect_b32 s60, 0, s60
	s_add_u32 s54, s54, s72
	s_addc_u32 s55, s55, 0
	s_add_u32 s56, s56, s73
	s_addc_u32 s57, s57, 0
	s_add_i32 s61, s61, 0x6000
	s_cmp_eq_u32 s61, 0x12000
	s_cselect_b32 s61, 0, s61
	s_waitcnt vmcnt(6) lgkmcnt(0)
	s_barrier
	v_add_u32_e32 v240, s61, v238
	v_add_u32_e32 v241, s61, v239
	s_setprio 1
	v_mfma_f32_16x16x32_bf16 v[2:5], v[210:213], v[178:181], v[2:5]
	v_mfma_f32_16x16x32_bf16 v[6:9], v[214:217], v[178:181], v[6:9]
	v_mfma_f32_16x16x32_bf16 v[10:13], v[218:221], v[178:181], v[10:13]
	v_mfma_f32_16x16x32_bf16 v[14:17], v[222:225], v[178:181], v[14:17]
	v_mfma_f32_16x16x32_bf16 v[18:21], v[210:213], v[182:185], v[18:21]
	v_mfma_f32_16x16x32_bf16 v[22:25], v[214:217], v[182:185], v[22:25]
	v_mfma_f32_16x16x32_bf16 v[26:29], v[218:221], v[182:185], v[26:29]
	v_mfma_f32_16x16x32_bf16 v[30:33], v[222:225], v[182:185], v[30:33]
	v_mfma_f32_16x16x32_bf16 v[34:37], v[210:213], v[186:189], v[34:37]
	ds_read_b128 v[162:165], v241 offset:0
	v_mfma_f32_16x16x32_bf16 v[38:41], v[214:217], v[186:189], v[38:41]
	ds_read_b128 v[166:169], v241 offset:256
	v_mfma_f32_16x16x32_bf16 v[42:45], v[218:221], v[186:189], v[42:45]
	ds_read_b128 v[170:173], v241 offset:512
	v_mfma_f32_16x16x32_bf16 v[46:49], v[222:225], v[186:189], v[46:49]
	ds_read_b128 v[174:177], v241 offset:768
	v_mfma_f32_16x16x32_bf16 v[50:53], v[210:213], v[190:193], v[50:53]
	ds_read_b128 v[130:133], v240 offset:0
	v_mfma_f32_16x16x32_bf16 v[54:57], v[214:217], v[190:193], v[54:57]
	ds_read_b128 v[134:137], v240 offset:1024
	v_mfma_f32_16x16x32_bf16 v[58:61], v[218:221], v[190:193], v[58:61]
	ds_read_b128 v[138:141], v240 offset:2048
	v_mfma_f32_16x16x32_bf16 v[62:65], v[222:225], v[190:193], v[62:65]
	ds_read_b128 v[142:145], v240 offset:3072
	v_mfma_f32_16x16x32_bf16 v[66:69], v[210:213], v[194:197], v[66:69]
	ds_read_b128 v[146:149], v240 offset:4096
	v_mfma_f32_16x16x32_bf16 v[70:73], v[214:217], v[194:197], v[70:73]
	ds_read_b128 v[150:153], v240 offset:5120
	v_mfma_f32_16x16x32_bf16 v[74:77], v[218:221], v[194:197], v[74:77]
	ds_read_b128 v[154:157], v240 offset:6144
	v_mfma_f32_16x16x32_bf16 v[78:81], v[222:225], v[194:197], v[78:81]
	ds_read_b128 v[158:161], v240 offset:7168
	v_mfma_f32_16x16x32_bf16 v[82:85], v[210:213], v[198:201], v[82:85]
	v_mfma_f32_16x16x32_bf16 v[86:89], v[214:217], v[198:201], v[86:89]
	v_mfma_f32_16x16x32_bf16 v[90:93], v[218:221], v[198:201], v[90:93]
	v_mfma_f32_16x16x32_bf16 v[94:97], v[222:225], v[198:201], v[94:97]
	v_mfma_f32_16x16x32_bf16 v[98:101], v[210:213], v[202:205], v[98:101]
	v_mfma_f32_16x16x32_bf16 v[102:105], v[214:217], v[202:205], v[102:105]
	v_mfma_f32_16x16x32_bf16 v[106:109], v[218:221], v[202:205], v[106:109]
	v_mfma_f32_16x16x32_bf16 v[110:113], v[222:225], v[202:205], v[110:113]
	v_mfma_f32_16x16x32_bf16 v[114:117], v[210:213], v[206:209], v[114:117]
	v_mfma_f32_16x16x32_bf16 v[118:121], v[214:217], v[206:209], v[118:121]
	v_mfma_f32_16x16x32_bf16 v[122:125], v[218:221], v[206:209], v[122:125]
	v_mfma_f32_16x16x32_bf16 v[126:129], v[222:225], v[206:209], v[126:129]
	s_setprio 0
	s_add_i32 s61, s61, 0x6000
	s_cmp_eq_u32 s61, 0x12000
	s_cselect_b32 s61, 0, s61
	s_waitcnt vmcnt(0) lgkmcnt(0)
	s_barrier
	v_add_u32_e32 v240, s61, v238
	v_add_u32_e32 v241, s61, v239
	s_setprio 1
	v_mfma_f32_16x16x32_bf16 v[2:5], v[162:165], v[130:133], v[2:5]
	v_mfma_f32_16x16x32_bf16 v[6:9], v[166:169], v[130:133], v[6:9]
	v_mfma_f32_16x16x32_bf16 v[10:13], v[170:173], v[130:133], v[10:13]
	v_mfma_f32_16x16x32_bf16 v[14:17], v[174:177], v[130:133], v[14:17]
	v_mfma_f32_16x16x32_bf16 v[18:21], v[162:165], v[134:137], v[18:21]
	v_mfma_f32_16x16x32_bf16 v[22:25], v[166:169], v[134:137], v[22:25]
	v_mfma_f32_16x16x32_bf16 v[26:29], v[170:173], v[134:137], v[26:29]
	v_mfma_f32_16x16x32_bf16 v[30:33], v[174:177], v[134:137], v[30:33]
	v_mfma_f32_16x16x32_bf16 v[34:37], v[162:165], v[138:141], v[34:37]
	ds_read_b128 v[210:213], v241 offset:0
	v_mfma_f32_16x16x32_bf16 v[38:41], v[166:169], v[138:141], v[38:41]
	ds_read_b128 v[214:217], v241 offset:256
	v_mfma_f32_16x16x32_bf16 v[42:45], v[170:173], v[138:141], v[42:45]
	ds_read_b128 v[218:221], v241 offset:512
	v_mfma_f32_16x16x32_bf16 v[46:49], v[174:177], v[138:141], v[46:49]
	ds_read_b128 v[222:225], v241 offset:768
	v_mfma_f32_16x16x32_bf16 v[50:53], v[162:165], v[142:145], v[50:53]
	ds_read_b128 v[178:181], v240 offset:0
	v_mfma_f32_16x16x32_bf16 v[54:57], v[166:169], v[142:145], v[54:57]
	ds_read_b128 v[182:185], v240 offset:1024
	v_mfma_f32_16x16x32_bf16 v[58:61], v[170:173], v[142:145], v[58:61]
	ds_read_b128 v[186:189], v240 offset:2048
	v_mfma_f32_16x16x32_bf16 v[62:65], v[174:177], v[142:145], v[62:65]
	ds_read_b128 v[190:193], v240 offset:3072
	v_mfma_f32_16x16x32_bf16 v[66:69], v[162:165], v[146:149], v[66:69]
	ds_read_b128 v[194:197], v240 offset:4096
	v_mfma_f32_16x16x32_bf16 v[70:73], v[166:169], v[146:149], v[70:73]
	ds_read_b128 v[198:201], v240 offset:5120
	v_mfma_f32_16x16x32_bf16 v[74:77], v[170:173], v[146:149], v[74:77]
	ds_read_b128 v[202:205], v240 offset:6144
	v_mfma_f32_16x16x32_bf16 v[78:81], v[174:177], v[146:149], v[78:81]
	ds_read_b128 v[206:209], v240 offset:7168
	v_mfma_f32_16x16x32_bf16 v[82:85], v[162:165], v[150:153], v[82:85]
	v_mfma_f32_16x16x32_bf16 v[86:89], v[166:169], v[150:153], v[86:89]
	v_mfma_f32_16x16x32_bf16 v[90:93], v[170:173], v[150:153], v[90:93]
	v_mfma_f32_16x16x32_bf16 v[94:97], v[174:177], v[150:153], v[94:97]
	v_mfma_f32_16x16x32_bf16 v[98:101], v[162:165], v[154:157], v[98:101]
	v_mfma_f32_16x16x32_bf16 v[102:105], v[166:169], v[154:157], v[102:105]
	v_mfma_f32_16x16x32_bf16 v[106:109], v[170:173], v[154:157], v[106:109]
	v_mfma_f32_16x16x32_bf16 v[110:113], v[174:177], v[154:157], v[110:113]
	v_mfma_f32_16x16x32_bf16 v[114:117], v[162:165], v[158:161], v[114:117]
	v_mfma_f32_16x16x32_bf16 v[118:121], v[166:169], v[158:161], v[118:121]
	v_mfma_f32_16x16x32_bf16 v[122:125], v[170:173], v[158:161], v[122:125]
	v_mfma_f32_16x16x32_bf16 v[126:129], v[174:177], v[158:161], v[126:129]
	s_setprio 0
	s_add_i32 s61, s61, 0x6000
	s_cmp_eq_u32 s61, 0x12000
	s_cselect_b32 s61, 0, s61
	s_waitcnt lgkmcnt(0)
	s_barrier
	s_setprio 1
	v_mfma_f32_16x16x32_bf16 v[2:5], v[210:213], v[178:181], v[2:5]
	v_mfma_f32_16x16x32_bf16 v[6:9], v[214:217], v[178:181], v[6:9]
	v_mfma_f32_16x16x32_bf16 v[10:13], v[218:221], v[178:181], v[10:13]
	v_mfma_f32_16x16x32_bf16 v[14:17], v[222:225], v[178:181], v[14:17]
	v_mfma_f32_16x16x32_bf16 v[18:21], v[210:213], v[182:185], v[18:21]
	v_mfma_f32_16x16x32_bf16 v[22:25], v[214:217], v[182:185], v[22:25]
	v_mfma_f32_16x16x32_bf16 v[26:29], v[218:221], v[182:185], v[26:29]
	v_mfma_f32_16x16x32_bf16 v[30:33], v[222:225], v[182:185], v[30:33]
	v_mfma_f32_16x16x32_bf16 v[34:37], v[210:213], v[186:189], v[34:37]
	v_mfma_f32_16x16x32_bf16 v[38:41], v[214:217], v[186:189], v[38:41]
	v_mfma_f32_16x16x32_bf16 v[42:45], v[218:221], v[186:189], v[42:45]
	v_mfma_f32_16x16x32_bf16 v[46:49], v[222:225], v[186:189], v[46:49]
	v_mfma_f32_16x16x32_bf16 v[50:53], v[210:213], v[190:193], v[50:53]
	v_mfma_f32_16x16x32_bf16 v[54:57], v[214:217], v[190:193], v[54:57]
	v_mfma_f32_16x16x32_bf16 v[58:61], v[218:221], v[190:193], v[58:61]
	v_mfma_f32_16x16x32_bf16 v[62:65], v[222:225], v[190:193], v[62:65]
	v_mfma_f32_16x16x32_bf16 v[66:69], v[210:213], v[194:197], v[66:69]
	v_mfma_f32_16x16x32_bf16 v[70:73], v[214:217], v[194:197], v[70:73]
	v_mfma_f32_16x16x32_bf16 v[74:77], v[218:221], v[194:197], v[74:77]
	v_mfma_f32_16x16x32_bf16 v[78:81], v[222:225], v[194:197], v[78:81]
	v_mfma_f32_16x16x32_bf16 v[82:85], v[210:213], v[198:201], v[82:85]
	v_mfma_f32_16x16x32_bf16 v[86:89], v[214:217], v[198:201], v[86:89]
	v_mfma_f32_16x16x32_bf16 v[90:93], v[218:221], v[198:201], v[90:93]
	v_mfma_f32_16x16x32_bf16 v[94:97], v[222:225], v[198:201], v[94:97]
	v_mfma_f32_16x16x32_bf16 v[98:101], v[210:213], v[202:205], v[98:101]
	v_mfma_f32_16x16x32_bf16 v[102:105], v[214:217], v[202:205], v[102:105]
	v_mfma_f32_16x16x32_bf16 v[106:109], v[218:221], v[202:205], v[106:109]
	v_mfma_f32_16x16x32_bf16 v[110:113], v[222:225], v[202:205], v[110:113]
	v_mfma_f32_16x16x32_bf16 v[114:117], v[210:213], v[206:209], v[114:117]
	v_mfma_f32_16x16x32_bf16 v[118:121], v[214:217], v[206:209], v[118:121]
	v_mfma_f32_16x16x32_bf16 v[122:125], v[218:221], v[206:209], v[122:125]
	v_mfma_f32_16x16x32_bf16 v[126:129], v[222:225], v[206:209], v[126:129]
	s_setprio 0
	s_nop 7
	s_nop 1
	s_lshl_b32 s26, s35, 11
	s_lshl_b32 s27, s36, 1
	s_add_i32 s26, s26, s27
	s_add_u32 s18, s52, s26
	s_addc_u32 s19, s53, 0
	v_cvt_pk_bf16_f32 v2, v2, v3
	v_cvt_pk_bf16_f32 v3, v4, v5
	v_cvt_pk_bf16_f32 v4, v6, v7
	v_cvt_pk_bf16_f32 v5, v8, v9
	v_cvt_pk_bf16_f32 v6, v10, v11
	v_cvt_pk_bf16_f32 v7, v12, v13
	v_cvt_pk_bf16_f32 v8, v14, v15
	v_cvt_pk_bf16_f32 v9, v16, v17
	global_store_dwordx4 v242, v[2:5], s[18:19]
	global_store_dwordx4 v242, v[6:9], s[18:19] offset:16
	s_add_u32 s18, s18, 0x8000
	s_addc_u32 s19, s19, 0
	v_cvt_pk_bf16_f32 v18, v18, v19
	v_cvt_pk_bf16_f32 v19, v20, v21
	v_cvt_pk_bf16_f32 v20, v22, v23
	v_cvt_pk_bf16_f32 v21, v24, v25
	v_cvt_pk_bf16_f32 v22, v26, v27
	v_cvt_pk_bf16_f32 v23, v28, v29
	v_cvt_pk_bf16_f32 v24, v30, v31
	v_cvt_pk_bf16_f32 v25, v32, v33
	global_store_dwordx4 v242, v[18:21], s[18:19]
	global_store_dwordx4 v242, v[22:25], s[18:19] offset:16
	s_add_u32 s18, s18, 0x8000
	s_addc_u32 s19, s19, 0
	v_cvt_pk_bf16_f32 v34, v34, v35
	v_cvt_pk_bf16_f32 v35, v36, v37
	v_cvt_pk_bf16_f32 v36, v38, v39
	v_cvt_pk_bf16_f32 v37, v40, v41
	v_cvt_pk_bf16_f32 v38, v42, v43
	v_cvt_pk_bf16_f32 v39, v44, v45
	v_cvt_pk_bf16_f32 v40, v46, v47
	v_cvt_pk_bf16_f32 v41, v48, v49
	global_store_dwordx4 v242, v[34:37], s[18:19]
	global_store_dwordx4 v242, v[38:41], s[18:19] offset:16
	s_add_u32 s18, s18, 0x8000
	s_addc_u32 s19, s19, 0
	v_cvt_pk_bf16_f32 v50, v50, v51
	v_cvt_pk_bf16_f32 v51, v52, v53
	v_cvt_pk_bf16_f32 v52, v54, v55
	v_cvt_pk_bf16_f32 v53, v56, v57
	v_cvt_pk_bf16_f32 v54, v58, v59
	v_cvt_pk_bf16_f32 v55, v60, v61
	v_cvt_pk_bf16_f32 v56, v62, v63
	v_cvt_pk_bf16_f32 v57, v64, v65
	global_store_dwordx4 v242, v[50:53], s[18:19]
	global_store_dwordx4 v242, v[54:57], s[18:19] offset:16
	s_add_u32 s18, s18, 0x8000
	s_addc_u32 s19, s19, 0
	v_cvt_pk_bf16_f32 v66, v66, v67
	v_cvt_pk_bf16_f32 v67, v68, v69
	v_cvt_pk_bf16_f32 v68, v70, v71
	v_cvt_pk_bf16_f32 v69, v72, v73
	v_cvt_pk_bf16_f32 v70, v74, v75
	v_cvt_pk_bf16_f32 v71, v76, v77
	v_cvt_pk_bf16_f32 v72, v78, v79
	v_cvt_pk_bf16_f32 v73, v80, v81
	global_store_dwordx4 v242, v[66:69], s[18:19]
	global_store_dwordx4 v242, v[70:73], s[18:19] offset:16
	s_add_u32 s18, s18, 0x8000
	s_addc_u32 s19, s19, 0
	v_cvt_pk_bf16_f32 v82, v82, v83
	v_cvt_pk_bf16_f32 v83, v84, v85
	v_cvt_pk_bf16_f32 v84, v86, v87
	v_cvt_pk_bf16_f32 v85, v88, v89
	v_cvt_pk_bf16_f32 v86, v90, v91
	v_cvt_pk_bf16_f32 v87, v92, v93
	v_cvt_pk_bf16_f32 v88, v94, v95
	v_cvt_pk_bf16_f32 v89, v96, v97
	global_store_dwordx4 v242, v[82:85], s[18:19]
	global_store_dwordx4 v242, v[86:89], s[18:19] offset:16
	s_add_u32 s18, s18, 0x8000
	s_addc_u32 s19, s19, 0
	v_cvt_pk_bf16_f32 v98, v98, v99
	v_cvt_pk_bf16_f32 v99, v100, v101
	v_cvt_pk_bf16_f32 v100, v102, v103
	v_cvt_pk_bf16_f32 v101, v104, v105
	v_cvt_pk_bf16_f32 v102, v106, v107
	v_cvt_pk_bf16_f32 v103, v108, v109
	v_cvt_pk_bf16_f32 v104, v110, v111
	v_cvt_pk_bf16_f32 v105, v112, v113
	global_store_dwordx4 v242, v[98:101], s[18:19]
	global_store_dwordx4 v242, v[102:105], s[18:19] offset:16
	s_add_u32 s18, s18, 0x8000
	s_addc_u32 s19, s19, 0
	v_cvt_pk_bf16_f32 v114, v114, v115
	v_cvt_pk_bf16_f32 v115, v116, v117
	v_cvt_pk_bf16_f32 v116, v118, v119
	v_cvt_pk_bf16_f32 v117, v120, v121
	v_cvt_pk_bf16_f32 v118, v122, v123
	v_cvt_pk_bf16_f32 v119, v124, v125
	v_cvt_pk_bf16_f32 v120, v126, v127
	v_cvt_pk_bf16_f32 v121, v128, v129
	global_store_dwordx4 v242, v[114:117], s[18:19]
	global_store_dwordx4 v242, v[118:121], s[18:19] offset:16

.Lup_nn_a:
	s_waitcnt vmcnt(6) lgkmcnt(0)
	s_barrier
	v_add_u32_e32 v240, s61, v238
	v_add_u32_e32 v241, s61, v239
	s_setprio 1
	s_add_i32 m0, s60, s62
	v_mfma_f32_16x16x32_bf16 v[2:5], v[162:165], v[130:133], 0
	global_load_lds_dwordx4 v226, s[54:55]
	v_mfma_f32_16x16x32_bf16 v[6:9], v[166:169], v[130:133], 0
	v_mfma_f32_16x16x32_bf16 v[10:13], v[170:173], v[130:133], 0
	v_mfma_f32_16x16x32_bf16 v[14:17], v[174:177], v[130:133], 0
	v_mfma_f32_16x16x32_bf16 v[18:21], v[162:165], v[134:137], 0
	v_mfma_f32_16x16x32_bf16 v[22:25], v[166:169], v[134:137], 0
	global_load_lds_dwordx4 v226, s[54:55] offset:1024
	v_mfma_f32_16x16x32_bf16 v[26:29], v[170:173], v[134:137], 0
	v_mfma_f32_16x16x32_bf16 v[30:33], v[174:177], v[134:137], 0
	v_mfma_f32_16x16x32_bf16 v[34:37], v[162:165], v[138:141], 0
	ds_read_b128 v[210:213], v241 offset:0
	v_mfma_f32_16x16x32_bf16 v[38:41], v[166:169], v[138:141], 0
	ds_read_b128 v[214:217], v241 offset:256
	v_mfma_f32_16x16x32_bf16 v[42:45], v[170:173], v[138:141], 0
	ds_read_b128 v[218:221], v241 offset:2048
	global_load_lds_dwordx4 v226, s[54:55] offset:2048
	v_mfma_f32_16x16x32_bf16 v[46:49], v[174:177], v[138:141], 0
	ds_read_b128 v[222:225], v241 offset:2304
	v_mfma_f32_16x16x32_bf16 v[50:53], v[162:165], v[142:145], 0
	ds_read_b128 v[178:181], v240 offset:0
	v_mfma_f32_16x16x32_bf16 v[54:57], v[166:169], v[142:145], 0
	ds_read_b128 v[182:185], v240 offset:1024
	v_mfma_f32_16x16x32_bf16 v[58:61], v[170:173], v[142:145], 0
	ds_read_b128 v[186:189], v240 offset:2048
	v_mfma_f32_16x16x32_bf16 v[62:65], v[174:177], v[142:145], 0
	ds_read_b128 v[190:193], v240 offset:3072
	global_load_lds_dwordx4 v226, s[54:55] offset:3072
	v_mfma_f32_16x16x32_bf16 v[66:69], v[162:165], v[146:149], 0
	ds_read_b128 v[194:197], v240 offset:4096
	v_mfma_f32_16x16x32_bf16 v[70:73], v[166:169], v[146:149], 0
	ds_read_b128 v[198:201], v240 offset:5120
	v_mfma_f32_16x16x32_bf16 v[74:77], v[170:173], v[146:149], 0
	ds_read_b128 v[202:205], v240 offset:6144
	v_mfma_f32_16x16x32_bf16 v[78:81], v[174:177], v[146:149], 0
	ds_read_b128 v[206:209], v240 offset:7168
	s_add_i32 m0, s60, s63
	v_mfma_f32_16x16x32_bf16 v[82:85], v[162:165], v[150:153], 0
	global_load_lds_dwordx4 v230, s[56:57]
	v_mfma_f32_16x16x32_bf16 v[86:89], v[166:169], v[150:153], 0
	v_mfma_f32_16x16x32_bf16 v[90:93], v[170:173], v[150:153], 0
	v_mfma_f32_16x16x32_bf16 v[94:97], v[174:177], v[150:153], 0
	v_mfma_f32_16x16x32_bf16 v[98:101], v[162:165], v[154:157], 0
	v_mfma_f32_16x16x32_bf16 v[102:105], v[166:169], v[154:157], 0
	global_load_lds_dwordx4 v231, s[56:57] offset:1024
	v_mfma_f32_16x16x32_bf16 v[106:109], v[170:173], v[154:157], 0
	v_mfma_f32_16x16x32_bf16 v[110:113], v[174:177], v[154:157], 0
	v_mfma_f32_16x16x32_bf16 v[114:117], v[162:165], v[158:161], 0
	v_mfma_f32_16x16x32_bf16 v[118:121], v[166:169], v[158:161], 0
	v_mfma_f32_16x16x32_bf16 v[122:125], v[170:173], v[158:161], 0
	v_mfma_f32_16x16x32_bf16 v[126:129], v[174:177], v[158:161], 0
	s_setprio 0
	s_add_i32 s60, s60, 0x6000
	s_cmp_eq_u32 s60, 0x12000
	s_cselect_b32 s60, 0, s60
	s_add_u32 s54, s54, s72
	s_addc_u32 s55, s55, 0
	s_add_u32 s56, s56, s73
	s_addc_u32 s57, s57, 0
	s_add_i32 s61, s61, 0x6000
	s_cmp_eq_u32 s61, 0x12000
	s_cselect_b32 s61, 0, s61
	v_mbcnt_lo_u32_b32 v0, -1, 0
	v_lshlrev_b32_e32 v0, 4, v0
	s_lshl_b32 s26, s36, 1
	v_add_u32_e32 v0, s26, v0
	s_lshl_b32 s26, s41, 8
	s_add_i32 m0, s26, 0x13010
	s_mov_b64 exec, 0xffff
	global_load_lds_dwordx4 v0, s[82:83]
	s_mov_b64 exec, -1
	s_waitcnt vmcnt(6) lgkmcnt(0)
	s_barrier
	v_add_u32_e32 v240, s61, v238
	v_add_u32_e32 v241, s61, v239
	s_setprio 1
	s_add_i32 m0, s60, s62
	v_mfma_f32_16x16x32_bf16 v[2:5], v[210:213], v[178:181], v[2:5]
	global_load_lds_dwordx4 v226, s[54:55]
	v_mfma_f32_16x16x32_bf16 v[6:9], v[214:217], v[178:181], v[6:9]
	v_mfma_f32_16x16x32_bf16 v[10:13], v[218:221], v[178:181], v[10:13]
	v_mfma_f32_16x16x32_bf16 v[14:17], v[222:225], v[178:181], v[14:17]
	v_mfma_f32_16x16x32_bf16 v[18:21], v[210:213], v[182:185], v[18:21]
	v_mfma_f32_16x16x32_bf16 v[22:25], v[214:217], v[182:185], v[22:25]
	global_load_lds_dwordx4 v226, s[54:55] offset:1024
	v_mfma_f32_16x16x32_bf16 v[26:29], v[218:221], v[182:185], v[26:29]
	v_mfma_f32_16x16x32_bf16 v[30:33], v[222:225], v[182:185], v[30:33]
	v_mfma_f32_16x16x32_bf16 v[34:37], v[210:213], v[186:189], v[34:37]
	ds_read_b128 v[162:165], v241 offset:0
	v_mfma_f32_16x16x32_bf16 v[38:41], v[214:217], v[186:189], v[38:41]
	ds_read_b128 v[166:169], v241 offset:256
	v_mfma_f32_16x16x32_bf16 v[42:45], v[218:221], v[186:189], v[42:45]
	ds_read_b128 v[170:173], v241 offset:2048
	global_load_lds_dwordx4 v226, s[54:55] offset:2048
	v_mfma_f32_16x16x32_bf16 v[46:49], v[222:225], v[186:189], v[46:49]
	ds_read_b128 v[174:177], v241 offset:2304
	v_mfma_f32_16x16x32_bf16 v[50:53], v[210:213], v[190:193], v[50:53]
	ds_read_b128 v[130:133], v240 offset:0
	v_mfma_f32_16x16x32_bf16 v[54:57], v[214:217], v[190:193], v[54:57]
	ds_read_b128 v[134:137], v240 offset:1024
	v_mfma_f32_16x16x32_bf16 v[58:61], v[218:221], v[190:193], v[58:61]
	ds_read_b128 v[138:141], v240 offset:2048
	v_mfma_f32_16x16x32_bf16 v[62:65], v[222:225], v[190:193], v[62:65]
	ds_read_b128 v[142:145], v240 offset:3072
	global_load_lds_dwordx4 v226, s[54:55] offset:3072
	v_mfma_f32_16x16x32_bf16 v[66:69], v[210:213], v[194:197], v[66:69]
	ds_read_b128 v[146:149], v240 offset:4096
	v_mfma_f32_16x16x32_bf16 v[70:73], v[214:217], v[194:197], v[70:73]
	ds_read_b128 v[150:153], v240 offset:5120
	v_mfma_f32_16x16x32_bf16 v[74:77], v[218:221], v[194:197], v[74:77]
	ds_read_b128 v[154:157], v240 offset:6144
	v_mfma_f32_16x16x32_bf16 v[78:81], v[222:225], v[194:197], v[78:81]
	ds_read_b128 v[158:161], v240 offset:7168
	s_add_i32 m0, s60, s63
	v_mfma_f32_16x16x32_bf16 v[82:85], v[210:213], v[198:201], v[82:85]
	global_load_lds_dwordx4 v230, s[56:57]
	v_mfma_f32_16x16x32_bf16 v[86:89], v[214:217], v[198:201], v[86:89]
	v_mfma_f32_16x16x32_bf16 v[90:93], v[218:221], v[198:201], v[90:93]
	v_mfma_f32_16x16x32_bf16 v[94:97], v[222:225], v[198:201], v[94:97]
	v_mfma_f32_16x16x32_bf16 v[98:101], v[210:213], v[202:205], v[98:101]
	v_mfma_f32_16x16x32_bf16 v[102:105], v[214:217], v[202:205], v[102:105]
	global_load_lds_dwordx4 v231, s[56:57] offset:1024
	v_mfma_f32_16x16x32_bf16 v[106:109], v[218:221], v[202:205], v[106:109]
	v_mfma_f32_16x16x32_bf16 v[110:113], v[222:225], v[202:205], v[110:113]
	v_mfma_f32_16x16x32_bf16 v[114:117], v[210:213], v[206:209], v[114:117]
	v_mfma_f32_16x16x32_bf16 v[118:121], v[214:217], v[206:209], v[118:121]
	v_mfma_f32_16x16x32_bf16 v[122:125], v[218:221], v[206:209], v[122:125]
	v_mfma_f32_16x16x32_bf16 v[126:129], v[222:225], v[206:209], v[126:129]
	s_setprio 0
	s_add_i32 s60, s60, 0x6000
	s_cmp_eq_u32 s60, 0x12000
	s_cselect_b32 s60, 0, s60
	s_add_u32 s54, s54, s72
	s_addc_u32 s55, s55, 0
	s_add_u32 s56, s56, s73
	s_addc_u32 s57, s57, 0
	s_add_i32 s61, s61, 0x6000
	s_cmp_eq_u32 s61, 0x12000
	s_cselect_b32 s61, 0, s61
	s_branch .Lup_main

.Lup_nn_b:
	s_waitcnt vmcnt(14) lgkmcnt(0)
	s_barrier
	v_add_u32_e32 v240, s61, v238
	v_add_u32_e32 v241, s61, v239
	s_setprio 1
	s_add_i32 m0, s60, s62
	v_mfma_f32_16x16x32_bf16 v[2:5], v[162:165], v[130:133], 0
	global_load_lds_dwordx4 v226, s[54:55]
	v_mfma_f32_16x16x32_bf16 v[6:9], v[166:169], v[130:133], 0
	v_mfma_f32_16x16x32_bf16 v[10:13], v[170:173], v[130:133], 0
	v_mfma_f32_16x16x32_bf16 v[14:17], v[174:177], v[130:133], 0
	v_mfma_f32_16x16x32_bf16 v[18:21], v[162:165], v[134:137], 0
	v_mfma_f32_16x16x32_bf16 v[22:25], v[166:169], v[134:137], 0
	global_load_lds_dwordx4 v226, s[54:55] offset:1024
	v_mfma_f32_16x16x32_bf16 v[26:29], v[170:173], v[134:137], 0
	v_mfma_f32_16x16x32_bf16 v[30:33], v[174:177], v[134:137], 0
	v_mfma_f32_16x16x32_bf16 v[34:37], v[162:165], v[138:141], 0
	ds_read_b128 v[210:213], v241 offset:0
	v_mfma_f32_16x16x32_bf16 v[38:41], v[166:169], v[138:141], 0
	ds_read_b128 v[214:217], v241 offset:256
	v_mfma_f32_16x16x32_bf16 v[42:45], v[170:173], v[138:141], 0
	ds_read_b128 v[218:221], v241 offset:2048
	global_load_lds_dwordx4 v226, s[54:55] offset:2048
	v_mfma_f32_16x16x32_bf16 v[46:49], v[174:177], v[138:141], 0
	ds_read_b128 v[222:225], v241 offset:2304
	v_mfma_f32_16x16x32_bf16 v[50:53], v[162:165], v[142:145], 0
	ds_read_b128 v[178:181], v240 offset:0
	v_mfma_f32_16x16x32_bf16 v[54:57], v[166:169], v[142:145], 0
	ds_read_b128 v[182:185], v240 offset:1024
	v_mfma_f32_16x16x32_bf16 v[58:61], v[170:173], v[142:145], 0
	ds_read_b128 v[186:189], v240 offset:2048
	v_mfma_f32_16x16x32_bf16 v[62:65], v[174:177], v[142:145], 0
	ds_read_b128 v[190:193], v240 offset:3072
	global_load_lds_dwordx4 v226, s[54:55] offset:3072
	v_mfma_f32_16x16x32_bf16 v[66:69], v[162:165], v[146:149], 0
	ds_read_b128 v[194:197], v240 offset:4096
	v_mfma_f32_16x16x32_bf16 v[70:73], v[166:169], v[146:149], 0
	ds_read_b128 v[198:201], v240 offset:5120
	v_mfma_f32_16x16x32_bf16 v[74:77], v[170:173], v[146:149], 0
	ds_read_b128 v[202:205], v240 offset:6144
	v_mfma_f32_16x16x32_bf16 v[78:81], v[174:177], v[146:149], 0
	ds_read_b128 v[206:209], v240 offset:7168
	s_add_i32 m0, s60, s63
	v_mfma_f32_16x16x32_bf16 v[82:85], v[162:165], v[150:153], 0
	global_load_lds_dwordx4 v230, s[56:57]
	v_mfma_f32_16x16x32_bf16 v[86:89], v[166:169], v[150:153], 0
	v_mfma_f32_16x16x32_bf16 v[90:93], v[170:173], v[150:153], 0
	v_mfma_f32_16x16x32_bf16 v[94:97], v[174:177], v[150:153], 0
	v_mfma_f32_16x16x32_bf16 v[98:101], v[162:165], v[154:157], 0
	v_mfma_f32_16x16x32_bf16 v[102:105], v[166:169], v[154:157], 0
	global_load_lds_dwordx4 v231, s[56:57] offset:1024
	v_mfma_f32_16x16x32_bf16 v[106:109], v[170:173], v[154:157], 0
	v_mfma_f32_16x16x32_bf16 v[110:113], v[174:177], v[154:157], 0
	v_mfma_f32_16x16x32_bf16 v[114:117], v[162:165], v[158:161], 0
	v_mfma_f32_16x16x32_bf16 v[118:121], v[166:169], v[158:161], 0
	v_mfma_f32_16x16x32_bf16 v[122:125], v[170:173], v[158:161], 0
	v_mfma_f32_16x16x32_bf16 v[126:129], v[174:177], v[158:161], 0
	s_setprio 0
	s_add_i32 s60, s60, 0x6000
	s_cmp_eq_u32 s60, 0x12000
	s_cselect_b32 s60, 0, s60
	s_add_u32 s54, s54, s72
	s_addc_u32 s55, s55, 0
	s_add_u32 s56, s56, s73
	s_addc_u32 s57, s57, 0
	s_add_i32 s61, s61, 0x6000
	s_cmp_eq_u32 s61, 0x12000
	s_cselect_b32 s61, 0, s61
	v_mbcnt_lo_u32_b32 v0, -1, 0
	v_lshlrev_b32_e32 v0, 4, v0
	s_lshl_b32 s26, s36, 1
	v_add_u32_e32 v0, s26, v0
	s_lshl_b32 s26, s41, 8
	s_add_i32 m0, s26, 0x13010
	s_mov_b64 exec, 0xffff
	global_load_lds_dwordx4 v0, s[82:83]
	s_mov_b64 exec, -1
	s_waitcnt vmcnt(14) lgkmcnt(0)
	s_barrier
	v_add_u32_e32 v240, s61, v238
	v_add_u32_e32 v241, s61, v239
	s_setprio 1
	s_add_i32 m0, s60, s62
	v_mfma_f32_16x16x32_bf16 v[2:5], v[210:213], v[178:181], v[2:5]
	global_load_lds_dwordx4 v226, s[54:55]
	v_mfma_f32_16x16x32_bf16 v[6:9], v[214:217], v[178:181], v[6:9]
	v_mfma_f32_16x16x32_bf16 v[10:13], v[218:221], v[178:181], v[10:13]
	v_mfma_f32_16x16x32_bf16 v[14:17], v[222:225], v[178:181], v[14:17]
	v_mfma_f32_16x16x32_bf16 v[18:21], v[210:213], v[182:185], v[18:21]
	v_mfma_f32_16x16x32_bf16 v[22:25], v[214:217], v[182:185], v[22:25]
	global_load_lds_dwordx4 v226, s[54:55] offset:1024
	v_mfma_f32_16x16x32_bf16 v[26:29], v[218:221], v[182:185], v[26:29]
	v_mfma_f32_16x16x32_bf16 v[30:33], v[222:225], v[182:185], v[30:33]
	v_mfma_f32_16x16x32_bf16 v[34:37], v[210:213], v[186:189], v[34:37]
	ds_read_b128 v[162:165], v241 offset:0
	v_mfma_f32_16x16x32_bf16 v[38:41], v[214:217], v[186:189], v[38:41]
	ds_read_b128 v[166:169], v241 offset:256
	v_mfma_f32_16x16x32_bf16 v[42:45], v[218:221], v[186:189], v[42:45]
	ds_read_b128 v[170:173], v241 offset:2048
	global_load_lds_dwordx4 v226, s[54:55] offset:2048
	v_mfma_f32_16x16x32_bf16 v[46:49], v[222:225], v[186:189], v[46:49]
	ds_read_b128 v[174:177], v241 offset:2304
	v_mfma_f32_16x16x32_bf16 v[50:53], v[210:213], v[190:193], v[50:53]
	ds_read_b128 v[130:133], v240 offset:0
	v_mfma_f32_16x16x32_bf16 v[54:57], v[214:217], v[190:193], v[54:57]
	ds_read_b128 v[134:137], v240 offset:1024
	v_mfma_f32_16x16x32_bf16 v[58:61], v[218:221], v[190:193], v[58:61]
	ds_read_b128 v[138:141], v240 offset:2048
	v_mfma_f32_16x16x32_bf16 v[62:65], v[222:225], v[190:193], v[62:65]
	ds_read_b128 v[142:145], v240 offset:3072
	global_load_lds_dwordx4 v226, s[54:55] offset:3072
	v_mfma_f32_16x16x32_bf16 v[66:69], v[210:213], v[194:197], v[66:69]
	ds_read_b128 v[146:149], v240 offset:4096
	v_mfma_f32_16x16x32_bf16 v[70:73], v[214:217], v[194:197], v[70:73]
	ds_read_b128 v[150:153], v240 offset:5120
	v_mfma_f32_16x16x32_bf16 v[74:77], v[218:221], v[194:197], v[74:77]
	ds_read_b128 v[154:157], v240 offset:6144
	v_mfma_f32_16x16x32_bf16 v[78:81], v[222:225], v[194:197], v[78:81]
	ds_read_b128 v[158:161], v240 offset:7168
	s_add_i32 m0, s60, s63
	v_mfma_f32_16x16x32_bf16 v[82:85], v[210:213], v[198:201], v[82:85]
	global_load_lds_dwordx4 v230, s[56:57]
	v_mfma_f32_16x16x32_bf16 v[86:89], v[214:217], v[198:201], v[86:89]
	v_mfma_f32_16x16x32_bf16 v[90:93], v[218:221], v[198:201], v[90:93]
	v_mfma_f32_16x16x32_bf16 v[94:97], v[222:225], v[198:201], v[94:97]
	v_mfma_f32_16x16x32_bf16 v[98:101], v[210:213], v[202:205], v[98:101]
	v_mfma_f32_16x16x32_bf16 v[102:105], v[214:217], v[202:205], v[102:105]
	global_load_lds_dwordx4 v231, s[56:57] offset:1024
	v_mfma_f32_16x16x32_bf16 v[106:109], v[218:221], v[202:205], v[106:109]
	v_mfma_f32_16x16x32_bf16 v[110:113], v[222:225], v[202:205], v[110:113]
	v_mfma_f32_16x16x32_bf16 v[114:117], v[210:213], v[206:209], v[114:117]
	v_mfma_f32_16x16x32_bf16 v[118:121], v[214:217], v[206:209], v[118:121]
	v_mfma_f32_16x16x32_bf16 v[122:125], v[218:221], v[206:209], v[122:125]
	v_mfma_f32_16x16x32_bf16 v[126:129], v[222:225], v[206:209], v[126:129]
	s_setprio 0
	s_add_i32 s60, s60, 0x6000
	s_cmp_eq_u32 s60, 0x12000
	s_cselect_b32 s60, 0, s60
	s_add_u32 s54, s54, s72
	s_addc_u32 s55, s55, 0
	s_add_u32 s56, s56, s73
	s_addc_u32 s57, s57, 0
	s_add_i32 s61, s61, 0x6000
	s_cmp_eq_u32 s61, 0x12000
	s_cselect_b32 s61, 0, s61

.Lup_kloop:
	s_waitcnt vmcnt(6) lgkmcnt(0)
	s_barrier
	v_add_u32_e32 v240, s61, v238
	v_add_u32_e32 v241, s61, v239
	s_setprio 1
	s_add_i32 m0, s60, s62
	v_mfma_f32_16x16x32_bf16 v[2:5], v[162:165], v[130:133], v[2:5]
	global_load_lds_dwordx4 v226, s[54:55]
	v_mfma_f32_16x16x32_bf16 v[6:9], v[166:169], v[130:133], v[6:9]
	v_mfma_f32_16x16x32_bf16 v[10:13], v[170:173], v[130:133], v[10:13]
	v_mfma_f32_16x16x32_bf16 v[14:17], v[174:177], v[130:133], v[14:17]
	v_mfma_f32_16x16x32_bf16 v[18:21], v[162:165], v[134:137], v[18:21]
	v_mfma_f32_16x16x32_bf16 v[22:25], v[166:169], v[134:137], v[22:25]
	global_load_lds_dwordx4 v226, s[54:55] offset:1024
	v_mfma_f32_16x16x32_bf16 v[26:29], v[170:173], v[134:137], v[26:29]
	v_mfma_f32_16x16x32_bf16 v[30:33], v[174:177], v[134:137], v[30:33]
	v_mfma_f32_16x16x32_bf16 v[34:37], v[162:165], v[138:141], v[34:37]
	ds_read_b128 v[210:213], v241 offset:0
	v_mfma_f32_16x16x32_bf16 v[38:41], v[166:169], v[138:141], v[38:41]
	ds_read_b128 v[214:217], v241 offset:256
	v_mfma_f32_16x16x32_bf16 v[42:45], v[170:173], v[138:141], v[42:45]
	ds_read_b128 v[218:221], v241 offset:2048
	global_load_lds_dwordx4 v226, s[54:55] offset:2048
	v_mfma_f32_16x16x32_bf16 v[46:49], v[174:177], v[138:141], v[46:49]
	ds_read_b128 v[222:225], v241 offset:2304
	v_mfma_f32_16x16x32_bf16 v[50:53], v[162:165], v[142:145], v[50:53]
	ds_read_b128 v[178:181], v240 offset:0
	v_mfma_f32_16x16x32_bf16 v[54:57], v[166:169], v[142:145], v[54:57]
	ds_read_b128 v[182:185], v240 offset:1024
	v_mfma_f32_16x16x32_bf16 v[58:61], v[170:173], v[142:145], v[58:61]
	ds_read_b128 v[186:189], v240 offset:2048
	v_mfma_f32_16x16x32_bf16 v[62:65], v[174:177], v[142:145], v[62:65]
	ds_read_b128 v[190:193], v240 offset:3072
	global_load_lds_dwordx4 v226, s[54:55] offset:3072
	v_mfma_f32_16x16x32_bf16 v[66:69], v[162:165], v[146:149], v[66:69]
	ds_read_b128 v[194:197], v240 offset:4096
	v_mfma_f32_16x16x32_bf16 v[70:73], v[166:169], v[146:149], v[70:73]
	ds_read_b128 v[198:201], v240 offset:5120
	v_mfma_f32_16x16x32_bf16 v[74:77], v[170:173], v[146:149], v[74:77]
	ds_read_b128 v[202:205], v240 offset:6144
	v_mfma_f32_16x16x32_bf16 v[78:81], v[174:177], v[146:149], v[78:81]
	ds_read_b128 v[206:209], v240 offset:7168
	s_add_i32 m0, s60, s63
	v_mfma_f32_16x16x32_bf16 v[82:85], v[162:165], v[150:153], v[82:85]
	global_load_lds_dwordx4 v230, s[56:57]
	v_mfma_f32_16x16x32_bf16 v[86:89], v[166:169], v[150:153], v[86:89]
	v_mfma_f32_16x16x32_bf16 v[90:93], v[170:173], v[150:153], v[90:93]
	v_mfma_f32_16x16x32_bf16 v[94:97], v[174:177], v[150:153], v[94:97]
	v_mfma_f32_16x16x32_bf16 v[98:101], v[162:165], v[154:157], v[98:101]
	v_mfma_f32_16x16x32_bf16 v[102:105], v[166:169], v[154:157], v[102:105]
	global_load_lds_dwordx4 v231, s[56:57] offset:1024
	v_mfma_f32_16x16x32_bf16 v[106:109], v[170:173], v[154:157], v[106:109]
	v_mfma_f32_16x16x32_bf16 v[110:113], v[174:177], v[154:157], v[110:113]
	v_mfma_f32_16x16x32_bf16 v[114:117], v[162:165], v[158:161], v[114:117]
	v_mfma_f32_16x16x32_bf16 v[118:121], v[166:169], v[158:161], v[118:121]
	v_mfma_f32_16x16x32_bf16 v[122:125], v[170:173], v[158:161], v[122:125]
	v_mfma_f32_16x16x32_bf16 v[126:129], v[174:177], v[158:161], v[126:129]
	s_setprio 0
	s_add_i32 s60, s60, 0x6000
	s_cmp_eq_u32 s60, 0x12000
	s_cselect_b32 s60, 0, s60
	s_add_u32 s54, s54, s72
	s_addc_u32 s55, s55, 0
	s_add_u32 s56, s56, s73
	s_addc_u32 s57, s57, 0
	s_add_i32 s61, s61, 0x6000
	s_cmp_eq_u32 s61, 0x12000
	s_cselect_b32 s61, 0, s61
	s_waitcnt vmcnt(6) lgkmcnt(0)
	s_barrier
	v_add_u32_e32 v240, s61, v238
	v_add_u32_e32 v241, s61, v239
	s_setprio 1
	s_add_i32 m0, s60, s62
	v_mfma_f32_16x16x32_bf16 v[2:5], v[210:213], v[178:181], v[2:5]
	global_load_lds_dwordx4 v226, s[54:55]
	v_mfma_f32_16x16x32_bf16 v[6:9], v[214:217], v[178:181], v[6:9]
	v_mfma_f32_16x16x32_bf16 v[10:13], v[218:221], v[178:181], v[10:13]
	v_mfma_f32_16x16x32_bf16 v[14:17], v[222:225], v[178:181], v[14:17]
	v_mfma_f32_16x16x32_bf16 v[18:21], v[210:213], v[182:185], v[18:21]
	v_mfma_f32_16x16x32_bf16 v[22:25], v[214:217], v[182:185], v[22:25]
	global_load_lds_dwordx4 v226, s[54:55] offset:1024
	v_mfma_f32_16x16x32_bf16 v[26:29], v[218:221], v[182:185], v[26:29]
	v_mfma_f32_16x16x32_bf16 v[30:33], v[222:225], v[182:185], v[30:33]
	v_mfma_f32_16x16x32_bf16 v[34:37], v[210:213], v[186:189], v[34:37]
	ds_read_b128 v[162:165], v241 offset:0
	v_mfma_f32_16x16x32_bf16 v[38:41], v[214:217], v[186:189], v[38:41]
	ds_read_b128 v[166:169], v241 offset:256
	v_mfma_f32_16x16x32_bf16 v[42:45], v[218:221], v[186:189], v[42:45]
	ds_read_b128 v[170:173], v241 offset:2048
	global_load_lds_dwordx4 v226, s[54:55] offset:2048
	v_mfma_f32_16x16x32_bf16 v[46:49], v[222:225], v[186:189], v[46:49]
	ds_read_b128 v[174:177], v241 offset:2304
	v_mfma_f32_16x16x32_bf16 v[50:53], v[210:213], v[190:193], v[50:53]
	ds_read_b128 v[130:133], v240 offset:0
	v_mfma_f32_16x16x32_bf16 v[54:57], v[214:217], v[190:193], v[54:57]
	ds_read_b128 v[134:137], v240 offset:1024
	v_mfma_f32_16x16x32_bf16 v[58:61], v[218:221], v[190:193], v[58:61]
	ds_read_b128 v[138:141], v240 offset:2048
	v_mfma_f32_16x16x32_bf16 v[62:65], v[222:225], v[190:193], v[62:65]
	ds_read_b128 v[142:145], v240 offset:3072
	global_load_lds_dwordx4 v226, s[54:55] offset:3072
	v_mfma_f32_16x16x32_bf16 v[66:69], v[210:213], v[194:197], v[66:69]
	ds_read_b128 v[146:149], v240 offset:4096
	v_mfma_f32_16x16x32_bf16 v[70:73], v[214:217], v[194:197], v[70:73]
	ds_read_b128 v[150:153], v240 offset:5120
	v_mfma_f32_16x16x32_bf16 v[74:77], v[218:221], v[194:197], v[74:77]
	ds_read_b128 v[154:157], v240 offset:6144
	v_mfma_f32_16x16x32_bf16 v[78:81], v[222:225], v[194:197], v[78:81]
	ds_read_b128 v[158:161], v240 offset:7168
	s_add_i32 m0, s60, s63
	v_mfma_f32_16x16x32_bf16 v[82:85], v[210:213], v[198:201], v[82:85]
	global_load_lds_dwordx4 v230, s[56:57]
	v_mfma_f32_16x16x32_bf16 v[86:89], v[214:217], v[198:201], v[86:89]
	v_mfma_f32_16x16x32_bf16 v[90:93], v[218:221], v[198:201], v[90:93]
	v_mfma_f32_16x16x32_bf16 v[94:97], v[222:225], v[198:201], v[94:97]
	v_mfma_f32_16x16x32_bf16 v[98:101], v[210:213], v[202:205], v[98:101]
	v_mfma_f32_16x16x32_bf16 v[102:105], v[214:217], v[202:205], v[102:105]
	global_load_lds_dwordx4 v231, s[56:57] offset:1024
	v_mfma_f32_16x16x32_bf16 v[106:109], v[218:221], v[202:205], v[106:109]
	v_mfma_f32_16x16x32_bf16 v[110:113], v[222:225], v[202:205], v[110:113]
	v_mfma_f32_16x16x32_bf16 v[114:117], v[210:213], v[206:209], v[114:117]
	v_mfma_f32_16x16x32_bf16 v[118:121], v[214:217], v[206:209], v[118:121]
	v_mfma_f32_16x16x32_bf16 v[122:125], v[218:221], v[206:209], v[122:125]
	v_mfma_f32_16x16x32_bf16 v[126:129], v[222:225], v[206:209], v[126:129]
	s_setprio 0
	s_add_i32 s60, s60, 0x6000
	s_cmp_eq_u32 s60, 0x12000
	s_cselect_b32 s60, 0, s60
	s_add_u32 s54, s54, s72
	s_addc_u32 s55, s55, 0
	s_add_u32 s56, s56, s73
	s_addc_u32 s57, s57, 0
	s_add_i32 s61, s61, 0x6000
	s_cmp_eq_u32 s61, 0x12000
	s_cselect_b32 s61, 0, s61
	s_add_i32 s40, s40, -1
	s_cmp_lg_u32 s40, 0
	s_cbranch_scc1 .Lup_kloop
.Lup_kdone:
	s_cmp_eq_u32 s37, 0
	s_cbranch_scc1 .Lup_tail_last
	s_waitcnt vmcnt(6) lgkmcnt(0)
	s_barrier
	v_add_u32_e32 v240, s61, v238
	v_add_u32_e32 v241, s61, v239
	s_setprio 1
	s_add_i32 m0, s60, s62
	v_mfma_f32_16x16x32_bf16 v[2:5], v[162:165], v[130:133], v[2:5]
	global_load_lds_dwordx4 v226, s[54:55]
	v_mfma_f32_16x16x32_bf16 v[6:9], v[166:169], v[130:133], v[6:9]
	v_mfma_f32_16x16x32_bf16 v[10:13], v[170:173], v[130:133], v[10:13]
	v_mfma_f32_16x16x32_bf16 v[14:17], v[174:177], v[130:133], v[14:17]
	v_mfma_f32_16x16x32_bf16 v[18:21], v[162:165], v[134:137], v[18:21]
	v_mfma_f32_16x16x32_bf16 v[22:25], v[166:169], v[134:137], v[22:25]
	global_load_lds_dwordx4 v226, s[54:55] offset:1024
	v_mfma_f32_16x16x32_bf16 v[26:29], v[170:173], v[134:137], v[26:29]
	v_mfma_f32_16x16x32_bf16 v[30:33], v[174:177], v[134:137], v[30:33]
	v_mfma_f32_16x16x32_bf16 v[34:37], v[162:165], v[138:141], v[34:37]
	ds_read_b128 v[210:213], v241 offset:0
	v_mfma_f32_16x16x32_bf16 v[38:41], v[166:169], v[138:141], v[38:41]
	ds_read_b128 v[214:217], v241 offset:256
	v_mfma_f32_16x16x32_bf16 v[42:45], v[170:173], v[138:141], v[42:45]
	ds_read_b128 v[218:221], v241 offset:2048
	global_load_lds_dwordx4 v226, s[54:55] offset:2048
	v_mfma_f32_16x16x32_bf16 v[46:49], v[174:177], v[138:141], v[46:49]
	ds_read_b128 v[222:225], v241 offset:2304
	v_mfma_f32_16x16x32_bf16 v[50:53], v[162:165], v[142:145], v[50:53]
	ds_read_b128 v[178:181], v240 offset:0
	v_mfma_f32_16x16x32_bf16 v[54:57], v[166:169], v[142:145], v[54:57]
	ds_read_b128 v[182:185], v240 offset:1024
	v_mfma_f32_16x16x32_bf16 v[58:61], v[170:173], v[142:145], v[58:61]
	ds_read_b128 v[186:189], v240 offset:2048
	v_mfma_f32_16x16x32_bf16 v[62:65], v[174:177], v[142:145], v[62:65]
	ds_read_b128 v[190:193], v240 offset:3072
	global_load_lds_dwordx4 v226, s[54:55] offset:3072
	v_mfma_f32_16x16x32_bf16 v[66:69], v[162:165], v[146:149], v[66:69]
	ds_read_b128 v[194:197], v240 offset:4096
	v_mfma_f32_16x16x32_bf16 v[70:73], v[166:169], v[146:149], v[70:73]
	ds_read_b128 v[198:201], v240 offset:5120
	v_mfma_f32_16x16x32_bf16 v[74:77], v[170:173], v[146:149], v[74:77]
	ds_read_b128 v[202:205], v240 offset:6144
	v_mfma_f32_16x16x32_bf16 v[78:81], v[174:177], v[146:149], v[78:81]
	ds_read_b128 v[206:209], v240 offset:7168
	s_add_i32 m0, s60, s63
	v_mfma_f32_16x16x32_bf16 v[82:85], v[162:165], v[150:153], v[82:85]
	global_load_lds_dwordx4 v230, s[56:57]
	v_mfma_f32_16x16x32_bf16 v[86:89], v[166:169], v[150:153], v[86:89]
	v_mfma_f32_16x16x32_bf16 v[90:93], v[170:173], v[150:153], v[90:93]
	v_mfma_f32_16x16x32_bf16 v[94:97], v[174:177], v[150:153], v[94:97]
	v_mfma_f32_16x16x32_bf16 v[98:101], v[162:165], v[154:157], v[98:101]
	v_mfma_f32_16x16x32_bf16 v[102:105], v[166:169], v[154:157], v[102:105]
	global_load_lds_dwordx4 v231, s[56:57] offset:1024
	v_mfma_f32_16x16x32_bf16 v[106:109], v[170:173], v[154:157], v[106:109]
	v_mfma_f32_16x16x32_bf16 v[110:113], v[174:177], v[154:157], v[110:113]
	v_mfma_f32_16x16x32_bf16 v[114:117], v[162:165], v[158:161], v[114:117]
	v_mfma_f32_16x16x32_bf16 v[118:121], v[166:169], v[158:161], v[118:121]
	v_mfma_f32_16x16x32_bf16 v[122:125], v[170:173], v[158:161], v[122:125]
	v_mfma_f32_16x16x32_bf16 v[126:129], v[174:177], v[158:161], v[126:129]
	s_setprio 0
	s_add_i32 s60, s60, 0x6000
	s_cmp_eq_u32 s60, 0x12000
	s_cselect_b32 s60, 0, s60
	s_add_u32 s54, s54, s72
	s_addc_u32 s55, s55, 0
	s_add_u32 s56, s56, s73
	s_addc_u32 s57, s57, 0
	s_add_i32 s61, s61, 0x6000
	s_cmp_eq_u32 s61, 0x12000
	s_cselect_b32 s61, 0, s61
	v_mov_b32_e32 v226, v232
	v_mov_b32_e32 v230, v236
	v_mov_b32_e32 v231, v237
	s_mov_b64 s[54:55], s[48:49]
	s_mov_b64 s[56:57], s[50:51]
	s_waitcnt vmcnt(6) lgkmcnt(0)
	s_barrier
	v_add_u32_e32 v240, s61, v238
	v_add_u32_e32 v241, s61, v239
	s_setprio 1
	s_add_i32 m0, s60, s62
	v_mfma_f32_16x16x32_bf16 v[2:5], v[210:213], v[178:181], v[2:5]
	global_load_lds_dwordx4 v226, s[54:55]
	v_mfma_f32_16x16x32_bf16 v[6:9], v[214:217], v[178:181], v[6:9]
	v_mfma_f32_16x16x32_bf16 v[10:13], v[218:221], v[178:181], v[10:13]
	v_mfma_f32_16x16x32_bf16 v[14:17], v[222:225], v[178:181], v[14:17]
	v_mfma_f32_16x16x32_bf16 v[18:21], v[210:213], v[182:185], v[18:21]
	v_mfma_f32_16x16x32_bf16 v[22:25], v[214:217], v[182:185], v[22:25]
	global_load_lds_dwordx4 v226, s[54:55] offset:1024
	v_mfma_f32_16x16x32_bf16 v[26:29], v[218:221], v[182:185], v[26:29]
	v_mfma_f32_16x16x32_bf16 v[30:33], v[222:225], v[182:185], v[30:33]
	v_mfma_f32_16x16x32_bf16 v[34:37], v[210:213], v[186:189], v[34:37]
	ds_read_b128 v[162:165], v241 offset:0
	v_mfma_f32_16x16x32_bf16 v[38:41], v[214:217], v[186:189], v[38:41]
	ds_read_b128 v[166:169], v241 offset:256
	v_mfma_f32_16x16x32_bf16 v[42:45], v[218:221], v[186:189], v[42:45]
	ds_read_b128 v[170:173], v241 offset:2048
	global_load_lds_dwordx4 v226, s[54:55] offset:2048
	v_mfma_f32_16x16x32_bf16 v[46:49], v[222:225], v[186:189], v[46:49]
	ds_read_b128 v[174:177], v241 offset:2304
	v_mfma_f32_16x16x32_bf16 v[50:53], v[210:213], v[190:193], v[50:53]
	ds_read_b128 v[130:133], v240 offset:0
	v_mfma_f32_16x16x32_bf16 v[54:57], v[214:217], v[190:193], v[54:57]
	ds_read_b128 v[134:137], v240 offset:1024
	v_mfma_f32_16x16x32_bf16 v[58:61], v[218:221], v[190:193], v[58:61]
	ds_read_b128 v[138:141], v240 offset:2048
	v_mfma_f32_16x16x32_bf16 v[62:65], v[222:225], v[190:193], v[62:65]
	ds_read_b128 v[142:145], v240 offset:3072
	global_load_lds_dwordx4 v226, s[54:55] offset:3072
	v_mfma_f32_16x16x32_bf16 v[66:69], v[210:213], v[194:197], v[66:69]
	ds_read_b128 v[146:149], v240 offset:4096
	v_mfma_f32_16x16x32_bf16 v[70:73], v[214:217], v[194:197], v[70:73]
	ds_read_b128 v[150:153], v240 offset:5120
	v_mfma_f32_16x16x32_bf16 v[74:77], v[218:221], v[194:197], v[74:77]
	ds_read_b128 v[154:157], v240 offset:6144
	v_mfma_f32_16x16x32_bf16 v[78:81], v[222:225], v[194:197], v[78:81]
	ds_read_b128 v[158:161], v240 offset:7168
	s_add_i32 m0, s60, s63
	v_mfma_f32_16x16x32_bf16 v[82:85], v[210:213], v[198:201], v[82:85]
	global_load_lds_dwordx4 v230, s[56:57]
	v_mfma_f32_16x16x32_bf16 v[86:89], v[214:217], v[198:201], v[86:89]
	v_mfma_f32_16x16x32_bf16 v[90:93], v[218:221], v[198:201], v[90:93]
	v_mfma_f32_16x16x32_bf16 v[94:97], v[222:225], v[198:201], v[94:97]
	v_mfma_f32_16x16x32_bf16 v[98:101], v[210:213], v[202:205], v[98:101]
	v_mfma_f32_16x16x32_bf16 v[102:105], v[214:217], v[202:205], v[102:105]
	global_load_lds_dwordx4 v231, s[56:57] offset:1024
	v_mfma_f32_16x16x32_bf16 v[106:109], v[218:221], v[202:205], v[106:109]
	v_mfma_f32_16x16x32_bf16 v[110:113], v[222:225], v[202:205], v[110:113]
	v_mfma_f32_16x16x32_bf16 v[114:117], v[210:213], v[206:209], v[114:117]
	v_mfma_f32_16x16x32_bf16 v[118:121], v[214:217], v[206:209], v[118:121]
	v_mfma_f32_16x16x32_bf16 v[122:125], v[218:221], v[206:209], v[122:125]
	v_mfma_f32_16x16x32_bf16 v[126:129], v[222:225], v[206:209], v[126:129]
	s_setprio 0
	s_add_i32 s60, s60, 0x6000
	s_cmp_eq_u32 s60, 0x12000
	s_cselect_b32 s60, 0, s60
	s_add_u32 s54, s54, s72
	s_addc_u32 s55, s55, 0
	s_add_u32 s56, s56, s73
	s_addc_u32 s57, s57, 0
	s_add_i32 s61, s61, 0x6000
	s_cmp_eq_u32 s61, 0x12000
	s_cselect_b32 s61, 0, s61
	s_waitcnt vmcnt(6) lgkmcnt(0)
	s_barrier
	v_add_u32_e32 v240, s61, v238
	v_add_u32_e32 v241, s61, v239
	s_setprio 1
	s_add_i32 m0, s60, s62
	v_mfma_f32_16x16x32_bf16 v[2:5], v[162:165], v[130:133], v[2:5]
	global_load_lds_dwordx4 v226, s[54:55]
	v_mfma_f32_16x16x32_bf16 v[6:9], v[166:169], v[130:133], v[6:9]
	v_mfma_f32_16x16x32_bf16 v[10:13], v[170:173], v[130:133], v[10:13]
	v_mfma_f32_16x16x32_bf16 v[14:17], v[174:177], v[130:133], v[14:17]
	v_mfma_f32_16x16x32_bf16 v[18:21], v[162:165], v[134:137], v[18:21]
	v_mfma_f32_16x16x32_bf16 v[22:25], v[166:169], v[134:137], v[22:25]
	global_load_lds_dwordx4 v226, s[54:55] offset:1024
	v_mfma_f32_16x16x32_bf16 v[26:29], v[170:173], v[134:137], v[26:29]
	v_mfma_f32_16x16x32_bf16 v[30:33], v[174:177], v[134:137], v[30:33]
	v_mfma_f32_16x16x32_bf16 v[34:37], v[162:165], v[138:141], v[34:37]
	ds_read_b128 v[210:213], v241 offset:0
	v_mfma_f32_16x16x32_bf16 v[38:41], v[166:169], v[138:141], v[38:41]
	ds_read_b128 v[214:217], v241 offset:256
	v_mfma_f32_16x16x32_bf16 v[42:45], v[170:173], v[138:141], v[42:45]
	ds_read_b128 v[218:221], v241 offset:2048
	global_load_lds_dwordx4 v226, s[54:55] offset:2048
	v_mfma_f32_16x16x32_bf16 v[46:49], v[174:177], v[138:141], v[46:49]
	ds_read_b128 v[222:225], v241 offset:2304
	v_mfma_f32_16x16x32_bf16 v[50:53], v[162:165], v[142:145], v[50:53]
	ds_read_b128 v[178:181], v240 offset:0
	v_mfma_f32_16x16x32_bf16 v[54:57], v[166:169], v[142:145], v[54:57]
	ds_read_b128 v[182:185], v240 offset:1024
	v_mfma_f32_16x16x32_bf16 v[58:61], v[170:173], v[142:145], v[58:61]
	ds_read_b128 v[186:189], v240 offset:2048
	v_mfma_f32_16x16x32_bf16 v[62:65], v[174:177], v[142:145], v[62:65]
	ds_read_b128 v[190:193], v240 offset:3072
	global_load_lds_dwordx4 v226, s[54:55] offset:3072
	v_mfma_f32_16x16x32_bf16 v[66:69], v[162:165], v[146:149], v[66:69]
	ds_read_b128 v[194:197], v240 offset:4096
	v_mfma_f32_16x16x32_bf16 v[70:73], v[166:169], v[146:149], v[70:73]
	ds_read_b128 v[198:201], v240 offset:5120
	v_mfma_f32_16x16x32_bf16 v[74:77], v[170:173], v[146:149], v[74:77]
	ds_read_b128 v[202:205], v240 offset:6144
	v_mfma_f32_16x16x32_bf16 v[78:81], v[174:177], v[146:149], v[78:81]
	ds_read_b128 v[206:209], v240 offset:7168
	s_add_i32 m0, s60, s63
	v_mfma_f32_16x16x32_bf16 v[82:85], v[162:165], v[150:153], v[82:85]
	global_load_lds_dwordx4 v230, s[56:57]
	v_mfma_f32_16x16x32_bf16 v[86:89], v[166:169], v[150:153], v[86:89]
	v_mfma_f32_16x16x32_bf16 v[90:93], v[170:173], v[150:153], v[90:93]
	v_mfma_f32_16x16x32_bf16 v[94:97], v[174:177], v[150:153], v[94:97]
	v_mfma_f32_16x16x32_bf16 v[98:101], v[162:165], v[154:157], v[98:101]
	v_mfma_f32_16x16x32_bf16 v[102:105], v[166:169], v[154:157], v[102:105]
	global_load_lds_dwordx4 v231, s[56:57] offset:1024
	v_mfma_f32_16x16x32_bf16 v[106:109], v[170:173], v[154:157], v[106:109]
	v_mfma_f32_16x16x32_bf16 v[110:113], v[174:177], v[154:157], v[110:113]
	v_mfma_f32_16x16x32_bf16 v[114:117], v[162:165], v[158:161], v[114:117]
	v_mfma_f32_16x16x32_bf16 v[118:121], v[166:169], v[158:161], v[118:121]
	v_mfma_f32_16x16x32_bf16 v[122:125], v[170:173], v[158:161], v[122:125]
	v_mfma_f32_16x16x32_bf16 v[126:129], v[174:177], v[158:161], v[126:129]
	s_setprio 0
	s_add_i32 s60, s60, 0x6000
	s_cmp_eq_u32 s60, 0x12000
	s_cselect_b32 s60, 0, s60
	s_add_u32 s54, s54, s72
	s_addc_u32 s55, s55, 0
	s_add_u32 s56, s56, s73
	s_addc_u32 s57, s57, 0
	s_add_i32 s61, s61, 0x6000
	s_cmp_eq_u32 s61, 0x12000
	s_cselect_b32 s61, 0, s61
	s_waitcnt vmcnt(6) lgkmcnt(0)
	s_barrier
	v_add_u32_e32 v240, s61, v238
	v_add_u32_e32 v241, s61, v239
	s_setprio 1
	s_add_i32 m0, s60, s62
	v_mfma_f32_16x16x32_bf16 v[2:5], v[210:213], v[178:181], v[2:5]
	global_load_lds_dwordx4 v226, s[54:55]
	v_mfma_f32_16x16x32_bf16 v[6:9], v[214:217], v[178:181], v[6:9]
	v_mfma_f32_16x16x32_bf16 v[10:13], v[218:221], v[178:181], v[10:13]
	v_mfma_f32_16x16x32_bf16 v[14:17], v[222:225], v[178:181], v[14:17]
	v_mfma_f32_16x16x32_bf16 v[18:21], v[210:213], v[182:185], v[18:21]
	v_mfma_f32_16x16x32_bf16 v[22:25], v[214:217], v[182:185], v[22:25]
	global_load_lds_dwordx4 v226, s[54:55] offset:1024
	v_mfma_f32_16x16x32_bf16 v[26:29], v[218:221], v[182:185], v[26:29]
	v_mfma_f32_16x16x32_bf16 v[30:33], v[222:225], v[182:185], v[30:33]
	v_mfma_f32_16x16x32_bf16 v[34:37], v[210:213], v[186:189], v[34:37]
	ds_read_b128 v[162:165], v241 offset:0
	v_mfma_f32_16x16x32_bf16 v[38:41], v[214:217], v[186:189], v[38:41]
	ds_read_b128 v[166:169], v241 offset:256
	v_mfma_f32_16x16x32_bf16 v[42:45], v[218:221], v[186:189], v[42:45]
	ds_read_b128 v[170:173], v241 offset:2048
	global_load_lds_dwordx4 v226, s[54:55] offset:2048
	v_mfma_f32_16x16x32_bf16 v[46:49], v[222:225], v[186:189], v[46:49]
	ds_read_b128 v[174:177], v241 offset:2304
	v_mfma_f32_16x16x32_bf16 v[50:53], v[210:213], v[190:193], v[50:53]
	ds_read_b128 v[130:133], v240 offset:0
	v_mfma_f32_16x16x32_bf16 v[54:57], v[214:217], v[190:193], v[54:57]
	ds_read_b128 v[134:137], v240 offset:1024
	v_mfma_f32_16x16x32_bf16 v[58:61], v[218:221], v[190:193], v[58:61]
	ds_read_b128 v[138:141], v240 offset:2048
	v_mfma_f32_16x16x32_bf16 v[62:65], v[222:225], v[190:193], v[62:65]
	ds_read_b128 v[142:145], v240 offset:3072
	global_load_lds_dwordx4 v226, s[54:55] offset:3072
	v_mfma_f32_16x16x32_bf16 v[66:69], v[210:213], v[194:197], v[66:69]
	ds_read_b128 v[146:149], v240 offset:4096
	v_mfma_f32_16x16x32_bf16 v[70:73], v[214:217], v[194:197], v[70:73]
	ds_read_b128 v[150:153], v240 offset:5120
	v_mfma_f32_16x16x32_bf16 v[74:77], v[218:221], v[194:197], v[74:77]
	ds_read_b128 v[154:157], v240 offset:6144
	v_mfma_f32_16x16x32_bf16 v[78:81], v[222:225], v[194:197], v[78:81]
	ds_read_b128 v[158:161], v240 offset:7168
	s_add_i32 m0, s60, s63
	v_mfma_f32_16x16x32_bf16 v[82:85], v[210:213], v[198:201], v[82:85]
	global_load_lds_dwordx4 v230, s[56:57]
	v_mfma_f32_16x16x32_bf16 v[86:89], v[214:217], v[198:201], v[86:89]
	v_mfma_f32_16x16x32_bf16 v[90:93], v[218:221], v[198:201], v[90:93]
	v_mfma_f32_16x16x32_bf16 v[94:97], v[222:225], v[198:201], v[94:97]
	v_mfma_f32_16x16x32_bf16 v[98:101], v[210:213], v[202:205], v[98:101]
	v_mfma_f32_16x16x32_bf16 v[102:105], v[214:217], v[202:205], v[102:105]
	global_load_lds_dwordx4 v231, s[56:57] offset:1024
	v_mfma_f32_16x16x32_bf16 v[106:109], v[218:221], v[202:205], v[106:109]
	v_mfma_f32_16x16x32_bf16 v[110:113], v[222:225], v[202:205], v[110:113]
	v_mfma_f32_16x16x32_bf16 v[114:117], v[210:213], v[206:209], v[114:117]
	v_mfma_f32_16x16x32_bf16 v[118:121], v[214:217], v[206:209], v[118:121]
	v_mfma_f32_16x16x32_bf16 v[122:125], v[218:221], v[206:209], v[122:125]
	v_mfma_f32_16x16x32_bf16 v[126:129], v[222:225], v[206:209], v[126:129]
	s_setprio 0
	s_add_i32 s60, s60, 0x6000
	s_cmp_eq_u32 s60, 0x12000
	s_cselect_b32 s60, 0, s60
	s_add_u32 s54, s54, s72
	s_addc_u32 s55, s55, 0
	s_add_u32 s56, s56, s73
	s_addc_u32 s57, s57, 0
	s_add_i32 s61, s61, 0x6000
	s_cmp_eq_u32 s61, 0x12000
	s_cselect_b32 s61, 0, s61
	s_and_b32 s39, s35, 0xfff
	s_lshr_b32 s21, s36, 7
	s_waitcnt vmcnt(18)
	v_mbcnt_lo_u32_b32 v217, -1, 0
	v_mbcnt_hi_u32_b32 v217, -1, v217
	v_lshlrev_b32_e32 v217, 5, v217
	s_lshl_b32 s26, s43, 11
	v_add_u32_e32 v248, s26, v217
	s_add_i32 s26, s26, 0x12010
	v_add_u32_e32 v217, s26, v217
	s_cmp_eq_u32 s42, 0
	s_cbranch_scc0 .Lup_en_nowr
	ds_write_b128 v217, v[114:117]
	ds_write_b128 v217, v[118:121] offset:16
	s_branch .Lup_en_wrd

.Lup_tail_last:
	s_waitcnt vmcnt(6) lgkmcnt(0)
	s_barrier
	v_add_u32_e32 v240, s61, v238
	v_add_u32_e32 v241, s61, v239
	s_setprio 1
	s_add_i32 m0, s60, s62
	v_mfma_f32_16x16x32_bf16 v[2:5], v[162:165], v[130:133], v[2:5]
	global_load_lds_dwordx4 v226, s[54:55]
	v_mfma_f32_16x16x32_bf16 v[6:9], v[166:169], v[130:133], v[6:9]
	v_mfma_f32_16x16x32_bf16 v[10:13], v[170:173], v[130:133], v[10:13]
	v_mfma_f32_16x16x32_bf16 v[14:17], v[174:177], v[130:133], v[14:17]
	v_mfma_f32_16x16x32_bf16 v[18:21], v[162:165], v[134:137], v[18:21]
	v_mfma_f32_16x16x32_bf16 v[22:25], v[166:169], v[134:137], v[22:25]
	global_load_lds_dwordx4 v226, s[54:55] offset:1024
	v_mfma_f32_16x16x32_bf16 v[26:29], v[170:173], v[134:137], v[26:29]
	v_mfma_f32_16x16x32_bf16 v[30:33], v[174:177], v[134:137], v[30:33]
	v_mfma_f32_16x16x32_bf16 v[34:37], v[162:165], v[138:141], v[34:37]
	ds_read_b128 v[210:213], v241 offset:0
	v_mfma_f32_16x16x32_bf16 v[38:41], v[166:169], v[138:141], v[38:41]
	ds_read_b128 v[214:217], v241 offset:256
	v_mfma_f32_16x16x32_bf16 v[42:45], v[170:173], v[138:141], v[42:45]
	ds_read_b128 v[218:221], v241 offset:2048
	global_load_lds_dwordx4 v226, s[54:55] offset:2048
	v_mfma_f32_16x16x32_bf16 v[46:49], v[174:177], v[138:141], v[46:49]
	ds_read_b128 v[222:225], v241 offset:2304
	v_mfma_f32_16x16x32_bf16 v[50:53], v[162:165], v[142:145], v[50:53]
	ds_read_b128 v[178:181], v240 offset:0
	v_mfma_f32_16x16x32_bf16 v[54:57], v[166:169], v[142:145], v[54:57]
	ds_read_b128 v[182:185], v240 offset:1024
	v_mfma_f32_16x16x32_bf16 v[58:61], v[170:173], v[142:145], v[58:61]
	ds_read_b128 v[186:189], v240 offset:2048
	v_mfma_f32_16x16x32_bf16 v[62:65], v[174:177], v[142:145], v[62:65]
	ds_read_b128 v[190:193], v240 offset:3072
	global_load_lds_dwordx4 v226, s[54:55] offset:3072
	v_mfma_f32_16x16x32_bf16 v[66:69], v[162:165], v[146:149], v[66:69]
	ds_read_b128 v[194:197], v240 offset:4096
	v_mfma_f32_16x16x32_bf16 v[70:73], v[166:169], v[146:149], v[70:73]
	ds_read_b128 v[198:201], v240 offset:5120
	v_mfma_f32_16x16x32_bf16 v[74:77], v[170:173], v[146:149], v[74:77]
	ds_read_b128 v[202:205], v240 offset:6144
	v_mfma_f32_16x16x32_bf16 v[78:81], v[174:177], v[146:149], v[78:81]
	ds_read_b128 v[206:209], v240 offset:7168
	s_add_i32 m0, s60, s63
	v_mfma_f32_16x16x32_bf16 v[82:85], v[162:165], v[150:153], v[82:85]
	global_load_lds_dwordx4 v230, s[56:57]
	v_mfma_f32_16x16x32_bf16 v[86:89], v[166:169], v[150:153], v[86:89]
	v_mfma_f32_16x16x32_bf16 v[90:93], v[170:173], v[150:153], v[90:93]
	v_mfma_f32_16x16x32_bf16 v[94:97], v[174:177], v[150:153], v[94:97]
	v_mfma_f32_16x16x32_bf16 v[98:101], v[162:165], v[154:157], v[98:101]
	v_mfma_f32_16x16x32_bf16 v[102:105], v[166:169], v[154:157], v[102:105]
	global_load_lds_dwordx4 v231, s[56:57] offset:1024
	v_mfma_f32_16x16x32_bf16 v[106:109], v[170:173], v[154:157], v[106:109]
	v_mfma_f32_16x16x32_bf16 v[110:113], v[174:177], v[154:157], v[110:113]
	v_mfma_f32_16x16x32_bf16 v[114:117], v[162:165], v[158:161], v[114:117]
	v_mfma_f32_16x16x32_bf16 v[118:121], v[166:169], v[158:161], v[118:121]
	v_mfma_f32_16x16x32_bf16 v[122:125], v[170:173], v[158:161], v[122:125]
	v_mfma_f32_16x16x32_bf16 v[126:129], v[174:177], v[158:161], v[126:129]
	s_setprio 0
	s_add_i32 s60, s60, 0x6000
	s_cmp_eq_u32 s60, 0x12000
	s_cselect_b32 s60, 0, s60
	s_add_u32 s54, s54, s72
	s_addc_u32 s55, s55, 0
	s_add_u32 s56, s56, s73
	s_addc_u32 s57, s57, 0
	s_add_i32 s61, s61, 0x6000
	s_cmp_eq_u32 s61, 0x12000
	s_cselect_b32 s61, 0, s61
	s_waitcnt vmcnt(6) lgkmcnt(0)
	s_barrier
	v_add_u32_e32 v240, s61, v238
	v_add_u32_e32 v241, s61, v239
	s_setprio 1
	v_mfma_f32_16x16x32_bf16 v[2:5], v[210:213], v[178:181], v[2:5]
	v_mfma_f32_16x16x32_bf16 v[6:9], v[214:217], v[178:181], v[6:9]
	v_mfma_f32_16x16x32_bf16 v[10:13], v[218:221], v[178:181], v[10:13]
	v_mfma_f32_16x16x32_bf16 v[14:17], v[222:225], v[178:181], v[14:17]
	v_mfma_f32_16x16x32_bf16 v[18:21], v[210:213], v[182:185], v[18:21]
	v_mfma_f32_16x16x32_bf16 v[22:25], v[214:217], v[182:185], v[22:25]
	v_mfma_f32_16x16x32_bf16 v[26:29], v[218:221], v[182:185], v[26:29]
	v_mfma_f32_16x16x32_bf16 v[30:33], v[222:225], v[182:185], v[30:33]
	v_mfma_f32_16x16x32_bf16 v[34:37], v[210:213], v[186:189], v[34:37]
	ds_read_b128 v[162:165], v241 offset:0
	v_mfma_f32_16x16x32_bf16 v[38:41], v[214:217], v[186:189], v[38:41]
	ds_read_b128 v[166:169], v241 offset:256
	v_mfma_f32_16x16x32_bf16 v[42:45], v[218:221], v[186:189], v[42:45]
	ds_read_b128 v[170:173], v241 offset:2048
	v_mfma_f32_16x16x32_bf16 v[46:49], v[222:225], v[186:189], v[46:49]
	ds_read_b128 v[174:177], v241 offset:2304
	v_mfma_f32_16x16x32_bf16 v[50:53], v[210:213], v[190:193], v[50:53]
	ds_read_b128 v[130:133], v240 offset:0
	v_mfma_f32_16x16x32_bf16 v[54:57], v[214:217], v[190:193], v[54:57]
	ds_read_b128 v[134:137], v240 offset:1024
	v_mfma_f32_16x16x32_bf16 v[58:61], v[218:221], v[190:193], v[58:61]
	ds_read_b128 v[138:141], v240 offset:2048
	v_mfma_f32_16x16x32_bf16 v[62:65], v[222:225], v[190:193], v[62:65]
	ds_read_b128 v[142:145], v240 offset:3072
	v_mfma_f32_16x16x32_bf16 v[66:69], v[210:213], v[194:197], v[66:69]
	ds_read_b128 v[146:149], v240 offset:4096
	v_mfma_f32_16x16x32_bf16 v[70:73], v[214:217], v[194:197], v[70:73]
	ds_read_b128 v[150:153], v240 offset:5120
	v_mfma_f32_16x16x32_bf16 v[74:77], v[218:221], v[194:197], v[74:77]
	ds_read_b128 v[154:157], v240 offset:6144
	v_mfma_f32_16x16x32_bf16 v[78:81], v[222:225], v[194:197], v[78:81]
	ds_read_b128 v[158:161], v240 offset:7168
	v_mfma_f32_16x16x32_bf16 v[82:85], v[210:213], v[198:201], v[82:85]
	v_mfma_f32_16x16x32_bf16 v[86:89], v[214:217], v[198:201], v[86:89]
	v_mfma_f32_16x16x32_bf16 v[90:93], v[218:221], v[198:201], v[90:93]
	v_mfma_f32_16x16x32_bf16 v[94:97], v[222:225], v[198:201], v[94:97]
	v_mfma_f32_16x16x32_bf16 v[98:101], v[210:213], v[202:205], v[98:101]
	v_mfma_f32_16x16x32_bf16 v[102:105], v[214:217], v[202:205], v[102:105]
	v_mfma_f32_16x16x32_bf16 v[106:109], v[218:221], v[202:205], v[106:109]
	v_mfma_f32_16x16x32_bf16 v[110:113], v[222:225], v[202:205], v[110:113]
	v_mfma_f32_16x16x32_bf16 v[114:117], v[210:213], v[206:209], v[114:117]
	v_mfma_f32_16x16x32_bf16 v[118:121], v[214:217], v[206:209], v[118:121]
	v_mfma_f32_16x16x32_bf16 v[122:125], v[218:221], v[206:209], v[122:125]
	v_mfma_f32_16x16x32_bf16 v[126:129], v[222:225], v[206:209], v[126:129]
	s_setprio 0
	s_add_i32 s61, s61, 0x6000
	s_cmp_eq_u32 s61, 0x12000
	s_cselect_b32 s61, 0, s61
	s_waitcnt vmcnt(0) lgkmcnt(0)
	s_barrier
	v_add_u32_e32 v240, s61, v238
	v_add_u32_e32 v241, s61, v239
	s_setprio 1
	v_mfma_f32_16x16x32_bf16 v[2:5], v[162:165], v[130:133], v[2:5]
	v_mfma_f32_16x16x32_bf16 v[6:9], v[166:169], v[130:133], v[6:9]
	v_mfma_f32_16x16x32_bf16 v[10:13], v[170:173], v[130:133], v[10:13]
	v_mfma_f32_16x16x32_bf16 v[14:17], v[174:177], v[130:133], v[14:17]
	v_mfma_f32_16x16x32_bf16 v[18:21], v[162:165], v[134:137], v[18:21]
	v_mfma_f32_16x16x32_bf16 v[22:25], v[166:169], v[134:137], v[22:25]
	v_mfma_f32_16x16x32_bf16 v[26:29], v[170:173], v[134:137], v[26:29]
	v_mfma_f32_16x16x32_bf16 v[30:33], v[174:177], v[134:137], v[30:33]
	v_mfma_f32_16x16x32_bf16 v[34:37], v[162:165], v[138:141], v[34:37]
	ds_read_b128 v[210:213], v241 offset:0
	v_mfma_f32_16x16x32_bf16 v[38:41], v[166:169], v[138:141], v[38:41]
	ds_read_b128 v[214:217], v241 offset:256
	v_mfma_f32_16x16x32_bf16 v[42:45], v[170:173], v[138:141], v[42:45]
	ds_read_b128 v[218:221], v241 offset:2048
	v_mfma_f32_16x16x32_bf16 v[46:49], v[174:177], v[138:141], v[46:49]
	ds_read_b128 v[222:225], v241 offset:2304
	v_mfma_f32_16x16x32_bf16 v[50:53], v[162:165], v[142:145], v[50:53]
	ds_read_b128 v[178:181], v240 offset:0
	v_mfma_f32_16x16x32_bf16 v[54:57], v[166:169], v[142:145], v[54:57]
	ds_read_b128 v[182:185], v240 offset:1024
	v_mfma_f32_16x16x32_bf16 v[58:61], v[170:173], v[142:145], v[58:61]
	ds_read_b128 v[186:189], v240 offset:2048
	v_mfma_f32_16x16x32_bf16 v[62:65], v[174:177], v[142:145], v[62:65]
	ds_read_b128 v[190:193], v240 offset:3072
	v_mfma_f32_16x16x32_bf16 v[66:69], v[162:165], v[146:149], v[66:69]
	ds_read_b128 v[194:197], v240 offset:4096
	v_mfma_f32_16x16x32_bf16 v[70:73], v[166:169], v[146:149], v[70:73]
	ds_read_b128 v[198:201], v240 offset:5120
	v_mfma_f32_16x16x32_bf16 v[74:77], v[170:173], v[146:149], v[74:77]
	ds_read_b128 v[202:205], v240 offset:6144
	v_mfma_f32_16x16x32_bf16 v[78:81], v[174:177], v[146:149], v[78:81]
	ds_read_b128 v[206:209], v240 offset:7168
	v_mfma_f32_16x16x32_bf16 v[82:85], v[162:165], v[150:153], v[82:85]
	v_mfma_f32_16x16x32_bf16 v[86:89], v[166:169], v[150:153], v[86:89]
	v_mfma_f32_16x16x32_bf16 v[90:93], v[170:173], v[150:153], v[90:93]
	v_mfma_f32_16x16x32_bf16 v[94:97], v[174:177], v[150:153], v[94:97]
	v_mfma_f32_16x16x32_bf16 v[98:101], v[162:165], v[154:157], v[98:101]
	v_mfma_f32_16x16x32_bf16 v[102:105], v[166:169], v[154:157], v[102:105]
	v_mfma_f32_16x16x32_bf16 v[106:109], v[170:173], v[154:157], v[106:109]
	v_mfma_f32_16x16x32_bf16 v[110:113], v[174:177], v[154:157], v[110:113]
	v_mfma_f32_16x16x32_bf16 v[114:117], v[162:165], v[158:161], v[114:117]
	v_mfma_f32_16x16x32_bf16 v[118:121], v[166:169], v[158:161], v[118:121]
	v_mfma_f32_16x16x32_bf16 v[122:125], v[170:173], v[158:161], v[122:125]
	v_mfma_f32_16x16x32_bf16 v[126:129], v[174:177], v[158:161], v[126:129]
	s_setprio 0
	s_add_i32 s61, s61, 0x6000
	s_cmp_eq_u32 s61, 0x12000
	s_cselect_b32 s61, 0, s61
	s_waitcnt lgkmcnt(0)
	s_barrier
	s_setprio 1
	v_mfma_f32_16x16x32_bf16 v[2:5], v[210:213], v[178:181], v[2:5]
	v_mfma_f32_16x16x32_bf16 v[6:9], v[214:217], v[178:181], v[6:9]
	v_mfma_f32_16x16x32_bf16 v[10:13], v[218:221], v[178:181], v[10:13]
	v_mfma_f32_16x16x32_bf16 v[14:17], v[222:225], v[178:181], v[14:17]
	v_mfma_f32_16x16x32_bf16 v[18:21], v[210:213], v[182:185], v[18:21]
	v_mfma_f32_16x16x32_bf16 v[22:25], v[214:217], v[182:185], v[22:25]
	v_mfma_f32_16x16x32_bf16 v[26:29], v[218:221], v[182:185], v[26:29]
	v_mfma_f32_16x16x32_bf16 v[30:33], v[222:225], v[182:185], v[30:33]
	v_mfma_f32_16x16x32_bf16 v[34:37], v[210:213], v[186:189], v[34:37]
	v_mfma_f32_16x16x32_bf16 v[38:41], v[214:217], v[186:189], v[38:41]
	v_mfma_f32_16x16x32_bf16 v[42:45], v[218:221], v[186:189], v[42:45]
	v_mfma_f32_16x16x32_bf16 v[46:49], v[222:225], v[186:189], v[46:49]
	v_mfma_f32_16x16x32_bf16 v[50:53], v[210:213], v[190:193], v[50:53]
	v_mfma_f32_16x16x32_bf16 v[54:57], v[214:217], v[190:193], v[54:57]
	v_mfma_f32_16x16x32_bf16 v[58:61], v[218:221], v[190:193], v[58:61]
	v_mfma_f32_16x16x32_bf16 v[62:65], v[222:225], v[190:193], v[62:65]
	v_mfma_f32_16x16x32_bf16 v[66:69], v[210:213], v[194:197], v[66:69]
	v_mfma_f32_16x16x32_bf16 v[70:73], v[214:217], v[194:197], v[70:73]
	v_mfma_f32_16x16x32_bf16 v[74:77], v[218:221], v[194:197], v[74:77]
	v_mfma_f32_16x16x32_bf16 v[78:81], v[222:225], v[194:197], v[78:81]
	v_mfma_f32_16x16x32_bf16 v[82:85], v[210:213], v[198:201], v[82:85]
	v_mfma_f32_16x16x32_bf16 v[86:89], v[214:217], v[198:201], v[86:89]
	v_mfma_f32_16x16x32_bf16 v[90:93], v[218:221], v[198:201], v[90:93]
	v_mfma_f32_16x16x32_bf16 v[94:97], v[222:225], v[198:201], v[94:97]
	v_mfma_f32_16x16x32_bf16 v[98:101], v[210:213], v[202:205], v[98:101]
	v_mfma_f32_16x16x32_bf16 v[102:105], v[214:217], v[202:205], v[102:105]
	v_mfma_f32_16x16x32_bf16 v[106:109], v[218:221], v[202:205], v[106:109]
	v_mfma_f32_16x16x32_bf16 v[110:113], v[222:225], v[202:205], v[110:113]
	v_mfma_f32_16x16x32_bf16 v[114:117], v[210:213], v[206:209], v[114:117]
	v_mfma_f32_16x16x32_bf16 v[118:121], v[214:217], v[206:209], v[118:121]
	v_mfma_f32_16x16x32_bf16 v[122:125], v[218:221], v[206:209], v[122:125]
	v_mfma_f32_16x16x32_bf16 v[126:129], v[222:225], v[206:209], v[126:129]
	s_setprio 0
	s_and_b32 s39, s35, 0xfff
	s_lshr_b32 s21, s36, 7
	s_waitcnt vmcnt(0)
	v_mbcnt_lo_u32_b32 v217, -1, 0
	v_mbcnt_hi_u32_b32 v217, -1, v217
	v_lshlrev_b32_e32 v217, 5, v217
	s_lshl_b32 s26, s43, 11
	v_add_u32_e32 v248, s26, v217
	s_add_i32 s26, s26, 0x12010
	v_add_u32_e32 v217, s26, v217
	s_cmp_eq_u32 s42, 0
	s_cbranch_scc0 .Lup_el_nowr
	ds_write_b128 v217, v[114:117]
	ds_write_b128 v217, v[118:121] offset:16
	s_branch .Lup_el_wrd

.Lpj_nn_a:
	s_waitcnt vmcnt(6) lgkmcnt(0)
	s_barrier
	v_add_u32_e32 v240, s61, v238
	v_add_u32_e32 v241, s61, v239
	s_setprio 1
	s_add_i32 m0, s60, s62
	v_mfma_f32_16x16x32_bf16 v[2:5], v[162:165], v[130:133], 0
	global_load_lds_dwordx4 v226, s[54:55]
	v_mfma_f32_16x16x32_bf16 v[6:9], v[166:169], v[130:133], 0
	v_mfma_f32_16x16x32_bf16 v[10:13], v[170:173], v[130:133], 0
	v_mfma_f32_16x16x32_bf16 v[14:17], v[174:177], v[130:133], 0
	v_mfma_f32_16x16x32_bf16 v[18:21], v[162:165], v[134:137], 0
	v_mfma_f32_16x16x32_bf16 v[22:25], v[166:169], v[134:137], 0
	global_load_lds_dwordx4 v226, s[54:55] offset:1024
	v_mfma_f32_16x16x32_bf16 v[26:29], v[170:173], v[134:137], 0
	v_mfma_f32_16x16x32_bf16 v[30:33], v[174:177], v[134:137], 0
	v_mfma_f32_16x16x32_bf16 v[34:37], v[162:165], v[138:141], 0
	ds_read_b128 v[210:213], v241 offset:0
	v_mfma_f32_16x16x32_bf16 v[38:41], v[166:169], v[138:141], 0
	ds_read_b128 v[214:217], v241 offset:256
	v_mfma_f32_16x16x32_bf16 v[42:45], v[170:173], v[138:141], 0
	ds_read_b128 v[218:221], v241 offset:2048
	global_load_lds_dwordx4 v226, s[54:55] offset:2048
	v_mfma_f32_16x16x32_bf16 v[46:49], v[174:177], v[138:141], 0
	ds_read_b128 v[222:225], v241 offset:2304
	v_mfma_f32_16x16x32_bf16 v[50:53], v[162:165], v[142:145], 0
	ds_read_b128 v[178:181], v240 offset:0
	v_mfma_f32_16x16x32_bf16 v[54:57], v[166:169], v[142:145], 0
	ds_read_b128 v[182:185], v240 offset:1024
	v_mfma_f32_16x16x32_bf16 v[58:61], v[170:173], v[142:145], 0
	ds_read_b128 v[186:189], v240 offset:2048
	v_mfma_f32_16x16x32_bf16 v[62:65], v[174:177], v[142:145], 0
	ds_read_b128 v[190:193], v240 offset:3072
	global_load_lds_dwordx4 v226, s[54:55] offset:3072
	v_mfma_f32_16x16x32_bf16 v[66:69], v[162:165], v[146:149], 0
	ds_read_b128 v[194:197], v240 offset:4096
	v_mfma_f32_16x16x32_bf16 v[70:73], v[166:169], v[146:149], 0
	ds_read_b128 v[198:201], v240 offset:5120
	v_mfma_f32_16x16x32_bf16 v[74:77], v[170:173], v[146:149], 0
	ds_read_b128 v[202:205], v240 offset:6144
	v_mfma_f32_16x16x32_bf16 v[78:81], v[174:177], v[146:149], 0
	ds_read_b128 v[206:209], v240 offset:7168
	s_add_i32 m0, s60, s63
	v_mfma_f32_16x16x32_bf16 v[82:85], v[162:165], v[150:153], 0
	global_load_lds_dwordx4 v230, s[56:57]
	v_mfma_f32_16x16x32_bf16 v[86:89], v[166:169], v[150:153], 0
	v_mfma_f32_16x16x32_bf16 v[90:93], v[170:173], v[150:153], 0
	v_mfma_f32_16x16x32_bf16 v[94:97], v[174:177], v[150:153], 0
	v_mfma_f32_16x16x32_bf16 v[98:101], v[162:165], v[154:157], 0
	v_mfma_f32_16x16x32_bf16 v[102:105], v[166:169], v[154:157], 0
	global_load_lds_dwordx4 v231, s[56:57] offset:1024
	v_mfma_f32_16x16x32_bf16 v[106:109], v[170:173], v[154:157], 0
	v_mfma_f32_16x16x32_bf16 v[110:113], v[174:177], v[154:157], 0
	v_mfma_f32_16x16x32_bf16 v[114:117], v[162:165], v[158:161], 0
	v_mfma_f32_16x16x32_bf16 v[118:121], v[166:169], v[158:161], 0
	v_mfma_f32_16x16x32_bf16 v[122:125], v[170:173], v[158:161], 0
	v_mfma_f32_16x16x32_bf16 v[126:129], v[174:177], v[158:161], 0
	s_setprio 0
	s_add_i32 s60, s60, 0x6000
	s_cmp_eq_u32 s60, 0x12000
	s_cselect_b32 s60, 0, s60
	s_add_u32 s54, s54, s72
	s_addc_u32 s55, s55, 0
	s_add_u32 s56, s56, s73
	s_addc_u32 s57, s57, 0
	s_add_i32 s61, s61, 0x6000
	s_cmp_eq_u32 s61, 0x12000
	s_cselect_b32 s61, 0, s61
	s_waitcnt vmcnt(6) lgkmcnt(0)
	s_barrier
	v_add_u32_e32 v240, s61, v238
	v_add_u32_e32 v241, s61, v239
	s_setprio 1
	s_add_i32 m0, s60, s62
	v_mfma_f32_16x16x32_bf16 v[2:5], v[210:213], v[178:181], v[2:5]
	global_load_lds_dwordx4 v226, s[54:55]
	v_mfma_f32_16x16x32_bf16 v[6:9], v[214:217], v[178:181], v[6:9]
	v_mfma_f32_16x16x32_bf16 v[10:13], v[218:221], v[178:181], v[10:13]
	v_mfma_f32_16x16x32_bf16 v[14:17], v[222:225], v[178:181], v[14:17]
	v_mfma_f32_16x16x32_bf16 v[18:21], v[210:213], v[182:185], v[18:21]
	v_mfma_f32_16x16x32_bf16 v[22:25], v[214:217], v[182:185], v[22:25]
	global_load_lds_dwordx4 v226, s[54:55] offset:1024
	v_mfma_f32_16x16x32_bf16 v[26:29], v[218:221], v[182:185], v[26:29]
	v_mfma_f32_16x16x32_bf16 v[30:33], v[222:225], v[182:185], v[30:33]
	v_mfma_f32_16x16x32_bf16 v[34:37], v[210:213], v[186:189], v[34:37]
	ds_read_b128 v[162:165], v241 offset:0
	v_mfma_f32_16x16x32_bf16 v[38:41], v[214:217], v[186:189], v[38:41]
	ds_read_b128 v[166:169], v241 offset:256
	v_mfma_f32_16x16x32_bf16 v[42:45], v[218:221], v[186:189], v[42:45]
	ds_read_b128 v[170:173], v241 offset:2048
	global_load_lds_dwordx4 v226, s[54:55] offset:2048
	v_mfma_f32_16x16x32_bf16 v[46:49], v[222:225], v[186:189], v[46:49]
	ds_read_b128 v[174:177], v241 offset:2304
	v_mfma_f32_16x16x32_bf16 v[50:53], v[210:213], v[190:193], v[50:53]
	ds_read_b128 v[130:133], v240 offset:0
	v_mfma_f32_16x16x32_bf16 v[54:57], v[214:217], v[190:193], v[54:57]
	ds_read_b128 v[134:137], v240 offset:1024
	v_mfma_f32_16x16x32_bf16 v[58:61], v[218:221], v[190:193], v[58:61]
	ds_read_b128 v[138:141], v240 offset:2048
	v_mfma_f32_16x16x32_bf16 v[62:65], v[222:225], v[190:193], v[62:65]
	ds_read_b128 v[142:145], v240 offset:3072
	global_load_lds_dwordx4 v226, s[54:55] offset:3072
	v_mfma_f32_16x16x32_bf16 v[66:69], v[210:213], v[194:197], v[66:69]
	ds_read_b128 v[146:149], v240 offset:4096
	v_mfma_f32_16x16x32_bf16 v[70:73], v[214:217], v[194:197], v[70:73]
	ds_read_b128 v[150:153], v240 offset:5120
	v_mfma_f32_16x16x32_bf16 v[74:77], v[218:221], v[194:197], v[74:77]
	ds_read_b128 v[154:157], v240 offset:6144
	v_mfma_f32_16x16x32_bf16 v[78:81], v[222:225], v[194:197], v[78:81]
	ds_read_b128 v[158:161], v240 offset:7168
	s_add_i32 m0, s60, s63
	v_mfma_f32_16x16x32_bf16 v[82:85], v[210:213], v[198:201], v[82:85]
	global_load_lds_dwordx4 v230, s[56:57]
	v_mfma_f32_16x16x32_bf16 v[86:89], v[214:217], v[198:201], v[86:89]
	v_mfma_f32_16x16x32_bf16 v[90:93], v[218:221], v[198:201], v[90:93]
	v_mfma_f32_16x16x32_bf16 v[94:97], v[222:225], v[198:201], v[94:97]
	v_mfma_f32_16x16x32_bf16 v[98:101], v[210:213], v[202:205], v[98:101]
	v_mfma_f32_16x16x32_bf16 v[102:105], v[214:217], v[202:205], v[102:105]
	global_load_lds_dwordx4 v231, s[56:57] offset:1024
	v_mfma_f32_16x16x32_bf16 v[106:109], v[218:221], v[202:205], v[106:109]
	v_mfma_f32_16x16x32_bf16 v[110:113], v[222:225], v[202:205], v[110:113]
	v_mfma_f32_16x16x32_bf16 v[114:117], v[210:213], v[206:209], v[114:117]
	v_mfma_f32_16x16x32_bf16 v[118:121], v[214:217], v[206:209], v[118:121]
	v_mfma_f32_16x16x32_bf16 v[122:125], v[218:221], v[206:209], v[122:125]
	v_mfma_f32_16x16x32_bf16 v[126:129], v[222:225], v[206:209], v[126:129]
	s_setprio 0
	s_add_i32 s60, s60, 0x6000
	s_cmp_eq_u32 s60, 0x12000
	s_cselect_b32 s60, 0, s60
	s_add_u32 s54, s54, s72
	s_addc_u32 s55, s55, 0
	s_add_u32 s56, s56, s73
	s_addc_u32 s57, s57, 0
	s_add_i32 s61, s61, 0x6000
	s_cmp_eq_u32 s61, 0x12000
	s_cselect_b32 s61, 0, s61
	s_branch .Lpj_main

.Lpj_nn_b:
	s_waitcnt vmcnt(63) lgkmcnt(0)
	s_barrier
	v_add_u32_e32 v240, s61, v238
	v_add_u32_e32 v241, s61, v239
	s_setprio 1
	s_add_i32 m0, s60, s62
	v_mfma_f32_16x16x32_bf16 v[2:5], v[162:165], v[130:133], 0
	global_load_lds_dwordx4 v226, s[54:55]
	v_mfma_f32_16x16x32_bf16 v[6:9], v[166:169], v[130:133], 0
	v_mfma_f32_16x16x32_bf16 v[10:13], v[170:173], v[130:133], 0
	v_mfma_f32_16x16x32_bf16 v[14:17], v[174:177], v[130:133], 0
	v_mfma_f32_16x16x32_bf16 v[18:21], v[162:165], v[134:137], 0
	v_mfma_f32_16x16x32_bf16 v[22:25], v[166:169], v[134:137], 0
	global_load_lds_dwordx4 v226, s[54:55] offset:1024
	v_mfma_f32_16x16x32_bf16 v[26:29], v[170:173], v[134:137], 0
	v_mfma_f32_16x16x32_bf16 v[30:33], v[174:177], v[134:137], 0
	v_mfma_f32_16x16x32_bf16 v[34:37], v[162:165], v[138:141], 0
	ds_read_b128 v[210:213], v241 offset:0
	v_mfma_f32_16x16x32_bf16 v[38:41], v[166:169], v[138:141], 0
	ds_read_b128 v[214:217], v241 offset:256
	v_mfma_f32_16x16x32_bf16 v[42:45], v[170:173], v[138:141], 0
	ds_read_b128 v[218:221], v241 offset:2048
	global_load_lds_dwordx4 v226, s[54:55] offset:2048
	v_mfma_f32_16x16x32_bf16 v[46:49], v[174:177], v[138:141], 0
	ds_read_b128 v[222:225], v241 offset:2304
	v_mfma_f32_16x16x32_bf16 v[50:53], v[162:165], v[142:145], 0
	ds_read_b128 v[178:181], v240 offset:0
	v_mfma_f32_16x16x32_bf16 v[54:57], v[166:169], v[142:145], 0
	ds_read_b128 v[182:185], v240 offset:1024
	v_mfma_f32_16x16x32_bf16 v[58:61], v[170:173], v[142:145], 0
	ds_read_b128 v[186:189], v240 offset:2048
	v_mfma_f32_16x16x32_bf16 v[62:65], v[174:177], v[142:145], 0
	ds_read_b128 v[190:193], v240 offset:3072
	global_load_lds_dwordx4 v226, s[54:55] offset:3072
	v_mfma_f32_16x16x32_bf16 v[66:69], v[162:165], v[146:149], 0
	ds_read_b128 v[194:197], v240 offset:4096
	v_mfma_f32_16x16x32_bf16 v[70:73], v[166:169], v[146:149], 0
	ds_read_b128 v[198:201], v240 offset:5120
	v_mfma_f32_16x16x32_bf16 v[74:77], v[170:173], v[146:149], 0
	ds_read_b128 v[202:205], v240 offset:6144
	v_mfma_f32_16x16x32_bf16 v[78:81], v[174:177], v[146:149], 0
	ds_read_b128 v[206:209], v240 offset:7168
	s_add_i32 m0, s60, s63
	v_mfma_f32_16x16x32_bf16 v[82:85], v[162:165], v[150:153], 0
	global_load_lds_dwordx4 v230, s[56:57]
	v_mfma_f32_16x16x32_bf16 v[86:89], v[166:169], v[150:153], 0
	v_mfma_f32_16x16x32_bf16 v[90:93], v[170:173], v[150:153], 0
	v_mfma_f32_16x16x32_bf16 v[94:97], v[174:177], v[150:153], 0
	v_mfma_f32_16x16x32_bf16 v[98:101], v[162:165], v[154:157], 0
	v_mfma_f32_16x16x32_bf16 v[102:105], v[166:169], v[154:157], 0
	global_load_lds_dwordx4 v231, s[56:57] offset:1024
	v_mfma_f32_16x16x32_bf16 v[106:109], v[170:173], v[154:157], 0
	v_mfma_f32_16x16x32_bf16 v[110:113], v[174:177], v[154:157], 0
	v_mfma_f32_16x16x32_bf16 v[114:117], v[162:165], v[158:161], 0
	v_mfma_f32_16x16x32_bf16 v[118:121], v[166:169], v[158:161], 0
	v_mfma_f32_16x16x32_bf16 v[122:125], v[170:173], v[158:161], 0
	v_mfma_f32_16x16x32_bf16 v[126:129], v[174:177], v[158:161], 0
	s_setprio 0
	s_add_i32 s60, s60, 0x6000
	s_cmp_eq_u32 s60, 0x12000
	s_cselect_b32 s60, 0, s60
	s_add_u32 s54, s54, s72
	s_addc_u32 s55, s55, 0
	s_add_u32 s56, s56, s73
	s_addc_u32 s57, s57, 0
	s_add_i32 s61, s61, 0x6000
	s_cmp_eq_u32 s61, 0x12000
	s_cselect_b32 s61, 0, s61
	s_waitcnt vmcnt(63) lgkmcnt(0)
	s_barrier
	v_add_u32_e32 v240, s61, v238
	v_add_u32_e32 v241, s61, v239
	s_setprio 1
	s_add_i32 m0, s60, s62
	v_mfma_f32_16x16x32_bf16 v[2:5], v[210:213], v[178:181], v[2:5]
	global_load_lds_dwordx4 v226, s[54:55]
	v_mfma_f32_16x16x32_bf16 v[6:9], v[214:217], v[178:181], v[6:9]
	v_mfma_f32_16x16x32_bf16 v[10:13], v[218:221], v[178:181], v[10:13]
	v_mfma_f32_16x16x32_bf16 v[14:17], v[222:225], v[178:181], v[14:17]
	v_mfma_f32_16x16x32_bf16 v[18:21], v[210:213], v[182:185], v[18:21]
	v_mfma_f32_16x16x32_bf16 v[22:25], v[214:217], v[182:185], v[22:25]
	global_load_lds_dwordx4 v226, s[54:55] offset:1024
	v_mfma_f32_16x16x32_bf16 v[26:29], v[218:221], v[182:185], v[26:29]
	v_mfma_f32_16x16x32_bf16 v[30:33], v[222:225], v[182:185], v[30:33]
	v_mfma_f32_16x16x32_bf16 v[34:37], v[210:213], v[186:189], v[34:37]
	ds_read_b128 v[162:165], v241 offset:0
	v_mfma_f32_16x16x32_bf16 v[38:41], v[214:217], v[186:189], v[38:41]
	ds_read_b128 v[166:169], v241 offset:256
	v_mfma_f32_16x16x32_bf16 v[42:45], v[218:221], v[186:189], v[42:45]
	ds_read_b128 v[170:173], v241 offset:2048
	global_load_lds_dwordx4 v226, s[54:55] offset:2048
	v_mfma_f32_16x16x32_bf16 v[46:49], v[222:225], v[186:189], v[46:49]
	ds_read_b128 v[174:177], v241 offset:2304
	v_mfma_f32_16x16x32_bf16 v[50:53], v[210:213], v[190:193], v[50:53]
	ds_read_b128 v[130:133], v240 offset:0
	v_mfma_f32_16x16x32_bf16 v[54:57], v[214:217], v[190:193], v[54:57]
	ds_read_b128 v[134:137], v240 offset:1024
	v_mfma_f32_16x16x32_bf16 v[58:61], v[218:221], v[190:193], v[58:61]
	ds_read_b128 v[138:141], v240 offset:2048
	v_mfma_f32_16x16x32_bf16 v[62:65], v[222:225], v[190:193], v[62:65]
	ds_read_b128 v[142:145], v240 offset:3072
	global_load_lds_dwordx4 v226, s[54:55] offset:3072
	v_mfma_f32_16x16x32_bf16 v[66:69], v[210:213], v[194:197], v[66:69]
	ds_read_b128 v[146:149], v240 offset:4096
	v_mfma_f32_16x16x32_bf16 v[70:73], v[214:217], v[194:197], v[70:73]
	ds_read_b128 v[150:153], v240 offset:5120
	v_mfma_f32_16x16x32_bf16 v[74:77], v[218:221], v[194:197], v[74:77]
	ds_read_b128 v[154:157], v240 offset:6144
	v_mfma_f32_16x16x32_bf16 v[78:81], v[222:225], v[194:197], v[78:81]
	ds_read_b128 v[158:161], v240 offset:7168
	s_add_i32 m0, s60, s63
	v_mfma_f32_16x16x32_bf16 v[82:85], v[210:213], v[198:201], v[82:85]
	global_load_lds_dwordx4 v230, s[56:57]
	v_mfma_f32_16x16x32_bf16 v[86:89], v[214:217], v[198:201], v[86:89]
	v_mfma_f32_16x16x32_bf16 v[90:93], v[218:221], v[198:201], v[90:93]
	v_mfma_f32_16x16x32_bf16 v[94:97], v[222:225], v[198:201], v[94:97]
	v_mfma_f32_16x16x32_bf16 v[98:101], v[210:213], v[202:205], v[98:101]
	v_mfma_f32_16x16x32_bf16 v[102:105], v[214:217], v[202:205], v[102:105]
	global_load_lds_dwordx4 v231, s[56:57] offset:1024
	v_mfma_f32_16x16x32_bf16 v[106:109], v[218:221], v[202:205], v[106:109]
	v_mfma_f32_16x16x32_bf16 v[110:113], v[222:225], v[202:205], v[110:113]
	v_mfma_f32_16x16x32_bf16 v[114:117], v[210:213], v[206:209], v[114:117]
	v_mfma_f32_16x16x32_bf16 v[118:121], v[214:217], v[206:209], v[118:121]
	v_mfma_f32_16x16x32_bf16 v[122:125], v[218:221], v[206:209], v[122:125]
	v_mfma_f32_16x16x32_bf16 v[126:129], v[222:225], v[206:209], v[126:129]
	s_setprio 0
	s_add_i32 s60, s60, 0x6000
	s_cmp_eq_u32 s60, 0x12000
	s_cselect_b32 s60, 0, s60
	s_add_u32 s54, s54, s72
	s_addc_u32 s55, s55, 0
	s_add_u32 s56, s56, s73
	s_addc_u32 s57, s57, 0
	s_add_i32 s61, s61, 0x6000
	s_cmp_eq_u32 s61, 0x12000
	s_cselect_b32 s61, 0, s61

.Lpj_kdone:
	s_cmp_eq_u32 s37, 0
	s_cbranch_scc1 .Lpj_tail_last
	s_waitcnt vmcnt(6) lgkmcnt(0)
	s_barrier
	v_add_u32_e32 v240, s61, v238
	v_add_u32_e32 v241, s61, v239
	s_setprio 1
	s_add_i32 m0, s60, s62
	v_mfma_f32_16x16x32_bf16 v[2:5], v[162:165], v[130:133], v[2:5]
	global_load_lds_dwordx4 v226, s[54:55]
	v_mfma_f32_16x16x32_bf16 v[6:9], v[166:169], v[130:133], v[6:9]
	v_mfma_f32_16x16x32_bf16 v[10:13], v[170:173], v[130:133], v[10:13]
	v_mfma_f32_16x16x32_bf16 v[14:17], v[174:177], v[130:133], v[14:17]
	v_mfma_f32_16x16x32_bf16 v[18:21], v[162:165], v[134:137], v[18:21]
	v_mfma_f32_16x16x32_bf16 v[22:25], v[166:169], v[134:137], v[22:25]
	global_load_lds_dwordx4 v226, s[54:55] offset:1024
	v_mfma_f32_16x16x32_bf16 v[26:29], v[170:173], v[134:137], v[26:29]
	v_mfma_f32_16x16x32_bf16 v[30:33], v[174:177], v[134:137], v[30:33]
	v_mfma_f32_16x16x32_bf16 v[34:37], v[162:165], v[138:141], v[34:37]
	ds_read_b128 v[210:213], v241 offset:0
	v_mfma_f32_16x16x32_bf16 v[38:41], v[166:169], v[138:141], v[38:41]
	ds_read_b128 v[214:217], v241 offset:256
	v_mfma_f32_16x16x32_bf16 v[42:45], v[170:173], v[138:141], v[42:45]
	ds_read_b128 v[218:221], v241 offset:2048
	global_load_lds_dwordx4 v226, s[54:55] offset:2048
	v_mfma_f32_16x16x32_bf16 v[46:49], v[174:177], v[138:141], v[46:49]
	ds_read_b128 v[222:225], v241 offset:2304
	v_mfma_f32_16x16x32_bf16 v[50:53], v[162:165], v[142:145], v[50:53]
	ds_read_b128 v[178:181], v240 offset:0
	v_mfma_f32_16x16x32_bf16 v[54:57], v[166:169], v[142:145], v[54:57]
	ds_read_b128 v[182:185], v240 offset:1024
	v_mfma_f32_16x16x32_bf16 v[58:61], v[170:173], v[142:145], v[58:61]
	ds_read_b128 v[186:189], v240 offset:2048
	v_mfma_f32_16x16x32_bf16 v[62:65], v[174:177], v[142:145], v[62:65]
	ds_read_b128 v[190:193], v240 offset:3072
	global_load_lds_dwordx4 v226, s[54:55] offset:3072
	v_mfma_f32_16x16x32_bf16 v[66:69], v[162:165], v[146:149], v[66:69]
	ds_read_b128 v[194:197], v240 offset:4096
	v_mfma_f32_16x16x32_bf16 v[70:73], v[166:169], v[146:149], v[70:73]
	ds_read_b128 v[198:201], v240 offset:5120
	v_mfma_f32_16x16x32_bf16 v[74:77], v[170:173], v[146:149], v[74:77]
	ds_read_b128 v[202:205], v240 offset:6144
	v_mfma_f32_16x16x32_bf16 v[78:81], v[174:177], v[146:149], v[78:81]
	ds_read_b128 v[206:209], v240 offset:7168
	s_add_i32 m0, s60, s63
	v_mfma_f32_16x16x32_bf16 v[82:85], v[162:165], v[150:153], v[82:85]
	global_load_lds_dwordx4 v230, s[56:57]
	v_mfma_f32_16x16x32_bf16 v[86:89], v[166:169], v[150:153], v[86:89]
	v_mfma_f32_16x16x32_bf16 v[90:93], v[170:173], v[150:153], v[90:93]
	v_mfma_f32_16x16x32_bf16 v[94:97], v[174:177], v[150:153], v[94:97]
	v_mfma_f32_16x16x32_bf16 v[98:101], v[162:165], v[154:157], v[98:101]
	v_mfma_f32_16x16x32_bf16 v[102:105], v[166:169], v[154:157], v[102:105]
	global_load_lds_dwordx4 v231, s[56:57] offset:1024
	v_mfma_f32_16x16x32_bf16 v[106:109], v[170:173], v[154:157], v[106:109]
	v_mfma_f32_16x16x32_bf16 v[110:113], v[174:177], v[154:157], v[110:113]
	v_mfma_f32_16x16x32_bf16 v[114:117], v[162:165], v[158:161], v[114:117]
	v_mfma_f32_16x16x32_bf16 v[118:121], v[166:169], v[158:161], v[118:121]
	v_mfma_f32_16x16x32_bf16 v[122:125], v[170:173], v[158:161], v[122:125]
	v_mfma_f32_16x16x32_bf16 v[126:129], v[174:177], v[158:161], v[126:129]
	s_setprio 0
	s_add_i32 s60, s60, 0x6000
	s_cmp_eq_u32 s60, 0x12000
	s_cselect_b32 s60, 0, s60
	s_add_u32 s54, s54, s72
	s_addc_u32 s55, s55, 0
	s_add_u32 s56, s56, s73
	s_addc_u32 s57, s57, 0
	s_add_i32 s61, s61, 0x6000
	s_cmp_eq_u32 s61, 0x12000
	s_cselect_b32 s61, 0, s61
	v_mov_b32_e32 v226, v232
	v_mov_b32_e32 v230, v236
	v_mov_b32_e32 v231, v237
	s_mov_b64 s[54:55], s[48:49]
	s_mov_b64 s[56:57], s[50:51]
	s_waitcnt vmcnt(6) lgkmcnt(0)
	s_barrier
	v_add_u32_e32 v240, s61, v238
	v_add_u32_e32 v241, s61, v239
	s_setprio 1
	s_add_i32 m0, s60, s62
	v_mfma_f32_16x16x32_bf16 v[2:5], v[210:213], v[178:181], v[2:5]
	global_load_lds_dwordx4 v226, s[54:55]
	v_mfma_f32_16x16x32_bf16 v[6:9], v[214:217], v[178:181], v[6:9]
	v_mfma_f32_16x16x32_bf16 v[10:13], v[218:221], v[178:181], v[10:13]
	v_mfma_f32_16x16x32_bf16 v[14:17], v[222:225], v[178:181], v[14:17]
	v_mfma_f32_16x16x32_bf16 v[18:21], v[210:213], v[182:185], v[18:21]
	v_mfma_f32_16x16x32_bf16 v[22:25], v[214:217], v[182:185], v[22:25]
	global_load_lds_dwordx4 v226, s[54:55] offset:1024
	v_mfma_f32_16x16x32_bf16 v[26:29], v[218:221], v[182:185], v[26:29]
	v_mfma_f32_16x16x32_bf16 v[30:33], v[222:225], v[182:185], v[30:33]
	v_mfma_f32_16x16x32_bf16 v[34:37], v[210:213], v[186:189], v[34:37]
	ds_read_b128 v[162:165], v241 offset:0
	v_mfma_f32_16x16x32_bf16 v[38:41], v[214:217], v[186:189], v[38:41]
	ds_read_b128 v[166:169], v241 offset:256
	v_mfma_f32_16x16x32_bf16 v[42:45], v[218:221], v[186:189], v[42:45]
	ds_read_b128 v[170:173], v241 offset:2048
	global_load_lds_dwordx4 v226, s[54:55] offset:2048
	v_mfma_f32_16x16x32_bf16 v[46:49], v[222:225], v[186:189], v[46:49]
	ds_read_b128 v[174:177], v241 offset:2304
	v_mfma_f32_16x16x32_bf16 v[50:53], v[210:213], v[190:193], v[50:53]
	ds_read_b128 v[130:133], v240 offset:0
	v_mfma_f32_16x16x32_bf16 v[54:57], v[214:217], v[190:193], v[54:57]
	ds_read_b128 v[134:137], v240 offset:1024
	v_mfma_f32_16x16x32_bf16 v[58:61], v[218:221], v[190:193], v[58:61]
	ds_read_b128 v[138:141], v240 offset:2048
	v_mfma_f32_16x16x32_bf16 v[62:65], v[222:225], v[190:193], v[62:65]
	ds_read_b128 v[142:145], v240 offset:3072
	global_load_lds_dwordx4 v226, s[54:55] offset:3072
	v_mfma_f32_16x16x32_bf16 v[66:69], v[210:213], v[194:197], v[66:69]
	ds_read_b128 v[146:149], v240 offset:4096
	v_mfma_f32_16x16x32_bf16 v[70:73], v[214:217], v[194:197], v[70:73]
	ds_read_b128 v[150:153], v240 offset:5120
	v_mfma_f32_16x16x32_bf16 v[74:77], v[218:221], v[194:197], v[74:77]
	ds_read_b128 v[154:157], v240 offset:6144
	v_mfma_f32_16x16x32_bf16 v[78:81], v[222:225], v[194:197], v[78:81]
	ds_read_b128 v[158:161], v240 offset:7168
	s_add_i32 m0, s60, s63
	v_mfma_f32_16x16x32_bf16 v[82:85], v[210:213], v[198:201], v[82:85]
	global_load_lds_dwordx4 v230, s[56:57]
	v_mfma_f32_16x16x32_bf16 v[86:89], v[214:217], v[198:201], v[86:89]
	v_mfma_f32_16x16x32_bf16 v[90:93], v[218:221], v[198:201], v[90:93]
	v_mfma_f32_16x16x32_bf16 v[94:97], v[222:225], v[198:201], v[94:97]
	v_mfma_f32_16x16x32_bf16 v[98:101], v[210:213], v[202:205], v[98:101]
	v_mfma_f32_16x16x32_bf16 v[102:105], v[214:217], v[202:205], v[102:105]
	global_load_lds_dwordx4 v231, s[56:57] offset:1024
	v_mfma_f32_16x16x32_bf16 v[106:109], v[218:221], v[202:205], v[106:109]
	v_mfma_f32_16x16x32_bf16 v[110:113], v[222:225], v[202:205], v[110:113]
	v_mfma_f32_16x16x32_bf16 v[114:117], v[210:213], v[206:209], v[114:117]
	v_mfma_f32_16x16x32_bf16 v[118:121], v[214:217], v[206:209], v[118:121]
	v_mfma_f32_16x16x32_bf16 v[122:125], v[218:221], v[206:209], v[122:125]
	v_mfma_f32_16x16x32_bf16 v[126:129], v[222:225], v[206:209], v[126:129]
	s_setprio 0
	s_add_i32 s60, s60, 0x6000
	s_cmp_eq_u32 s60, 0x12000
	s_cselect_b32 s60, 0, s60
	s_add_u32 s54, s54, s72
	s_addc_u32 s55, s55, 0
	s_add_u32 s56, s56, s73
	s_addc_u32 s57, s57, 0
	s_add_i32 s61, s61, 0x6000
	s_cmp_eq_u32 s61, 0x12000
	s_cselect_b32 s61, 0, s61
	s_waitcnt vmcnt(6) lgkmcnt(0)
	s_barrier
	v_add_u32_e32 v240, s61, v238
	v_add_u32_e32 v241, s61, v239
	s_setprio 1
	s_add_i32 m0, s60, s62
	v_mfma_f32_16x16x32_bf16 v[2:5], v[162:165], v[130:133], v[2:5]
	global_load_lds_dwordx4 v226, s[54:55]
	v_mfma_f32_16x16x32_bf16 v[6:9], v[166:169], v[130:133], v[6:9]
	v_mfma_f32_16x16x32_bf16 v[10:13], v[170:173], v[130:133], v[10:13]
	v_mfma_f32_16x16x32_bf16 v[14:17], v[174:177], v[130:133], v[14:17]
	v_mfma_f32_16x16x32_bf16 v[18:21], v[162:165], v[134:137], v[18:21]
	v_mfma_f32_16x16x32_bf16 v[22:25], v[166:169], v[134:137], v[22:25]
	global_load_lds_dwordx4 v226, s[54:55] offset:1024
	v_mfma_f32_16x16x32_bf16 v[26:29], v[170:173], v[134:137], v[26:29]
	v_mfma_f32_16x16x32_bf16 v[30:33], v[174:177], v[134:137], v[30:33]
	v_mfma_f32_16x16x32_bf16 v[34:37], v[162:165], v[138:141], v[34:37]
	ds_read_b128 v[210:213], v241 offset:0
	v_mfma_f32_16x16x32_bf16 v[38:41], v[166:169], v[138:141], v[38:41]
	ds_read_b128 v[214:217], v241 offset:256
	v_mfma_f32_16x16x32_bf16 v[42:45], v[170:173], v[138:141], v[42:45]
	ds_read_b128 v[218:221], v241 offset:2048
	global_load_lds_dwordx4 v226, s[54:55] offset:2048
	v_mfma_f32_16x16x32_bf16 v[46:49], v[174:177], v[138:141], v[46:49]
	ds_read_b128 v[222:225], v241 offset:2304
	v_mfma_f32_16x16x32_bf16 v[50:53], v[162:165], v[142:145], v[50:53]
	ds_read_b128 v[178:181], v240 offset:0
	v_mfma_f32_16x16x32_bf16 v[54:57], v[166:169], v[142:145], v[54:57]
	ds_read_b128 v[182:185], v240 offset:1024
	v_mfma_f32_16x16x32_bf16 v[58:61], v[170:173], v[142:145], v[58:61]
	ds_read_b128 v[186:189], v240 offset:2048
	v_mfma_f32_16x16x32_bf16 v[62:65], v[174:177], v[142:145], v[62:65]
	ds_read_b128 v[190:193], v240 offset:3072
	global_load_lds_dwordx4 v226, s[54:55] offset:3072
	v_mfma_f32_16x16x32_bf16 v[66:69], v[162:165], v[146:149], v[66:69]
	ds_read_b128 v[194:197], v240 offset:4096
	v_mfma_f32_16x16x32_bf16 v[70:73], v[166:169], v[146:149], v[70:73]
	ds_read_b128 v[198:201], v240 offset:5120
	v_mfma_f32_16x16x32_bf16 v[74:77], v[170:173], v[146:149], v[74:77]
	ds_read_b128 v[202:205], v240 offset:6144
	v_mfma_f32_16x16x32_bf16 v[78:81], v[174:177], v[146:149], v[78:81]
	ds_read_b128 v[206:209], v240 offset:7168
	s_add_i32 m0, s60, s63
	v_mfma_f32_16x16x32_bf16 v[82:85], v[162:165], v[150:153], v[82:85]
	global_load_lds_dwordx4 v230, s[56:57]
	v_mfma_f32_16x16x32_bf16 v[86:89], v[166:169], v[150:153], v[86:89]
	v_mfma_f32_16x16x32_bf16 v[90:93], v[170:173], v[150:153], v[90:93]
	v_mfma_f32_16x16x32_bf16 v[94:97], v[174:177], v[150:153], v[94:97]
	v_mfma_f32_16x16x32_bf16 v[98:101], v[162:165], v[154:157], v[98:101]
	v_mfma_f32_16x16x32_bf16 v[102:105], v[166:169], v[154:157], v[102:105]
	global_load_lds_dwordx4 v231, s[56:57] offset:1024
	v_mfma_f32_16x16x32_bf16 v[106:109], v[170:173], v[154:157], v[106:109]
	v_mfma_f32_16x16x32_bf16 v[110:113], v[174:177], v[154:157], v[110:113]
	v_mfma_f32_16x16x32_bf16 v[114:117], v[162:165], v[158:161], v[114:117]
	v_mfma_f32_16x16x32_bf16 v[118:121], v[166:169], v[158:161], v[118:121]
	v_mfma_f32_16x16x32_bf16 v[122:125], v[170:173], v[158:161], v[122:125]
	v_mfma_f32_16x16x32_bf16 v[126:129], v[174:177], v[158:161], v[126:129]
	s_setprio 0
	s_add_i32 s60, s60, 0x6000
	s_cmp_eq_u32 s60, 0x12000
	s_cselect_b32 s60, 0, s60
	s_add_u32 s54, s54, s72
	s_addc_u32 s55, s55, 0
	s_add_u32 s56, s56, s73
	s_addc_u32 s57, s57, 0
	s_add_i32 s61, s61, 0x6000
	s_cmp_eq_u32 s61, 0x12000
	s_cselect_b32 s61, 0, s61
	s_waitcnt vmcnt(6) lgkmcnt(0)
	s_barrier
	v_add_u32_e32 v240, s61, v238
	v_add_u32_e32 v241, s61, v239
	s_setprio 1
	s_add_i32 m0, s60, s62
	v_mfma_f32_16x16x32_bf16 v[2:5], v[210:213], v[178:181], v[2:5]
	global_load_lds_dwordx4 v226, s[54:55]
	v_mfma_f32_16x16x32_bf16 v[6:9], v[214:217], v[178:181], v[6:9]
	v_mfma_f32_16x16x32_bf16 v[10:13], v[218:221], v[178:181], v[10:13]
	v_mfma_f32_16x16x32_bf16 v[14:17], v[222:225], v[178:181], v[14:17]
	v_mfma_f32_16x16x32_bf16 v[18:21], v[210:213], v[182:185], v[18:21]
	v_mfma_f32_16x16x32_bf16 v[22:25], v[214:217], v[182:185], v[22:25]
	global_load_lds_dwordx4 v226, s[54:55] offset:1024
	v_mfma_f32_16x16x32_bf16 v[26:29], v[218:221], v[182:185], v[26:29]
	v_mfma_f32_16x16x32_bf16 v[30:33], v[222:225], v[182:185], v[30:33]
	v_mfma_f32_16x16x32_bf16 v[34:37], v[210:213], v[186:189], v[34:37]
	ds_read_b128 v[162:165], v241 offset:0
	v_mfma_f32_16x16x32_bf16 v[38:41], v[214:217], v[186:189], v[38:41]
	ds_read_b128 v[166:169], v241 offset:256
	v_mfma_f32_16x16x32_bf16 v[42:45], v[218:221], v[186:189], v[42:45]
	ds_read_b128 v[170:173], v241 offset:2048
	global_load_lds_dwordx4 v226, s[54:55] offset:2048
	v_mfma_f32_16x16x32_bf16 v[46:49], v[222:225], v[186:189], v[46:49]
	ds_read_b128 v[174:177], v241 offset:2304
	v_mfma_f32_16x16x32_bf16 v[50:53], v[210:213], v[190:193], v[50:53]
	ds_read_b128 v[130:133], v240 offset:0
	v_mfma_f32_16x16x32_bf16 v[54:57], v[214:217], v[190:193], v[54:57]
	ds_read_b128 v[134:137], v240 offset:1024
	v_mfma_f32_16x16x32_bf16 v[58:61], v[218:221], v[190:193], v[58:61]
	ds_read_b128 v[138:141], v240 offset:2048
	v_mfma_f32_16x16x32_bf16 v[62:65], v[222:225], v[190:193], v[62:65]
	ds_read_b128 v[142:145], v240 offset:3072
	global_load_lds_dwordx4 v226, s[54:55] offset:3072
	v_mfma_f32_16x16x32_bf16 v[66:69], v[210:213], v[194:197], v[66:69]
	ds_read_b128 v[146:149], v240 offset:4096
	v_mfma_f32_16x16x32_bf16 v[70:73], v[214:217], v[194:197], v[70:73]
	ds_read_b128 v[150:153], v240 offset:5120
	v_mfma_f32_16x16x32_bf16 v[74:77], v[218:221], v[194:197], v[74:77]
	ds_read_b128 v[154:157], v240 offset:6144
	v_mfma_f32_16x16x32_bf16 v[78:81], v[222:225], v[194:197], v[78:81]
	ds_read_b128 v[158:161], v240 offset:7168
	s_add_i32 m0, s60, s63
	v_mfma_f32_16x16x32_bf16 v[82:85], v[210:213], v[198:201], v[82:85]
	global_load_lds_dwordx4 v230, s[56:57]
	v_mfma_f32_16x16x32_bf16 v[86:89], v[214:217], v[198:201], v[86:89]
	v_mfma_f32_16x16x32_bf16 v[90:93], v[218:221], v[198:201], v[90:93]
	v_mfma_f32_16x16x32_bf16 v[94:97], v[222:225], v[198:201], v[94:97]
	v_mfma_f32_16x16x32_bf16 v[98:101], v[210:213], v[202:205], v[98:101]
	v_mfma_f32_16x16x32_bf16 v[102:105], v[214:217], v[202:205], v[102:105]
	global_load_lds_dwordx4 v231, s[56:57] offset:1024
	v_mfma_f32_16x16x32_bf16 v[106:109], v[218:221], v[202:205], v[106:109]
	v_mfma_f32_16x16x32_bf16 v[110:113], v[222:225], v[202:205], v[110:113]
	v_mfma_f32_16x16x32_bf16 v[114:117], v[210:213], v[206:209], v[114:117]
	v_mfma_f32_16x16x32_bf16 v[118:121], v[214:217], v[206:209], v[118:121]
	v_mfma_f32_16x16x32_bf16 v[122:125], v[218:221], v[206:209], v[122:125]
	v_mfma_f32_16x16x32_bf16 v[126:129], v[222:225], v[206:209], v[126:129]
	s_setprio 0
	s_add_i32 s60, s60, 0x6000
	s_cmp_eq_u32 s60, 0x12000
	s_cselect_b32 s60, 0, s60
	s_add_u32 s54, s54, s72
	s_addc_u32 s55, s55, 0
	s_add_u32 s56, s56, s73
	s_addc_u32 s57, s57, 0
	s_add_i32 s61, s61, 0x6000
	s_cmp_eq_u32 s61, 0x12000
	s_cselect_b32 s61, 0, s61
	s_branch .Lpj_epi

.Lpj_tail_last:
	s_waitcnt vmcnt(6) lgkmcnt(0)
	s_barrier
	v_add_u32_e32 v240, s61, v238
	v_add_u32_e32 v241, s61, v239
	s_setprio 1
	s_add_i32 m0, s60, s62
	v_mfma_f32_16x16x32_bf16 v[2:5], v[162:165], v[130:133], v[2:5]
	global_load_lds_dwordx4 v226, s[54:55]
	v_mfma_f32_16x16x32_bf16 v[6:9], v[166:169], v[130:133], v[6:9]
	v_mfma_f32_16x16x32_bf16 v[10:13], v[170:173], v[130:133], v[10:13]
	v_mfma_f32_16x16x32_bf16 v[14:17], v[174:177], v[130:133], v[14:17]
	v_mfma_f32_16x16x32_bf16 v[18:21], v[162:165], v[134:137], v[18:21]
	v_mfma_f32_16x16x32_bf16 v[22:25], v[166:169], v[134:137], v[22:25]
	global_load_lds_dwordx4 v226, s[54:55] offset:1024
	v_mfma_f32_16x16x32_bf16 v[26:29], v[170:173], v[134:137], v[26:29]
	v_mfma_f32_16x16x32_bf16 v[30:33], v[174:177], v[134:137], v[30:33]
	v_mfma_f32_16x16x32_bf16 v[34:37], v[162:165], v[138:141], v[34:37]
	ds_read_b128 v[210:213], v241 offset:0
	v_mfma_f32_16x16x32_bf16 v[38:41], v[166:169], v[138:141], v[38:41]
	ds_read_b128 v[214:217], v241 offset:256
	v_mfma_f32_16x16x32_bf16 v[42:45], v[170:173], v[138:141], v[42:45]
	ds_read_b128 v[218:221], v241 offset:2048
	global_load_lds_dwordx4 v226, s[54:55] offset:2048
	v_mfma_f32_16x16x32_bf16 v[46:49], v[174:177], v[138:141], v[46:49]
	ds_read_b128 v[222:225], v241 offset:2304
	v_mfma_f32_16x16x32_bf16 v[50:53], v[162:165], v[142:145], v[50:53]
	ds_read_b128 v[178:181], v240 offset:0
	v_mfma_f32_16x16x32_bf16 v[54:57], v[166:169], v[142:145], v[54:57]
	ds_read_b128 v[182:185], v240 offset:1024
	v_mfma_f32_16x16x32_bf16 v[58:61], v[170:173], v[142:145], v[58:61]
	ds_read_b128 v[186:189], v240 offset:2048
	v_mfma_f32_16x16x32_bf16 v[62:65], v[174:177], v[142:145], v[62:65]
	ds_read_b128 v[190:193], v240 offset:3072
	global_load_lds_dwordx4 v226, s[54:55] offset:3072
	v_mfma_f32_16x16x32_bf16 v[66:69], v[162:165], v[146:149], v[66:69]
	ds_read_b128 v[194:197], v240 offset:4096
	v_mfma_f32_16x16x32_bf16 v[70:73], v[166:169], v[146:149], v[70:73]
	ds_read_b128 v[198:201], v240 offset:5120
	v_mfma_f32_16x16x32_bf16 v[74:77], v[170:173], v[146:149], v[74:77]
	ds_read_b128 v[202:205], v240 offset:6144
	v_mfma_f32_16x16x32_bf16 v[78:81], v[174:177], v[146:149], v[78:81]
	ds_read_b128 v[206:209], v240 offset:7168
	s_add_i32 m0, s60, s63
	v_mfma_f32_16x16x32_bf16 v[82:85], v[162:165], v[150:153], v[82:85]
	global_load_lds_dwordx4 v230, s[56:57]
	v_mfma_f32_16x16x32_bf16 v[86:89], v[166:169], v[150:153], v[86:89]
	v_mfma_f32_16x16x32_bf16 v[90:93], v[170:173], v[150:153], v[90:93]
	v_mfma_f32_16x16x32_bf16 v[94:97], v[174:177], v[150:153], v[94:97]
	v_mfma_f32_16x16x32_bf16 v[98:101], v[162:165], v[154:157], v[98:101]
	v_mfma_f32_16x16x32_bf16 v[102:105], v[166:169], v[154:157], v[102:105]
	global_load_lds_dwordx4 v231, s[56:57] offset:1024
	v_mfma_f32_16x16x32_bf16 v[106:109], v[170:173], v[154:157], v[106:109]
	v_mfma_f32_16x16x32_bf16 v[110:113], v[174:177], v[154:157], v[110:113]
	v_mfma_f32_16x16x32_bf16 v[114:117], v[162:165], v[158:161], v[114:117]
	v_mfma_f32_16x16x32_bf16 v[118:121], v[166:169], v[158:161], v[118:121]
	v_mfma_f32_16x16x32_bf16 v[122:125], v[170:173], v[158:161], v[122:125]
	v_mfma_f32_16x16x32_bf16 v[126:129], v[174:177], v[158:161], v[126:129]
	s_setprio 0
	s_add_i32 s60, s60, 0x6000
	s_cmp_eq_u32 s60, 0x12000
	s_cselect_b32 s60, 0, s60
	s_add_u32 s54, s54, s72
	s_addc_u32 s55, s55, 0
	s_add_u32 s56, s56, s73
	s_addc_u32 s57, s57, 0
	s_add_i32 s61, s61, 0x6000
	s_cmp_eq_u32 s61, 0x12000
	s_cselect_b32 s61, 0, s61
	s_waitcnt vmcnt(6) lgkmcnt(0)
	s_barrier
	v_add_u32_e32 v240, s61, v238
	v_add_u32_e32 v241, s61, v239
	s_setprio 1
	v_mfma_f32_16x16x32_bf16 v[2:5], v[210:213], v[178:181], v[2:5]
	v_mfma_f32_16x16x32_bf16 v[6:9], v[214:217], v[178:181], v[6:9]
	v_mfma_f32_16x16x32_bf16 v[10:13], v[218:221], v[178:181], v[10:13]
	v_mfma_f32_16x16x32_bf16 v[14:17], v[222:225], v[178:181], v[14:17]
	v_mfma_f32_16x16x32_bf16 v[18:21], v[210:213], v[182:185], v[18:21]
	v_mfma_f32_16x16x32_bf16 v[22:25], v[214:217], v[182:185], v[22:25]
	v_mfma_f32_16x16x32_bf16 v[26:29], v[218:221], v[182:185], v[26:29]
	v_mfma_f32_16x16x32_bf16 v[30:33], v[222:225], v[182:185], v[30:33]
	v_mfma_f32_16x16x32_bf16 v[34:37], v[210:213], v[186:189], v[34:37]
	ds_read_b128 v[162:165], v241 offset:0
	v_mfma_f32_16x16x32_bf16 v[38:41], v[214:217], v[186:189], v[38:41]
	ds_read_b128 v[166:169], v241 offset:256
	v_mfma_f32_16x16x32_bf16 v[42:45], v[218:221], v[186:189], v[42:45]
	ds_read_b128 v[170:173], v241 offset:2048
	v_mfma_f32_16x16x32_bf16 v[46:49], v[222:225], v[186:189], v[46:49]
	ds_read_b128 v[174:177], v241 offset:2304
	v_mfma_f32_16x16x32_bf16 v[50:53], v[210:213], v[190:193], v[50:53]
	ds_read_b128 v[130:133], v240 offset:0
	v_mfma_f32_16x16x32_bf16 v[54:57], v[214:217], v[190:193], v[54:57]
	ds_read_b128 v[134:137], v240 offset:1024
	v_mfma_f32_16x16x32_bf16 v[58:61], v[218:221], v[190:193], v[58:61]
	ds_read_b128 v[138:141], v240 offset:2048
	v_mfma_f32_16x16x32_bf16 v[62:65], v[222:225], v[190:193], v[62:65]
	ds_read_b128 v[142:145], v240 offset:3072
	v_mfma_f32_16x16x32_bf16 v[66:69], v[210:213], v[194:197], v[66:69]
	ds_read_b128 v[146:149], v240 offset:4096
	v_mfma_f32_16x16x32_bf16 v[70:73], v[214:217], v[194:197], v[70:73]
	ds_read_b128 v[150:153], v240 offset:5120
	v_mfma_f32_16x16x32_bf16 v[74:77], v[218:221], v[194:197], v[74:77]
	ds_read_b128 v[154:157], v240 offset:6144
	v_mfma_f32_16x16x32_bf16 v[78:81], v[222:225], v[194:197], v[78:81]
	ds_read_b128 v[158:161], v240 offset:7168
	v_mfma_f32_16x16x32_bf16 v[82:85], v[210:213], v[198:201], v[82:85]
	v_mfma_f32_16x16x32_bf16 v[86:89], v[214:217], v[198:201], v[86:89]
	v_mfma_f32_16x16x32_bf16 v[90:93], v[218:221], v[198:201], v[90:93]
	v_mfma_f32_16x16x32_bf16 v[94:97], v[222:225], v[198:201], v[94:97]
	v_mfma_f32_16x16x32_bf16 v[98:101], v[210:213], v[202:205], v[98:101]
	v_mfma_f32_16x16x32_bf16 v[102:105], v[214:217], v[202:205], v[102:105]
	v_mfma_f32_16x16x32_bf16 v[106:109], v[218:221], v[202:205], v[106:109]
	v_mfma_f32_16x16x32_bf16 v[110:113], v[222:225], v[202:205], v[110:113]
	v_mfma_f32_16x16x32_bf16 v[114:117], v[210:213], v[206:209], v[114:117]
	v_mfma_f32_16x16x32_bf16 v[118:121], v[214:217], v[206:209], v[118:121]
	v_mfma_f32_16x16x32_bf16 v[122:125], v[218:221], v[206:209], v[122:125]
	v_mfma_f32_16x16x32_bf16 v[126:129], v[222:225], v[206:209], v[126:129]
	s_setprio 0
	s_add_i32 s61, s61, 0x6000
	s_cmp_eq_u32 s61, 0x12000
	s_cselect_b32 s61, 0, s61
	s_waitcnt vmcnt(0) lgkmcnt(0)
	s_barrier
	v_add_u32_e32 v240, s61, v238
	v_add_u32_e32 v241, s61, v239
	s_setprio 1
	v_mfma_f32_16x16x32_bf16 v[2:5], v[162:165], v[130:133], v[2:5]
	v_mfma_f32_16x16x32_bf16 v[6:9], v[166:169], v[130:133], v[6:9]
	v_mfma_f32_16x16x32_bf16 v[10:13], v[170:173], v[130:133], v[10:13]
	v_mfma_f32_16x16x32_bf16 v[14:17], v[174:177], v[130:133], v[14:17]
	v_mfma_f32_16x16x32_bf16 v[18:21], v[162:165], v[134:137], v[18:21]
	v_mfma_f32_16x16x32_bf16 v[22:25], v[166:169], v[134:137], v[22:25]
	v_mfma_f32_16x16x32_bf16 v[26:29], v[170:173], v[134:137], v[26:29]
	v_mfma_f32_16x16x32_bf16 v[30:33], v[174:177], v[134:137], v[30:33]
	v_mfma_f32_16x16x32_bf16 v[34:37], v[162:165], v[138:141], v[34:37]
	ds_read_b128 v[210:213], v241 offset:0
	v_mfma_f32_16x16x32_bf16 v[38:41], v[166:169], v[138:141], v[38:41]
	ds_read_b128 v[214:217], v241 offset:256
	v_mfma_f32_16x16x32_bf16 v[42:45], v[170:173], v[138:141], v[42:45]
	ds_read_b128 v[218:221], v241 offset:2048
	v_mfma_f32_16x16x32_bf16 v[46:49], v[174:177], v[138:141], v[46:49]
	ds_read_b128 v[222:225], v241 offset:2304
	v_mfma_f32_16x16x32_bf16 v[50:53], v[162:165], v[142:145], v[50:53]
	ds_read_b128 v[178:181], v240 offset:0
	v_mfma_f32_16x16x32_bf16 v[54:57], v[166:169], v[142:145], v[54:57]
	ds_read_b128 v[182:185], v240 offset:1024
	v_mfma_f32_16x16x32_bf16 v[58:61], v[170:173], v[142:145], v[58:61]
	ds_read_b128 v[186:189], v240 offset:2048
	v_mfma_f32_16x16x32_bf16 v[62:65], v[174:177], v[142:145], v[62:65]
	ds_read_b128 v[190:193], v240 offset:3072
	v_mfma_f32_16x16x32_bf16 v[66:69], v[162:165], v[146:149], v[66:69]
	ds_read_b128 v[194:197], v240 offset:4096
	v_mfma_f32_16x16x32_bf16 v[70:73], v[166:169], v[146:149], v[70:73]
	ds_read_b128 v[198:201], v240 offset:5120
	v_mfma_f32_16x16x32_bf16 v[74:77], v[170:173], v[146:149], v[74:77]
	ds_read_b128 v[202:205], v240 offset:6144
	v_mfma_f32_16x16x32_bf16 v[78:81], v[174:177], v[146:149], v[78:81]
	ds_read_b128 v[206:209], v240 offset:7168
	v_mfma_f32_16x16x32_bf16 v[82:85], v[162:165], v[150:153], v[82:85]
	v_mfma_f32_16x16x32_bf16 v[86:89], v[166:169], v[150:153], v[86:89]
	v_mfma_f32_16x16x32_bf16 v[90:93], v[170:173], v[150:153], v[90:93]
	v_mfma_f32_16x16x32_bf16 v[94:97], v[174:177], v[150:153], v[94:97]
	v_mfma_f32_16x16x32_bf16 v[98:101], v[162:165], v[154:157], v[98:101]
	v_mfma_f32_16x16x32_bf16 v[102:105], v[166:169], v[154:157], v[102:105]
	v_mfma_f32_16x16x32_bf16 v[106:109], v[170:173], v[154:157], v[106:109]
	v_mfma_f32_16x16x32_bf16 v[110:113], v[174:177], v[154:157], v[110:113]
	v_mfma_f32_16x16x32_bf16 v[114:117], v[162:165], v[158:161], v[114:117]
	v_mfma_f32_16x16x32_bf16 v[118:121], v[166:169], v[158:161], v[118:121]
	v_mfma_f32_16x16x32_bf16 v[122:125], v[170:173], v[158:161], v[122:125]
	v_mfma_f32_16x16x32_bf16 v[126:129], v[174:177], v[158:161], v[126:129]
	s_setprio 0
	s_add_i32 s61, s61, 0x6000
	s_cmp_eq_u32 s61, 0x12000
	s_cselect_b32 s61, 0, s61
	s_waitcnt lgkmcnt(0)
	s_barrier
	s_setprio 1
	v_mfma_f32_16x16x32_bf16 v[2:5], v[210:213], v[178:181], v[2:5]
	v_mfma_f32_16x16x32_bf16 v[6:9], v[214:217], v[178:181], v[6:9]
	v_mfma_f32_16x16x32_bf16 v[10:13], v[218:221], v[178:181], v[10:13]
	v_mfma_f32_16x16x32_bf16 v[14:17], v[222:225], v[178:181], v[14:17]
	v_mfma_f32_16x16x32_bf16 v[18:21], v[210:213], v[182:185], v[18:21]
	v_mfma_f32_16x16x32_bf16 v[22:25], v[214:217], v[182:185], v[22:25]
	v_mfma_f32_16x16x32_bf16 v[26:29], v[218:221], v[182:185], v[26:29]
	v_mfma_f32_16x16x32_bf16 v[30:33], v[222:225], v[182:185], v[30:33]
	v_mfma_f32_16x16x32_bf16 v[34:37], v[210:213], v[186:189], v[34:37]
	v_mfma_f32_16x16x32_bf16 v[38:41], v[214:217], v[186:189], v[38:41]
	v_mfma_f32_16x16x32_bf16 v[42:45], v[218:221], v[186:189], v[42:45]
	v_mfma_f32_16x16x32_bf16 v[46:49], v[222:225], v[186:189], v[46:49]
	v_mfma_f32_16x16x32_bf16 v[50:53], v[210:213], v[190:193], v[50:53]
	v_mfma_f32_16x16x32_bf16 v[54:57], v[214:217], v[190:193], v[54:57]
	v_mfma_f32_16x16x32_bf16 v[58:61], v[218:221], v[190:193], v[58:61]
	v_mfma_f32_16x16x32_bf16 v[62:65], v[222:225], v[190:193], v[62:65]
	v_mfma_f32_16x16x32_bf16 v[66:69], v[210:213], v[194:197], v[66:69]
	v_mfma_f32_16x16x32_bf16 v[70:73], v[214:217], v[194:197], v[70:73]
	v_mfma_f32_16x16x32_bf16 v[74:77], v[218:221], v[194:197], v[74:77]
	v_mfma_f32_16x16x32_bf16 v[78:81], v[222:225], v[194:197], v[78:81]
	v_mfma_f32_16x16x32_bf16 v[82:85], v[210:213], v[198:201], v[82:85]
	v_mfma_f32_16x16x32_bf16 v[86:89], v[214:217], v[198:201], v[86:89]
	v_mfma_f32_16x16x32_bf16 v[90:93], v[218:221], v[198:201], v[90:93]
	v_mfma_f32_16x16x32_bf16 v[94:97], v[222:225], v[198:201], v[94:97]
	v_mfma_f32_16x16x32_bf16 v[98:101], v[210:213], v[202:205], v[98:101]
	v_mfma_f32_16x16x32_bf16 v[102:105], v[214:217], v[202:205], v[102:105]
	v_mfma_f32_16x16x32_bf16 v[106:109], v[218:221], v[202:205], v[106:109]
	v_mfma_f32_16x16x32_bf16 v[110:113], v[222:225], v[202:205], v[110:113]
	v_mfma_f32_16x16x32_bf16 v[114:117], v[210:213], v[206:209], v[114:117]
	v_mfma_f32_16x16x32_bf16 v[118:121], v[214:217], v[206:209], v[118:121]
	v_mfma_f32_16x16x32_bf16 v[122:125], v[218:221], v[206:209], v[122:125]
	v_mfma_f32_16x16x32_bf16 v[126:129], v[222:225], v[206:209], v[126:129]
	s_setprio 0
